# SSM: latent fwd/bwd waves meet in the middle (each stores only its first-half partial y; second half finishes gelu directly) - no separate combine pass, half the partial-y traffic
# speedup vs baseline: 1.0100x; 1.0100x over previous
.LBB0_340:
	s_cmp_lt_i32 s96, 4
	s_cselect_b64 s[0:1], -1, 0
	s_and_b64 s[8:9], s[0:1], s[4:5]
	s_andn2_b64 vcc, exec, s[8:9]
	s_cbranch_vccnz .LBB0_393
	v_cmp_gt_u32_e32 vcc, 2, v190
	s_and_saveexec_b64 s[0:1], vcc
	v_lshlrev_b32_e32 v2, 2, v190
	v_add_u32_e32 v2, 0x21000, v2
	v_mov_b32_e32 v3, 0
	ds_write_b32 v2, v3
	s_mov_b64 exec, s[0:1]
	v_and_b32_e32 v172, 31, v191
	v_lshrrev_b32_e32 v173, 5, v191
	v_and_b32_e32 v174, 1, v191
	v_and_b32_e32 v175, 15, v191
	v_lshrrev_b32_e32 v176, 4, v191
	s_mul_i32 s20, s89, 0x3200
	v_lshl_add_u32 v151, v191, 2, s20
	v_mul_u32_u24_e32 v182, 0x110, v175
	v_lshl_add_u32 v182, v176, 4, v182
	v_add_u32_e32 v152, s20, v182
	v_mul_u32_u24_e32 v182, 0x1800, v172
	v_lshl_add_u32 v150, v173, 4, v182
	v_mul_u32_u24_e32 v182, 0x1800, v175
	v_lshl_add_u32 v154, v176, 3, v182
	v_add_u32_e32 v158, 0x18000, v154
	v_lshlrev_b32_e32 v182, 12, v175
	v_lshl_add_u32 v153, v176, 4, v182
	v_add_u32_e32 v157, 0x10000, v153
	v_lshlrev_b32_e32 v182, 11, v175
	v_lshl_add_u32 v156, v176, 3, v182
	v_add_u32_e32 v159, 0x8000, v156
	s_and_b32 s21, s89, 3
	s_lshl_b32 s21, s21, 13
	s_add_u32 s21, s21, 0x19000
	v_lshlrev_b32_e32 v182, 5, v175
	v_lshl_add_u32 v182, v176, 3, v182
	v_add_u32_e32 v155, s21, v182
	v_lshrrev_b32_e32 v182, 4, v172
	v_lshlrev_b32_e32 v182, 10, v182
	v_lshl_add_u32 v182, v175, 4, v182
	v_lshl_add_u32 v177, v173, 8, v182
	v_lshrrev_b32_e32 v182, 1, v176
	v_lshlrev_b32_e32 v182, 8, v182
	v_and_b32_e32 v183, 1, v176
	v_lshl_add_u32 v182, v183, 3, v182
	v_lshl_add_u32 v178, v175, 4, v182
	v_lshrrev_b32_e32 v182, 1, v172
	v_lshl_add_u32 v182, v173, 5, v182
	v_lshlrev_b32_e32 v179, 3, v182
	v_lshlrev_b32_e32 v183, 14, v174
	v_lshl_add_u32 v180, v182, 2, v183
	v_lshlrev_b32_e32 v181, 4, v176
	s_waitcnt vmcnt(0) lgkmcnt(0)
	s_barrier
	s_cmp_lt_u32 s89, 4
	s_cbranch_scc0 .Lssm_ctx
	s_lshr_b32 s21, s89, 1
	s_and_b32 s22, s2, 7
	s_lshl_b32 s22, s22, 6
	s_lshr_b32 s26, s2, 3
	s_lshl_b32 s26, s26, 1
	s_add_u32 s22, s22, s26
	s_add_u32 s22, s22, s21
	s_lshr_b32 s23, s22, 6
	s_and_b32 s24, s22, 63
	s_lshl_b32 s25, s23, 10
	s_add_u32 s25, s25, 0x2000
	s_and_b32 s26, s89, 1
	s_cmp_eq_u32 s26, 0
	s_cbranch_scc0 .Lssm_lat_bwd
	s_add_u32 s28, s24, 0
	s_lshl_b32 s29, s28, 13
	s_add_u32 s29, s29, 0x200000
	s_add_u32 s10, s62, s29
	s_addc_u32 s11, s63, 0
	global_load_dwordx4 v[84:87], v177, s[10:11]
	global_load_dwordx4 v[88:91], v177, s[10:11] offset:2048
	s_add_u32 s12, s10, 0x1000
	s_addc_u32 s13, s11, 0
	global_load_dwordx4 v[92:95], v177, s[12:13]
	global_load_dwordx4 v[96:99], v177, s[12:13] offset:2048
	s_lshl_b32 s29, s28, 12
	s_add_u32 s29, s29, 0x300000
	s_add_u32 s16, s62, s29
	s_addc_u32 s17, s63, 0
	global_load_dwordx2 v[2:3], v178, s[16:17]
	global_load_dwordx2 v[4:5], v178, s[16:17] offset:1024
	global_load_dwordx2 v[6:7], v178, s[16:17] offset:512
	global_load_dwordx2 v[8:9], v178, s[16:17] offset:1536
	global_load_dwordx2 v[10:11], v178, s[16:17] offset:2048
	global_load_dwordx2 v[12:13], v178, s[16:17] offset:3072
	global_load_dwordx2 v[14:15], v178, s[16:17] offset:2560
	global_load_dwordx2 v[16:17], v178, s[16:17] offset:3584
	s_lshl_b32 s29, s28, 9
	s_add_u32 s29, s29, 0x100000
	s_add_u32 s18, s62, s29
	s_addc_u32 s19, s63, 0
	global_load_dwordx2 v[116:117], v179, s[18:19]
	global_load_dwordx2 v[118:119], v179, s[18:19] offset:128
	s_lshl_b32 s30, s23, 1
	s_lshl_b32 s30, s30, 15
	s_lshl_b32 s31, s24, 8
	s_add_u32 s30, s30, s31
	v_readlane_b32 s34, v254, 10
	v_readlane_b32 s35, v254, 11
	s_nop 3
	s_add_u32 s34, s34, s30
	s_addc_u32 s35, s35, 0
	global_load_dword v120, v180, s[34:35]
	global_load_dword v121, v180, s[34:35] offset:64
	v_readlane_b32 s34, v254, 28
	v_readlane_b32 s35, v254, 29
	s_nop 3
	s_lshl_b32 s31, s24, 6
	s_add_u32 s34, s34, s31
	s_addc_u32 s35, s35, 0
	global_load_dwordx4 v[164:167], v181, s[34:35]
	s_mul_i32 s31, s25, 0x1800
	s_lshl_b32 s29, s24, 5
	s_add_u32 s31, s31, s29
	s_add_u32 s31, s31, 0x8801000
	s_add_u32 s4, s62, s31
	s_addc_u32 s5, s63, 0
	s_lshl_b32 s31, s25, 12
	s_lshl_b32 s29, s24, 6
	s_add_u32 s31, s31, s29
	s_add_u32 s6, s60, s31
	s_addc_u32 s7, s61, 0
	s_add_u32 s34, s4, 0
	s_addc_u32 s35, s5, 0
	global_load_dwordx4 v[80:83], v150, s[34:35]
	s_mov_b64 s[10:11], s[34:35]
	s_add_u32 s10, s10, 196608
	s_addc_u32 s11, s11, 0
	global_load_dwordx4 v[144:147], v150, s[10:11]
	s_mov_b64 s[34:35], s[10:11]
	s_add_u32 s10, s10, 196608
	s_addc_u32 s11, s11, 0
	s_add_u32 s12, s6, 0
	s_addc_u32 s13, s7, 0
	s_mov_b32 s14, 0
	s_mov_b32 s40, 0xffff0000
	s_waitcnt vmcnt(0)
	v_and_b32_e32 v182, 0xffff, v2
	v_lshrrev_b32_e32 v183, 16, v2
	v_and_b32_e32 v184, 0xffff, v3
	v_lshrrev_b32_e32 v185, 16, v3
	v_lshl_or_b32 v100, v4, 16, v182
	v_and_or_b32 v101, v4, s40, v183
	v_lshl_or_b32 v102, v5, 16, v184
	v_and_or_b32 v103, v5, s40, v185
	v_and_b32_e32 v182, 0xffff, v6
	v_lshrrev_b32_e32 v183, 16, v6
	v_and_b32_e32 v184, 0xffff, v7
	v_lshrrev_b32_e32 v185, 16, v7
	v_lshl_or_b32 v104, v8, 16, v182
	v_and_or_b32 v105, v8, s40, v183
	v_lshl_or_b32 v106, v9, 16, v184
	v_and_or_b32 v107, v9, s40, v185
	v_and_b32_e32 v182, 0xffff, v10
	v_lshrrev_b32_e32 v183, 16, v10
	v_and_b32_e32 v184, 0xffff, v11
	v_lshrrev_b32_e32 v185, 16, v11
	v_lshl_or_b32 v108, v12, 16, v182
	v_and_or_b32 v109, v12, s40, v183
	v_lshl_or_b32 v110, v13, 16, v184
	v_and_or_b32 v111, v13, s40, v185
	v_and_b32_e32 v182, 0xffff, v14
	v_lshrrev_b32_e32 v183, 16, v14
	v_and_b32_e32 v184, 0xffff, v15
	v_lshrrev_b32_e32 v185, 16, v15
	v_lshl_or_b32 v112, v16, 16, v182
	v_and_or_b32 v113, v16, s40, v183
	v_lshl_or_b32 v114, v17, 16, v184
	v_and_or_b32 v115, v17, s40, v185
	v_cmp_eq_u32_e32 vcc, 1, v174
	v_xor_b32_e32 v182, 0x80000000, v117
	v_xor_b32_e32 v183, 0x80000000, v119
	s_nop 1
	v_cndmask_b32_e32 v122, v182, v117, vcc
	v_cndmask_b32_e32 v123, v183, v119, vcc
.Lssm_tileA_d0m0:
	s_waitcnt vmcnt(5)
	v_mfma_f32_32x32x16_bf16 v[16:31], v[80:83], v[84:87], 0
	v_mfma_f32_32x32x16_bf16 v[32:47], v[80:83], v[88:91], 0
	v_mfma_f32_32x32x16_bf16 v[48:63], v[80:83], v[92:95], 0
	v_mfma_f32_32x32x16_bf16 v[64:79], v[80:83], v[96:99], 0
	s_nop 11
	global_load_dwordx4 v[80:83], v150, s[10:11]
	s_add_u32 s34, s34, 196608
	s_addc_u32 s35, s35, 0
	s_add_u32 s10, s10, 196608
	s_addc_u32 s11, s11, 0
	v_permlane32_swap_b32_e32 v16, v48
	v_permlane32_swap_b32_e32 v17, v49
	v_permlane32_swap_b32_e32 v18, v50
	v_permlane32_swap_b32_e32 v19, v51
	v_permlane32_swap_b32_e32 v20, v52
	v_permlane32_swap_b32_e32 v21, v53
	v_permlane32_swap_b32_e32 v22, v54
	v_permlane32_swap_b32_e32 v23, v55
	v_permlane32_swap_b32_e32 v24, v56
	v_permlane32_swap_b32_e32 v25, v57
	v_permlane32_swap_b32_e32 v26, v58
	v_permlane32_swap_b32_e32 v27, v59
	v_permlane32_swap_b32_e32 v28, v60
	v_permlane32_swap_b32_e32 v29, v61
	v_permlane32_swap_b32_e32 v30, v62
	v_permlane32_swap_b32_e32 v31, v63
	v_permlane32_swap_b32_e32 v32, v64
	v_permlane32_swap_b32_e32 v33, v65
	v_permlane32_swap_b32_e32 v34, v66
	v_permlane32_swap_b32_e32 v35, v67
	v_permlane32_swap_b32_e32 v36, v68
	v_permlane32_swap_b32_e32 v37, v69
	v_permlane32_swap_b32_e32 v38, v70
	v_permlane32_swap_b32_e32 v39, v71
	v_permlane32_swap_b32_e32 v40, v72
	v_permlane32_swap_b32_e32 v41, v73
	v_permlane32_swap_b32_e32 v42, v74
	v_permlane32_swap_b32_e32 v43, v75
	v_permlane32_swap_b32_e32 v44, v76
	v_permlane32_swap_b32_e32 v45, v77
	v_permlane32_swap_b32_e32 v46, v78
	v_permlane32_swap_b32_e32 v47, v79
	v_fmac_f32_e32 v16, v116, v120
	v_fmac_f32_e32 v32, v118, v121
	v_fmac_f32_dpp v16, v120, v122 quad_perm:[1,0,3,2] row_mask:0xf bank_mask:0xf
	v_fmac_f32_dpp v32, v121, v123 quad_perm:[1,0,3,2] row_mask:0xf bank_mask:0xf
	v_cvt_pk_bf16_f32 v148, v16, v32
	ds_write_b32 v151, v148
	v_fmac_f32_e32 v17, v116, v16
	v_fmac_f32_e32 v33, v118, v32
	v_fmac_f32_dpp v17, v16, v122 quad_perm:[1,0,3,2] row_mask:0xf bank_mask:0xf
	v_fmac_f32_dpp v33, v32, v123 quad_perm:[1,0,3,2] row_mask:0xf bank_mask:0xf
	v_cvt_pk_bf16_f32 v149, v17, v33
	ds_write_b32 v151, v149 offset:272
	v_fmac_f32_e32 v18, v116, v17
	v_fmac_f32_e32 v34, v118, v33
	v_fmac_f32_dpp v18, v17, v122 quad_perm:[1,0,3,2] row_mask:0xf bank_mask:0xf
	v_fmac_f32_dpp v34, v33, v123 quad_perm:[1,0,3,2] row_mask:0xf bank_mask:0xf
	v_cvt_pk_bf16_f32 v148, v18, v34
	ds_write_b32 v151, v148 offset:544
	v_fmac_f32_e32 v19, v116, v18
	v_fmac_f32_e32 v35, v118, v34
	v_fmac_f32_dpp v19, v18, v122 quad_perm:[1,0,3,2] row_mask:0xf bank_mask:0xf
	v_fmac_f32_dpp v35, v34, v123 quad_perm:[1,0,3,2] row_mask:0xf bank_mask:0xf
	v_cvt_pk_bf16_f32 v149, v19, v35
	ds_write_b32 v151, v149 offset:816
	v_fmac_f32_e32 v48, v116, v19
	v_fmac_f32_e32 v64, v118, v35
	v_fmac_f32_dpp v48, v19, v122 quad_perm:[1,0,3,2] row_mask:0xf bank_mask:0xf
	v_fmac_f32_dpp v64, v35, v123 quad_perm:[1,0,3,2] row_mask:0xf bank_mask:0xf
	v_cvt_pk_bf16_f32 v148, v48, v64
	ds_write_b32 v151, v148 offset:1088
	v_fmac_f32_e32 v49, v116, v48
	v_fmac_f32_e32 v65, v118, v64
	v_fmac_f32_dpp v49, v48, v122 quad_perm:[1,0,3,2] row_mask:0xf bank_mask:0xf
	v_fmac_f32_dpp v65, v64, v123 quad_perm:[1,0,3,2] row_mask:0xf bank_mask:0xf
	v_cvt_pk_bf16_f32 v149, v49, v65
	ds_write_b32 v151, v149 offset:1360
	v_fmac_f32_e32 v50, v116, v49
	v_fmac_f32_e32 v66, v118, v65
	v_fmac_f32_dpp v50, v49, v122 quad_perm:[1,0,3,2] row_mask:0xf bank_mask:0xf
	v_fmac_f32_dpp v66, v65, v123 quad_perm:[1,0,3,2] row_mask:0xf bank_mask:0xf
	v_cvt_pk_bf16_f32 v148, v50, v66
	ds_write_b32 v151, v148 offset:1632
	v_fmac_f32_e32 v51, v116, v50
	v_fmac_f32_e32 v67, v118, v66
	v_fmac_f32_dpp v51, v50, v122 quad_perm:[1,0,3,2] row_mask:0xf bank_mask:0xf
	v_fmac_f32_dpp v67, v66, v123 quad_perm:[1,0,3,2] row_mask:0xf bank_mask:0xf
	v_cvt_pk_bf16_f32 v149, v51, v67
	ds_write_b32 v151, v149 offset:1904
	v_fmac_f32_e32 v20, v116, v51
	v_fmac_f32_e32 v36, v118, v67
	v_fmac_f32_dpp v20, v51, v122 quad_perm:[1,0,3,2] row_mask:0xf bank_mask:0xf
	v_fmac_f32_dpp v36, v67, v123 quad_perm:[1,0,3,2] row_mask:0xf bank_mask:0xf
	v_cvt_pk_bf16_f32 v148, v20, v36
	ds_write_b32 v151, v148 offset:2176
	v_fmac_f32_e32 v21, v116, v20
	v_fmac_f32_e32 v37, v118, v36
	v_fmac_f32_dpp v21, v20, v122 quad_perm:[1,0,3,2] row_mask:0xf bank_mask:0xf
	v_fmac_f32_dpp v37, v36, v123 quad_perm:[1,0,3,2] row_mask:0xf bank_mask:0xf
	v_cvt_pk_bf16_f32 v149, v21, v37
	ds_write_b32 v151, v149 offset:2448
	v_fmac_f32_e32 v22, v116, v21
	v_fmac_f32_e32 v38, v118, v37
	v_fmac_f32_dpp v22, v21, v122 quad_perm:[1,0,3,2] row_mask:0xf bank_mask:0xf
	v_fmac_f32_dpp v38, v37, v123 quad_perm:[1,0,3,2] row_mask:0xf bank_mask:0xf
	v_cvt_pk_bf16_f32 v148, v22, v38
	ds_write_b32 v151, v148 offset:2720
	v_fmac_f32_e32 v23, v116, v22
	v_fmac_f32_e32 v39, v118, v38
	v_fmac_f32_dpp v23, v22, v122 quad_perm:[1,0,3,2] row_mask:0xf bank_mask:0xf
	v_fmac_f32_dpp v39, v38, v123 quad_perm:[1,0,3,2] row_mask:0xf bank_mask:0xf
	v_cvt_pk_bf16_f32 v149, v23, v39
	ds_write_b32 v151, v149 offset:2992
	v_fmac_f32_e32 v52, v116, v23
	v_fmac_f32_e32 v68, v118, v39
	v_fmac_f32_dpp v52, v23, v122 quad_perm:[1,0,3,2] row_mask:0xf bank_mask:0xf
	v_fmac_f32_dpp v68, v39, v123 quad_perm:[1,0,3,2] row_mask:0xf bank_mask:0xf
	v_cvt_pk_bf16_f32 v148, v52, v68
	ds_write_b32 v151, v148 offset:3264
	v_fmac_f32_e32 v53, v116, v52
	v_fmac_f32_e32 v69, v118, v68
	v_fmac_f32_dpp v53, v52, v122 quad_perm:[1,0,3,2] row_mask:0xf bank_mask:0xf
	v_fmac_f32_dpp v69, v68, v123 quad_perm:[1,0,3,2] row_mask:0xf bank_mask:0xf
	v_cvt_pk_bf16_f32 v149, v53, v69
	ds_write_b32 v151, v149 offset:3536
	v_fmac_f32_e32 v54, v116, v53
	v_fmac_f32_e32 v70, v118, v69
	v_fmac_f32_dpp v54, v53, v122 quad_perm:[1,0,3,2] row_mask:0xf bank_mask:0xf
	v_fmac_f32_dpp v70, v69, v123 quad_perm:[1,0,3,2] row_mask:0xf bank_mask:0xf
	v_cvt_pk_bf16_f32 v148, v54, v70
	ds_write_b32 v151, v148 offset:3808
	v_fmac_f32_e32 v55, v116, v54
	v_fmac_f32_e32 v71, v118, v70
	v_fmac_f32_dpp v55, v54, v122 quad_perm:[1,0,3,2] row_mask:0xf bank_mask:0xf
	v_fmac_f32_dpp v71, v70, v123 quad_perm:[1,0,3,2] row_mask:0xf bank_mask:0xf
	v_cvt_pk_bf16_f32 v149, v55, v71
	ds_write_b32 v151, v149 offset:4080
	v_fmac_f32_e32 v24, v116, v55
	v_fmac_f32_e32 v40, v118, v71
	v_fmac_f32_dpp v24, v55, v122 quad_perm:[1,0,3,2] row_mask:0xf bank_mask:0xf
	v_fmac_f32_dpp v40, v71, v123 quad_perm:[1,0,3,2] row_mask:0xf bank_mask:0xf
	v_cvt_pk_bf16_f32 v148, v24, v40
	ds_write_b32 v151, v148 offset:4352
	v_fmac_f32_e32 v25, v116, v24
	v_fmac_f32_e32 v41, v118, v40
	v_fmac_f32_dpp v25, v24, v122 quad_perm:[1,0,3,2] row_mask:0xf bank_mask:0xf
	v_fmac_f32_dpp v41, v40, v123 quad_perm:[1,0,3,2] row_mask:0xf bank_mask:0xf
	v_cvt_pk_bf16_f32 v149, v25, v41
	ds_write_b32 v151, v149 offset:4624
	v_fmac_f32_e32 v26, v116, v25
	v_fmac_f32_e32 v42, v118, v41
	v_fmac_f32_dpp v26, v25, v122 quad_perm:[1,0,3,2] row_mask:0xf bank_mask:0xf
	v_fmac_f32_dpp v42, v41, v123 quad_perm:[1,0,3,2] row_mask:0xf bank_mask:0xf
	v_cvt_pk_bf16_f32 v148, v26, v42
	ds_write_b32 v151, v148 offset:4896
	v_fmac_f32_e32 v27, v116, v26
	v_fmac_f32_e32 v43, v118, v42
	v_fmac_f32_dpp v27, v26, v122 quad_perm:[1,0,3,2] row_mask:0xf bank_mask:0xf
	v_fmac_f32_dpp v43, v42, v123 quad_perm:[1,0,3,2] row_mask:0xf bank_mask:0xf
	v_cvt_pk_bf16_f32 v149, v27, v43
	ds_write_b32 v151, v149 offset:5168
	v_fmac_f32_e32 v56, v116, v27
	v_fmac_f32_e32 v72, v118, v43
	v_fmac_f32_dpp v56, v27, v122 quad_perm:[1,0,3,2] row_mask:0xf bank_mask:0xf
	v_fmac_f32_dpp v72, v43, v123 quad_perm:[1,0,3,2] row_mask:0xf bank_mask:0xf
	v_cvt_pk_bf16_f32 v148, v56, v72
	ds_write_b32 v151, v148 offset:5440
	v_fmac_f32_e32 v57, v116, v56
	v_fmac_f32_e32 v73, v118, v72
	v_fmac_f32_dpp v57, v56, v122 quad_perm:[1,0,3,2] row_mask:0xf bank_mask:0xf
	v_fmac_f32_dpp v73, v72, v123 quad_perm:[1,0,3,2] row_mask:0xf bank_mask:0xf
	v_cvt_pk_bf16_f32 v149, v57, v73
	ds_write_b32 v151, v149 offset:5712
	v_fmac_f32_e32 v58, v116, v57
	v_fmac_f32_e32 v74, v118, v73
	v_fmac_f32_dpp v58, v57, v122 quad_perm:[1,0,3,2] row_mask:0xf bank_mask:0xf
	v_fmac_f32_dpp v74, v73, v123 quad_perm:[1,0,3,2] row_mask:0xf bank_mask:0xf
	v_cvt_pk_bf16_f32 v148, v58, v74
	ds_write_b32 v151, v148 offset:5984
	v_fmac_f32_e32 v59, v116, v58
	v_fmac_f32_e32 v75, v118, v74
	v_fmac_f32_dpp v59, v58, v122 quad_perm:[1,0,3,2] row_mask:0xf bank_mask:0xf
	v_fmac_f32_dpp v75, v74, v123 quad_perm:[1,0,3,2] row_mask:0xf bank_mask:0xf
	v_cvt_pk_bf16_f32 v149, v59, v75
	ds_write_b32 v151, v149 offset:6256
	v_fmac_f32_e32 v28, v116, v59
	v_fmac_f32_e32 v44, v118, v75
	v_fmac_f32_dpp v28, v59, v122 quad_perm:[1,0,3,2] row_mask:0xf bank_mask:0xf
	v_fmac_f32_dpp v44, v75, v123 quad_perm:[1,0,3,2] row_mask:0xf bank_mask:0xf
	v_cvt_pk_bf16_f32 v148, v28, v44
	ds_write_b32 v151, v148 offset:6528
	v_fmac_f32_e32 v29, v116, v28
	v_fmac_f32_e32 v45, v118, v44
	v_fmac_f32_dpp v29, v28, v122 quad_perm:[1,0,3,2] row_mask:0xf bank_mask:0xf
	v_fmac_f32_dpp v45, v44, v123 quad_perm:[1,0,3,2] row_mask:0xf bank_mask:0xf
	v_cvt_pk_bf16_f32 v149, v29, v45
	ds_write_b32 v151, v149 offset:6800
	v_fmac_f32_e32 v30, v116, v29
	v_fmac_f32_e32 v46, v118, v45
	v_fmac_f32_dpp v30, v29, v122 quad_perm:[1,0,3,2] row_mask:0xf bank_mask:0xf
	v_fmac_f32_dpp v46, v45, v123 quad_perm:[1,0,3,2] row_mask:0xf bank_mask:0xf
	v_cvt_pk_bf16_f32 v148, v30, v46
	ds_write_b32 v151, v148 offset:7072
	v_fmac_f32_e32 v31, v116, v30
	v_fmac_f32_e32 v47, v118, v46
	v_fmac_f32_dpp v31, v30, v122 quad_perm:[1,0,3,2] row_mask:0xf bank_mask:0xf
	v_fmac_f32_dpp v47, v46, v123 quad_perm:[1,0,3,2] row_mask:0xf bank_mask:0xf
	v_cvt_pk_bf16_f32 v149, v31, v47
	ds_write_b32 v151, v149 offset:7344
	v_fmac_f32_e32 v60, v116, v31
	v_fmac_f32_e32 v76, v118, v47
	v_fmac_f32_dpp v60, v31, v122 quad_perm:[1,0,3,2] row_mask:0xf bank_mask:0xf
	v_fmac_f32_dpp v76, v47, v123 quad_perm:[1,0,3,2] row_mask:0xf bank_mask:0xf
	v_cvt_pk_bf16_f32 v148, v60, v76
	ds_write_b32 v151, v148 offset:7616
	v_fmac_f32_e32 v61, v116, v60
	v_fmac_f32_e32 v77, v118, v76
	v_fmac_f32_dpp v61, v60, v122 quad_perm:[1,0,3,2] row_mask:0xf bank_mask:0xf
	v_fmac_f32_dpp v77, v76, v123 quad_perm:[1,0,3,2] row_mask:0xf bank_mask:0xf
	v_cvt_pk_bf16_f32 v149, v61, v77
	ds_write_b32 v151, v149 offset:7888
	v_fmac_f32_e32 v62, v116, v61
	v_fmac_f32_e32 v78, v118, v77
	v_fmac_f32_dpp v62, v61, v122 quad_perm:[1,0,3,2] row_mask:0xf bank_mask:0xf
	v_fmac_f32_dpp v78, v77, v123 quad_perm:[1,0,3,2] row_mask:0xf bank_mask:0xf
	v_cvt_pk_bf16_f32 v148, v62, v78
	ds_write_b32 v151, v148 offset:8160
	v_fmac_f32_e32 v63, v116, v62
	v_fmac_f32_e32 v79, v118, v78
	v_fmac_f32_dpp v63, v62, v122 quad_perm:[1,0,3,2] row_mask:0xf bank_mask:0xf
	v_fmac_f32_dpp v79, v78, v123 quad_perm:[1,0,3,2] row_mask:0xf bank_mask:0xf
	v_cvt_pk_bf16_f32 v149, v63, v79
	ds_write_b32 v151, v149 offset:8432
	v_mov_b32_e32 v120, v63
	v_mov_b32_e32 v121, v79
	ds_read_b128 v[124:127], v152
	ds_read_b128 v[128:131], v152 offset:64
	ds_read_b128 v[132:135], v152 offset:128
	ds_read_b128 v[136:139], v152 offset:192
	s_waitcnt lgkmcnt(3)
	v_mfma_f32_16x16x32_bf16 v[140:143], v[100:103], v[124:127], 0
	s_waitcnt lgkmcnt(2)
	v_mfma_f32_16x16x32_bf16 v[140:143], v[104:107], v[128:131], v[140:143]
	s_waitcnt lgkmcnt(1)
	v_mfma_f32_16x16x32_bf16 v[140:143], v[108:111], v[132:135], v[140:143]
	s_waitcnt lgkmcnt(0)
	v_mfma_f32_16x16x32_bf16 v[140:143], v[112:115], v[136:139], v[140:143]
	s_nop 9
	global_store_dwordx4 v153, v[140:143], s[12:13]
	s_nop 1
	ds_read_b128 v[124:127], v152 offset:4352
	ds_read_b128 v[128:131], v152 offset:4416
	ds_read_b128 v[132:135], v152 offset:4480
	ds_read_b128 v[136:139], v152 offset:4544
	s_waitcnt lgkmcnt(3)
	v_mfma_f32_16x16x32_bf16 v[140:143], v[100:103], v[124:127], 0
	s_waitcnt lgkmcnt(2)
	v_mfma_f32_16x16x32_bf16 v[140:143], v[104:107], v[128:131], v[140:143]
	s_waitcnt lgkmcnt(1)
	v_mfma_f32_16x16x32_bf16 v[140:143], v[108:111], v[132:135], v[140:143]
	s_waitcnt lgkmcnt(0)
	v_mfma_f32_16x16x32_bf16 v[140:143], v[112:115], v[136:139], v[140:143]
	s_nop 9
	global_store_dwordx4 v157, v[140:143], s[12:13]
	s_nop 1
	s_add_u32 s12, s12, 131072
	s_addc_u32 s13, s13, 0
	s_waitcnt vmcnt(5)
	v_mfma_f32_32x32x16_bf16 v[16:31], v[144:147], v[84:87], 0
	v_mfma_f32_32x32x16_bf16 v[32:47], v[144:147], v[88:91], 0
	v_mfma_f32_32x32x16_bf16 v[48:63], v[144:147], v[92:95], 0
	v_mfma_f32_32x32x16_bf16 v[64:79], v[144:147], v[96:99], 0
	s_nop 11
	global_load_dwordx4 v[144:147], v150, s[10:11]
	s_add_u32 s34, s34, 196608
	s_addc_u32 s35, s35, 0
	s_add_u32 s10, s10, 196608
	s_addc_u32 s11, s11, 0
	v_permlane32_swap_b32_e32 v16, v48
	v_permlane32_swap_b32_e32 v17, v49
	v_permlane32_swap_b32_e32 v18, v50
	v_permlane32_swap_b32_e32 v19, v51
	v_permlane32_swap_b32_e32 v20, v52
	v_permlane32_swap_b32_e32 v21, v53
	v_permlane32_swap_b32_e32 v22, v54
	v_permlane32_swap_b32_e32 v23, v55
	v_permlane32_swap_b32_e32 v24, v56
	v_permlane32_swap_b32_e32 v25, v57
	v_permlane32_swap_b32_e32 v26, v58
	v_permlane32_swap_b32_e32 v27, v59
	v_permlane32_swap_b32_e32 v28, v60
	v_permlane32_swap_b32_e32 v29, v61
	v_permlane32_swap_b32_e32 v30, v62
	v_permlane32_swap_b32_e32 v31, v63
	v_permlane32_swap_b32_e32 v32, v64
	v_permlane32_swap_b32_e32 v33, v65
	v_permlane32_swap_b32_e32 v34, v66
	v_permlane32_swap_b32_e32 v35, v67
	v_permlane32_swap_b32_e32 v36, v68
	v_permlane32_swap_b32_e32 v37, v69
	v_permlane32_swap_b32_e32 v38, v70
	v_permlane32_swap_b32_e32 v39, v71
	v_permlane32_swap_b32_e32 v40, v72
	v_permlane32_swap_b32_e32 v41, v73
	v_permlane32_swap_b32_e32 v42, v74
	v_permlane32_swap_b32_e32 v43, v75
	v_permlane32_swap_b32_e32 v44, v76
	v_permlane32_swap_b32_e32 v45, v77
	v_permlane32_swap_b32_e32 v46, v78
	v_permlane32_swap_b32_e32 v47, v79
	v_fmac_f32_e32 v16, v116, v120
	v_fmac_f32_e32 v32, v118, v121
	v_fmac_f32_dpp v16, v120, v122 quad_perm:[1,0,3,2] row_mask:0xf bank_mask:0xf
	v_fmac_f32_dpp v32, v121, v123 quad_perm:[1,0,3,2] row_mask:0xf bank_mask:0xf
	v_cvt_pk_bf16_f32 v148, v16, v32
	ds_write_b32 v151, v148
	v_fmac_f32_e32 v17, v116, v16
	v_fmac_f32_e32 v33, v118, v32
	v_fmac_f32_dpp v17, v16, v122 quad_perm:[1,0,3,2] row_mask:0xf bank_mask:0xf
	v_fmac_f32_dpp v33, v32, v123 quad_perm:[1,0,3,2] row_mask:0xf bank_mask:0xf
	v_cvt_pk_bf16_f32 v149, v17, v33
	ds_write_b32 v151, v149 offset:272
	v_fmac_f32_e32 v18, v116, v17
	v_fmac_f32_e32 v34, v118, v33
	v_fmac_f32_dpp v18, v17, v122 quad_perm:[1,0,3,2] row_mask:0xf bank_mask:0xf
	v_fmac_f32_dpp v34, v33, v123 quad_perm:[1,0,3,2] row_mask:0xf bank_mask:0xf
	v_cvt_pk_bf16_f32 v148, v18, v34
	ds_write_b32 v151, v148 offset:544
	v_fmac_f32_e32 v19, v116, v18
	v_fmac_f32_e32 v35, v118, v34
	v_fmac_f32_dpp v19, v18, v122 quad_perm:[1,0,3,2] row_mask:0xf bank_mask:0xf
	v_fmac_f32_dpp v35, v34, v123 quad_perm:[1,0,3,2] row_mask:0xf bank_mask:0xf
	v_cvt_pk_bf16_f32 v149, v19, v35
	ds_write_b32 v151, v149 offset:816
	v_fmac_f32_e32 v48, v116, v19
	v_fmac_f32_e32 v64, v118, v35
	v_fmac_f32_dpp v48, v19, v122 quad_perm:[1,0,3,2] row_mask:0xf bank_mask:0xf
	v_fmac_f32_dpp v64, v35, v123 quad_perm:[1,0,3,2] row_mask:0xf bank_mask:0xf
	v_cvt_pk_bf16_f32 v148, v48, v64
	ds_write_b32 v151, v148 offset:1088
	v_fmac_f32_e32 v49, v116, v48
	v_fmac_f32_e32 v65, v118, v64
	v_fmac_f32_dpp v49, v48, v122 quad_perm:[1,0,3,2] row_mask:0xf bank_mask:0xf
	v_fmac_f32_dpp v65, v64, v123 quad_perm:[1,0,3,2] row_mask:0xf bank_mask:0xf
	v_cvt_pk_bf16_f32 v149, v49, v65
	ds_write_b32 v151, v149 offset:1360
	v_fmac_f32_e32 v50, v116, v49
	v_fmac_f32_e32 v66, v118, v65
	v_fmac_f32_dpp v50, v49, v122 quad_perm:[1,0,3,2] row_mask:0xf bank_mask:0xf
	v_fmac_f32_dpp v66, v65, v123 quad_perm:[1,0,3,2] row_mask:0xf bank_mask:0xf
	v_cvt_pk_bf16_f32 v148, v50, v66
	ds_write_b32 v151, v148 offset:1632
	v_fmac_f32_e32 v51, v116, v50
	v_fmac_f32_e32 v67, v118, v66
	v_fmac_f32_dpp v51, v50, v122 quad_perm:[1,0,3,2] row_mask:0xf bank_mask:0xf
	v_fmac_f32_dpp v67, v66, v123 quad_perm:[1,0,3,2] row_mask:0xf bank_mask:0xf
	v_cvt_pk_bf16_f32 v149, v51, v67
	ds_write_b32 v151, v149 offset:1904
	v_fmac_f32_e32 v20, v116, v51
	v_fmac_f32_e32 v36, v118, v67
	v_fmac_f32_dpp v20, v51, v122 quad_perm:[1,0,3,2] row_mask:0xf bank_mask:0xf
	v_fmac_f32_dpp v36, v67, v123 quad_perm:[1,0,3,2] row_mask:0xf bank_mask:0xf
	v_cvt_pk_bf16_f32 v148, v20, v36
	ds_write_b32 v151, v148 offset:2176
	v_fmac_f32_e32 v21, v116, v20
	v_fmac_f32_e32 v37, v118, v36
	v_fmac_f32_dpp v21, v20, v122 quad_perm:[1,0,3,2] row_mask:0xf bank_mask:0xf
	v_fmac_f32_dpp v37, v36, v123 quad_perm:[1,0,3,2] row_mask:0xf bank_mask:0xf
	v_cvt_pk_bf16_f32 v149, v21, v37
	ds_write_b32 v151, v149 offset:2448
	v_fmac_f32_e32 v22, v116, v21
	v_fmac_f32_e32 v38, v118, v37
	v_fmac_f32_dpp v22, v21, v122 quad_perm:[1,0,3,2] row_mask:0xf bank_mask:0xf
	v_fmac_f32_dpp v38, v37, v123 quad_perm:[1,0,3,2] row_mask:0xf bank_mask:0xf
	v_cvt_pk_bf16_f32 v148, v22, v38
	ds_write_b32 v151, v148 offset:2720
	v_fmac_f32_e32 v23, v116, v22
	v_fmac_f32_e32 v39, v118, v38
	v_fmac_f32_dpp v23, v22, v122 quad_perm:[1,0,3,2] row_mask:0xf bank_mask:0xf
	v_fmac_f32_dpp v39, v38, v123 quad_perm:[1,0,3,2] row_mask:0xf bank_mask:0xf
	v_cvt_pk_bf16_f32 v149, v23, v39
	ds_write_b32 v151, v149 offset:2992
	v_fmac_f32_e32 v52, v116, v23
	v_fmac_f32_e32 v68, v118, v39
	v_fmac_f32_dpp v52, v23, v122 quad_perm:[1,0,3,2] row_mask:0xf bank_mask:0xf
	v_fmac_f32_dpp v68, v39, v123 quad_perm:[1,0,3,2] row_mask:0xf bank_mask:0xf
	v_cvt_pk_bf16_f32 v148, v52, v68
	ds_write_b32 v151, v148 offset:3264
	v_fmac_f32_e32 v53, v116, v52
	v_fmac_f32_e32 v69, v118, v68
	v_fmac_f32_dpp v53, v52, v122 quad_perm:[1,0,3,2] row_mask:0xf bank_mask:0xf
	v_fmac_f32_dpp v69, v68, v123 quad_perm:[1,0,3,2] row_mask:0xf bank_mask:0xf
	v_cvt_pk_bf16_f32 v149, v53, v69
	ds_write_b32 v151, v149 offset:3536
	v_fmac_f32_e32 v54, v116, v53
	v_fmac_f32_e32 v70, v118, v69
	v_fmac_f32_dpp v54, v53, v122 quad_perm:[1,0,3,2] row_mask:0xf bank_mask:0xf
	v_fmac_f32_dpp v70, v69, v123 quad_perm:[1,0,3,2] row_mask:0xf bank_mask:0xf
	v_cvt_pk_bf16_f32 v148, v54, v70
	ds_write_b32 v151, v148 offset:3808
	v_fmac_f32_e32 v55, v116, v54
	v_fmac_f32_e32 v71, v118, v70
	v_fmac_f32_dpp v55, v54, v122 quad_perm:[1,0,3,2] row_mask:0xf bank_mask:0xf
	v_fmac_f32_dpp v71, v70, v123 quad_perm:[1,0,3,2] row_mask:0xf bank_mask:0xf
	v_cvt_pk_bf16_f32 v149, v55, v71
	ds_write_b32 v151, v149 offset:4080
	v_fmac_f32_e32 v24, v116, v55
	v_fmac_f32_e32 v40, v118, v71
	v_fmac_f32_dpp v24, v55, v122 quad_perm:[1,0,3,2] row_mask:0xf bank_mask:0xf
	v_fmac_f32_dpp v40, v71, v123 quad_perm:[1,0,3,2] row_mask:0xf bank_mask:0xf
	v_cvt_pk_bf16_f32 v148, v24, v40
	ds_write_b32 v151, v148 offset:4352
	v_fmac_f32_e32 v25, v116, v24
	v_fmac_f32_e32 v41, v118, v40
	v_fmac_f32_dpp v25, v24, v122 quad_perm:[1,0,3,2] row_mask:0xf bank_mask:0xf
	v_fmac_f32_dpp v41, v40, v123 quad_perm:[1,0,3,2] row_mask:0xf bank_mask:0xf
	v_cvt_pk_bf16_f32 v149, v25, v41
	ds_write_b32 v151, v149 offset:4624
	v_fmac_f32_e32 v26, v116, v25
	v_fmac_f32_e32 v42, v118, v41
	v_fmac_f32_dpp v26, v25, v122 quad_perm:[1,0,3,2] row_mask:0xf bank_mask:0xf
	v_fmac_f32_dpp v42, v41, v123 quad_perm:[1,0,3,2] row_mask:0xf bank_mask:0xf
	v_cvt_pk_bf16_f32 v148, v26, v42
	ds_write_b32 v151, v148 offset:4896
	v_fmac_f32_e32 v27, v116, v26
	v_fmac_f32_e32 v43, v118, v42
	v_fmac_f32_dpp v27, v26, v122 quad_perm:[1,0,3,2] row_mask:0xf bank_mask:0xf
	v_fmac_f32_dpp v43, v42, v123 quad_perm:[1,0,3,2] row_mask:0xf bank_mask:0xf
	v_cvt_pk_bf16_f32 v149, v27, v43
	ds_write_b32 v151, v149 offset:5168
	v_fmac_f32_e32 v56, v116, v27
	v_fmac_f32_e32 v72, v118, v43
	v_fmac_f32_dpp v56, v27, v122 quad_perm:[1,0,3,2] row_mask:0xf bank_mask:0xf
	v_fmac_f32_dpp v72, v43, v123 quad_perm:[1,0,3,2] row_mask:0xf bank_mask:0xf
	v_cvt_pk_bf16_f32 v148, v56, v72
	ds_write_b32 v151, v148 offset:5440
	v_fmac_f32_e32 v57, v116, v56
	v_fmac_f32_e32 v73, v118, v72
	v_fmac_f32_dpp v57, v56, v122 quad_perm:[1,0,3,2] row_mask:0xf bank_mask:0xf
	v_fmac_f32_dpp v73, v72, v123 quad_perm:[1,0,3,2] row_mask:0xf bank_mask:0xf
	v_cvt_pk_bf16_f32 v149, v57, v73
	ds_write_b32 v151, v149 offset:5712
	v_fmac_f32_e32 v58, v116, v57
	v_fmac_f32_e32 v74, v118, v73
	v_fmac_f32_dpp v58, v57, v122 quad_perm:[1,0,3,2] row_mask:0xf bank_mask:0xf
	v_fmac_f32_dpp v74, v73, v123 quad_perm:[1,0,3,2] row_mask:0xf bank_mask:0xf
	v_cvt_pk_bf16_f32 v148, v58, v74
	ds_write_b32 v151, v148 offset:5984
	v_fmac_f32_e32 v59, v116, v58
	v_fmac_f32_e32 v75, v118, v74
	v_fmac_f32_dpp v59, v58, v122 quad_perm:[1,0,3,2] row_mask:0xf bank_mask:0xf
	v_fmac_f32_dpp v75, v74, v123 quad_perm:[1,0,3,2] row_mask:0xf bank_mask:0xf
	v_cvt_pk_bf16_f32 v149, v59, v75
	ds_write_b32 v151, v149 offset:6256
	v_fmac_f32_e32 v28, v116, v59
	v_fmac_f32_e32 v44, v118, v75
	v_fmac_f32_dpp v28, v59, v122 quad_perm:[1,0,3,2] row_mask:0xf bank_mask:0xf
	v_fmac_f32_dpp v44, v75, v123 quad_perm:[1,0,3,2] row_mask:0xf bank_mask:0xf
	v_cvt_pk_bf16_f32 v148, v28, v44
	ds_write_b32 v151, v148 offset:6528
	v_fmac_f32_e32 v29, v116, v28
	v_fmac_f32_e32 v45, v118, v44
	v_fmac_f32_dpp v29, v28, v122 quad_perm:[1,0,3,2] row_mask:0xf bank_mask:0xf
	v_fmac_f32_dpp v45, v44, v123 quad_perm:[1,0,3,2] row_mask:0xf bank_mask:0xf
	v_cvt_pk_bf16_f32 v149, v29, v45
	ds_write_b32 v151, v149 offset:6800
	v_fmac_f32_e32 v30, v116, v29
	v_fmac_f32_e32 v46, v118, v45
	v_fmac_f32_dpp v30, v29, v122 quad_perm:[1,0,3,2] row_mask:0xf bank_mask:0xf
	v_fmac_f32_dpp v46, v45, v123 quad_perm:[1,0,3,2] row_mask:0xf bank_mask:0xf
	v_cvt_pk_bf16_f32 v148, v30, v46
	ds_write_b32 v151, v148 offset:7072
	v_fmac_f32_e32 v31, v116, v30
	v_fmac_f32_e32 v47, v118, v46
	v_fmac_f32_dpp v31, v30, v122 quad_perm:[1,0,3,2] row_mask:0xf bank_mask:0xf
	v_fmac_f32_dpp v47, v46, v123 quad_perm:[1,0,3,2] row_mask:0xf bank_mask:0xf
	v_cvt_pk_bf16_f32 v149, v31, v47
	ds_write_b32 v151, v149 offset:7344
	v_fmac_f32_e32 v60, v116, v31
	v_fmac_f32_e32 v76, v118, v47
	v_fmac_f32_dpp v60, v31, v122 quad_perm:[1,0,3,2] row_mask:0xf bank_mask:0xf
	v_fmac_f32_dpp v76, v47, v123 quad_perm:[1,0,3,2] row_mask:0xf bank_mask:0xf
	v_cvt_pk_bf16_f32 v148, v60, v76
	ds_write_b32 v151, v148 offset:7616
	v_fmac_f32_e32 v61, v116, v60
	v_fmac_f32_e32 v77, v118, v76
	v_fmac_f32_dpp v61, v60, v122 quad_perm:[1,0,3,2] row_mask:0xf bank_mask:0xf
	v_fmac_f32_dpp v77, v76, v123 quad_perm:[1,0,3,2] row_mask:0xf bank_mask:0xf
	v_cvt_pk_bf16_f32 v149, v61, v77
	ds_write_b32 v151, v149 offset:7888
	v_fmac_f32_e32 v62, v116, v61
	v_fmac_f32_e32 v78, v118, v77
	v_fmac_f32_dpp v62, v61, v122 quad_perm:[1,0,3,2] row_mask:0xf bank_mask:0xf
	v_fmac_f32_dpp v78, v77, v123 quad_perm:[1,0,3,2] row_mask:0xf bank_mask:0xf
	v_cvt_pk_bf16_f32 v148, v62, v78
	ds_write_b32 v151, v148 offset:8160
	v_fmac_f32_e32 v63, v116, v62
	v_fmac_f32_e32 v79, v118, v78
	v_fmac_f32_dpp v63, v62, v122 quad_perm:[1,0,3,2] row_mask:0xf bank_mask:0xf
	v_fmac_f32_dpp v79, v78, v123 quad_perm:[1,0,3,2] row_mask:0xf bank_mask:0xf
	v_cvt_pk_bf16_f32 v149, v63, v79
	ds_write_b32 v151, v149 offset:8432
	v_mov_b32_e32 v120, v63
	v_mov_b32_e32 v121, v79
	ds_read_b128 v[124:127], v152
	ds_read_b128 v[128:131], v152 offset:64
	ds_read_b128 v[132:135], v152 offset:128
	ds_read_b128 v[136:139], v152 offset:192
	s_waitcnt lgkmcnt(3)
	v_mfma_f32_16x16x32_bf16 v[140:143], v[100:103], v[124:127], 0
	s_waitcnt lgkmcnt(2)
	v_mfma_f32_16x16x32_bf16 v[140:143], v[104:107], v[128:131], v[140:143]
	s_waitcnt lgkmcnt(1)
	v_mfma_f32_16x16x32_bf16 v[140:143], v[108:111], v[132:135], v[140:143]
	s_waitcnt lgkmcnt(0)
	v_mfma_f32_16x16x32_bf16 v[140:143], v[112:115], v[136:139], v[140:143]
	s_nop 9
	global_store_dwordx4 v153, v[140:143], s[12:13]
	s_nop 1
	ds_read_b128 v[124:127], v152 offset:4352
	ds_read_b128 v[128:131], v152 offset:4416
	ds_read_b128 v[132:135], v152 offset:4480
	ds_read_b128 v[136:139], v152 offset:4544
	s_waitcnt lgkmcnt(3)
	v_mfma_f32_16x16x32_bf16 v[140:143], v[100:103], v[124:127], 0
	s_waitcnt lgkmcnt(2)
	v_mfma_f32_16x16x32_bf16 v[140:143], v[104:107], v[128:131], v[140:143]
	s_waitcnt lgkmcnt(1)
	v_mfma_f32_16x16x32_bf16 v[140:143], v[108:111], v[132:135], v[140:143]
	s_waitcnt lgkmcnt(0)
	v_mfma_f32_16x16x32_bf16 v[140:143], v[112:115], v[136:139], v[140:143]
	s_nop 9
	global_store_dwordx4 v157, v[140:143], s[12:13]
	s_nop 1
	s_add_u32 s12, s12, 131072
	s_addc_u32 s13, s13, 0
	s_add_u32 s14, s14, 2
	s_cmp_lt_u32 s14, 16
	s_cbranch_scc1 .Lssm_tileA_d0m0
	s_waitcnt vmcnt(0) lgkmcnt(0)
	s_lshr_b32 s21, s89, 1
	s_lshl_b32 s21, s21, 2
	s_add_u32 s37, s21, 0x21000
	v_mov_b32_e32 v182, s37
	v_mov_b32_e32 v183, 1
	v_cmp_eq_u32_e32 vcc, 0, v191
	s_and_saveexec_b64 s[0:1], vcc
	ds_add_u32 v182, v183
	s_mov_b64 exec, s[0:1]
	s_waitcnt lgkmcnt(0)
	s_mov_b32 s38, 0
.Lssm_spin_d0m0:
	ds_read_b32 v183, v182
	s_waitcnt lgkmcnt(0)
	v_readfirstlane_b32 s39, v183
	s_nop 3
	s_cmp_ge_u32 s39, 2
	s_cbranch_scc1 .Lssm_spin_done_d0m0
	s_sleep 2
	s_add_u32 s38, s38, 1
	s_cmp_lt_u32 s38, 0x100000
	s_cbranch_scc1 .Lssm_spin_d0m0
.Lssm_spin_done_d0m0:
	s_mov_b64 s[42:43], s[12:13]
	s_add_u32 s42, s42, 67108864
	s_addc_u32 s43, s43, 0
	s_lshl_b32 s31, s25, 11
	s_lshl_b32 s29, s24, 5
	s_add_u32 s31, s31, s29
	s_add_u32 s31, s31, 344981504
	s_add_u32 s12, s62, s31
	s_addc_u32 s13, s63, 0
	s_mov_b64 s[64:65], s[34:35]
	s_sub_u32 s64, s64, 196608
	s_subb_u32 s65, s65, 0
	global_load_dwordx2 v[160:161], v154, s[64:65]
	global_load_dwordx2 v[162:163], v158, s[64:65]
	global_load_dwordx4 v[6:9], v153, s[42:43]
	global_load_dwordx4 v[10:13], v157, s[42:43]
	s_add_u32 s42, s42, 131072
	s_addc_u32 s43, s43, 0
	s_waitcnt vmcnt(0)
.Lssm_tileB_d0m0:
	s_waitcnt vmcnt(9)
	v_mfma_f32_32x32x16_bf16 v[16:31], v[80:83], v[84:87], 0
	v_mfma_f32_32x32x16_bf16 v[32:47], v[80:83], v[88:91], 0
	v_mfma_f32_32x32x16_bf16 v[48:63], v[80:83], v[92:95], 0
	v_mfma_f32_32x32x16_bf16 v[64:79], v[80:83], v[96:99], 0
	global_load_dwordx2 v[2:3], v154, s[34:35]
	global_load_dwordx2 v[4:5], v158, s[34:35]
	global_load_dwordx4 v[172:175], v153, s[42:43]
	global_load_dwordx4 v[176:179], v157, s[42:43]
	s_add_u32 s42, s42, 131072
	s_addc_u32 s43, s43, 0
	s_nop 11
	global_load_dwordx4 v[80:83], v150, s[10:11]
	s_add_u32 s34, s34, 196608
	s_addc_u32 s35, s35, 0
	s_add_u32 s10, s10, 196608
	s_addc_u32 s11, s11, 0
	v_permlane32_swap_b32_e32 v16, v48
	v_permlane32_swap_b32_e32 v17, v49
	v_permlane32_swap_b32_e32 v18, v50
	v_permlane32_swap_b32_e32 v19, v51
	v_permlane32_swap_b32_e32 v20, v52
	v_permlane32_swap_b32_e32 v21, v53
	v_permlane32_swap_b32_e32 v22, v54
	v_permlane32_swap_b32_e32 v23, v55
	v_permlane32_swap_b32_e32 v24, v56
	v_permlane32_swap_b32_e32 v25, v57
	v_permlane32_swap_b32_e32 v26, v58
	v_permlane32_swap_b32_e32 v27, v59
	v_permlane32_swap_b32_e32 v28, v60
	v_permlane32_swap_b32_e32 v29, v61
	v_permlane32_swap_b32_e32 v30, v62
	v_permlane32_swap_b32_e32 v31, v63
	v_permlane32_swap_b32_e32 v32, v64
	v_permlane32_swap_b32_e32 v33, v65
	v_permlane32_swap_b32_e32 v34, v66
	v_permlane32_swap_b32_e32 v35, v67
	v_permlane32_swap_b32_e32 v36, v68
	v_permlane32_swap_b32_e32 v37, v69
	v_permlane32_swap_b32_e32 v38, v70
	v_permlane32_swap_b32_e32 v39, v71
	v_permlane32_swap_b32_e32 v40, v72
	v_permlane32_swap_b32_e32 v41, v73
	v_permlane32_swap_b32_e32 v42, v74
	v_permlane32_swap_b32_e32 v43, v75
	v_permlane32_swap_b32_e32 v44, v76
	v_permlane32_swap_b32_e32 v45, v77
	v_permlane32_swap_b32_e32 v46, v78
	v_permlane32_swap_b32_e32 v47, v79
	v_fmac_f32_e32 v16, v116, v120
	v_fmac_f32_e32 v32, v118, v121
	v_fmac_f32_dpp v16, v120, v122 quad_perm:[1,0,3,2] row_mask:0xf bank_mask:0xf
	v_fmac_f32_dpp v32, v121, v123 quad_perm:[1,0,3,2] row_mask:0xf bank_mask:0xf
	v_cvt_pk_bf16_f32 v148, v16, v32
	ds_write_b32 v151, v148
	v_fmac_f32_e32 v17, v116, v16
	v_fmac_f32_e32 v33, v118, v32
	v_fmac_f32_dpp v17, v16, v122 quad_perm:[1,0,3,2] row_mask:0xf bank_mask:0xf
	v_fmac_f32_dpp v33, v32, v123 quad_perm:[1,0,3,2] row_mask:0xf bank_mask:0xf
	v_cvt_pk_bf16_f32 v149, v17, v33
	ds_write_b32 v151, v149 offset:272
	v_fmac_f32_e32 v18, v116, v17
	v_fmac_f32_e32 v34, v118, v33
	v_fmac_f32_dpp v18, v17, v122 quad_perm:[1,0,3,2] row_mask:0xf bank_mask:0xf
	v_fmac_f32_dpp v34, v33, v123 quad_perm:[1,0,3,2] row_mask:0xf bank_mask:0xf
	v_cvt_pk_bf16_f32 v148, v18, v34
	ds_write_b32 v151, v148 offset:544
	v_fmac_f32_e32 v19, v116, v18
	v_fmac_f32_e32 v35, v118, v34
	v_fmac_f32_dpp v19, v18, v122 quad_perm:[1,0,3,2] row_mask:0xf bank_mask:0xf
	v_fmac_f32_dpp v35, v34, v123 quad_perm:[1,0,3,2] row_mask:0xf bank_mask:0xf
	v_cvt_pk_bf16_f32 v149, v19, v35
	ds_write_b32 v151, v149 offset:816
	v_fmac_f32_e32 v48, v116, v19
	v_fmac_f32_e32 v64, v118, v35
	v_fmac_f32_dpp v48, v19, v122 quad_perm:[1,0,3,2] row_mask:0xf bank_mask:0xf
	v_fmac_f32_dpp v64, v35, v123 quad_perm:[1,0,3,2] row_mask:0xf bank_mask:0xf
	v_cvt_pk_bf16_f32 v148, v48, v64
	ds_write_b32 v151, v148 offset:1088
	v_fmac_f32_e32 v49, v116, v48
	v_fmac_f32_e32 v65, v118, v64
	v_fmac_f32_dpp v49, v48, v122 quad_perm:[1,0,3,2] row_mask:0xf bank_mask:0xf
	v_fmac_f32_dpp v65, v64, v123 quad_perm:[1,0,3,2] row_mask:0xf bank_mask:0xf
	v_cvt_pk_bf16_f32 v149, v49, v65
	ds_write_b32 v151, v149 offset:1360
	v_fmac_f32_e32 v50, v116, v49
	v_fmac_f32_e32 v66, v118, v65
	v_fmac_f32_dpp v50, v49, v122 quad_perm:[1,0,3,2] row_mask:0xf bank_mask:0xf
	v_fmac_f32_dpp v66, v65, v123 quad_perm:[1,0,3,2] row_mask:0xf bank_mask:0xf
	v_cvt_pk_bf16_f32 v148, v50, v66
	ds_write_b32 v151, v148 offset:1632
	v_fmac_f32_e32 v51, v116, v50
	v_fmac_f32_e32 v67, v118, v66
	v_fmac_f32_dpp v51, v50, v122 quad_perm:[1,0,3,2] row_mask:0xf bank_mask:0xf
	v_fmac_f32_dpp v67, v66, v123 quad_perm:[1,0,3,2] row_mask:0xf bank_mask:0xf
	v_cvt_pk_bf16_f32 v149, v51, v67
	ds_write_b32 v151, v149 offset:1904
	v_fmac_f32_e32 v20, v116, v51
	v_fmac_f32_e32 v36, v118, v67
	v_fmac_f32_dpp v20, v51, v122 quad_perm:[1,0,3,2] row_mask:0xf bank_mask:0xf
	v_fmac_f32_dpp v36, v67, v123 quad_perm:[1,0,3,2] row_mask:0xf bank_mask:0xf
	v_cvt_pk_bf16_f32 v148, v20, v36
	ds_write_b32 v151, v148 offset:2176
	v_fmac_f32_e32 v21, v116, v20
	v_fmac_f32_e32 v37, v118, v36
	v_fmac_f32_dpp v21, v20, v122 quad_perm:[1,0,3,2] row_mask:0xf bank_mask:0xf
	v_fmac_f32_dpp v37, v36, v123 quad_perm:[1,0,3,2] row_mask:0xf bank_mask:0xf
	v_cvt_pk_bf16_f32 v149, v21, v37
	ds_write_b32 v151, v149 offset:2448
	v_fmac_f32_e32 v22, v116, v21
	v_fmac_f32_e32 v38, v118, v37
	v_fmac_f32_dpp v22, v21, v122 quad_perm:[1,0,3,2] row_mask:0xf bank_mask:0xf
	v_fmac_f32_dpp v38, v37, v123 quad_perm:[1,0,3,2] row_mask:0xf bank_mask:0xf
	v_cvt_pk_bf16_f32 v148, v22, v38
	ds_write_b32 v151, v148 offset:2720
	v_fmac_f32_e32 v23, v116, v22
	v_fmac_f32_e32 v39, v118, v38
	v_fmac_f32_dpp v23, v22, v122 quad_perm:[1,0,3,2] row_mask:0xf bank_mask:0xf
	v_fmac_f32_dpp v39, v38, v123 quad_perm:[1,0,3,2] row_mask:0xf bank_mask:0xf
	v_cvt_pk_bf16_f32 v149, v23, v39
	ds_write_b32 v151, v149 offset:2992
	v_fmac_f32_e32 v52, v116, v23
	v_fmac_f32_e32 v68, v118, v39
	v_fmac_f32_dpp v52, v23, v122 quad_perm:[1,0,3,2] row_mask:0xf bank_mask:0xf
	v_fmac_f32_dpp v68, v39, v123 quad_perm:[1,0,3,2] row_mask:0xf bank_mask:0xf
	v_cvt_pk_bf16_f32 v148, v52, v68
	ds_write_b32 v151, v148 offset:3264
	v_fmac_f32_e32 v53, v116, v52
	v_fmac_f32_e32 v69, v118, v68
	v_fmac_f32_dpp v53, v52, v122 quad_perm:[1,0,3,2] row_mask:0xf bank_mask:0xf
	v_fmac_f32_dpp v69, v68, v123 quad_perm:[1,0,3,2] row_mask:0xf bank_mask:0xf
	v_cvt_pk_bf16_f32 v149, v53, v69
	ds_write_b32 v151, v149 offset:3536
	v_fmac_f32_e32 v54, v116, v53
	v_fmac_f32_e32 v70, v118, v69
	v_fmac_f32_dpp v54, v53, v122 quad_perm:[1,0,3,2] row_mask:0xf bank_mask:0xf
	v_fmac_f32_dpp v70, v69, v123 quad_perm:[1,0,3,2] row_mask:0xf bank_mask:0xf
	v_cvt_pk_bf16_f32 v148, v54, v70
	ds_write_b32 v151, v148 offset:3808
	v_fmac_f32_e32 v55, v116, v54
	v_fmac_f32_e32 v71, v118, v70
	v_fmac_f32_dpp v55, v54, v122 quad_perm:[1,0,3,2] row_mask:0xf bank_mask:0xf
	v_fmac_f32_dpp v71, v70, v123 quad_perm:[1,0,3,2] row_mask:0xf bank_mask:0xf
	v_cvt_pk_bf16_f32 v149, v55, v71
	ds_write_b32 v151, v149 offset:4080
	v_fmac_f32_e32 v24, v116, v55
	v_fmac_f32_e32 v40, v118, v71
	v_fmac_f32_dpp v24, v55, v122 quad_perm:[1,0,3,2] row_mask:0xf bank_mask:0xf
	v_fmac_f32_dpp v40, v71, v123 quad_perm:[1,0,3,2] row_mask:0xf bank_mask:0xf
	v_cvt_pk_bf16_f32 v148, v24, v40
	ds_write_b32 v151, v148 offset:4352
	v_fmac_f32_e32 v25, v116, v24
	v_fmac_f32_e32 v41, v118, v40
	v_fmac_f32_dpp v25, v24, v122 quad_perm:[1,0,3,2] row_mask:0xf bank_mask:0xf
	v_fmac_f32_dpp v41, v40, v123 quad_perm:[1,0,3,2] row_mask:0xf bank_mask:0xf
	v_cvt_pk_bf16_f32 v149, v25, v41
	ds_write_b32 v151, v149 offset:4624
	v_fmac_f32_e32 v26, v116, v25
	v_fmac_f32_e32 v42, v118, v41
	v_fmac_f32_dpp v26, v25, v122 quad_perm:[1,0,3,2] row_mask:0xf bank_mask:0xf
	v_fmac_f32_dpp v42, v41, v123 quad_perm:[1,0,3,2] row_mask:0xf bank_mask:0xf
	v_cvt_pk_bf16_f32 v148, v26, v42
	ds_write_b32 v151, v148 offset:4896
	v_fmac_f32_e32 v27, v116, v26
	v_fmac_f32_e32 v43, v118, v42
	v_fmac_f32_dpp v27, v26, v122 quad_perm:[1,0,3,2] row_mask:0xf bank_mask:0xf
	v_fmac_f32_dpp v43, v42, v123 quad_perm:[1,0,3,2] row_mask:0xf bank_mask:0xf
	v_cvt_pk_bf16_f32 v149, v27, v43
	ds_write_b32 v151, v149 offset:5168
	v_fmac_f32_e32 v56, v116, v27
	v_fmac_f32_e32 v72, v118, v43
	v_fmac_f32_dpp v56, v27, v122 quad_perm:[1,0,3,2] row_mask:0xf bank_mask:0xf
	v_fmac_f32_dpp v72, v43, v123 quad_perm:[1,0,3,2] row_mask:0xf bank_mask:0xf
	v_cvt_pk_bf16_f32 v148, v56, v72
	ds_write_b32 v151, v148 offset:5440
	v_fmac_f32_e32 v57, v116, v56
	v_fmac_f32_e32 v73, v118, v72
	v_fmac_f32_dpp v57, v56, v122 quad_perm:[1,0,3,2] row_mask:0xf bank_mask:0xf
	v_fmac_f32_dpp v73, v72, v123 quad_perm:[1,0,3,2] row_mask:0xf bank_mask:0xf
	v_cvt_pk_bf16_f32 v149, v57, v73
	ds_write_b32 v151, v149 offset:5712
	v_fmac_f32_e32 v58, v116, v57
	v_fmac_f32_e32 v74, v118, v73
	v_fmac_f32_dpp v58, v57, v122 quad_perm:[1,0,3,2] row_mask:0xf bank_mask:0xf
	v_fmac_f32_dpp v74, v73, v123 quad_perm:[1,0,3,2] row_mask:0xf bank_mask:0xf
	v_cvt_pk_bf16_f32 v148, v58, v74
	ds_write_b32 v151, v148 offset:5984
	v_fmac_f32_e32 v59, v116, v58
	v_fmac_f32_e32 v75, v118, v74
	v_fmac_f32_dpp v59, v58, v122 quad_perm:[1,0,3,2] row_mask:0xf bank_mask:0xf
	v_fmac_f32_dpp v75, v74, v123 quad_perm:[1,0,3,2] row_mask:0xf bank_mask:0xf
	v_cvt_pk_bf16_f32 v149, v59, v75
	ds_write_b32 v151, v149 offset:6256
	v_fmac_f32_e32 v28, v116, v59
	v_fmac_f32_e32 v44, v118, v75
	v_fmac_f32_dpp v28, v59, v122 quad_perm:[1,0,3,2] row_mask:0xf bank_mask:0xf
	v_fmac_f32_dpp v44, v75, v123 quad_perm:[1,0,3,2] row_mask:0xf bank_mask:0xf
	v_cvt_pk_bf16_f32 v148, v28, v44
	ds_write_b32 v151, v148 offset:6528
	v_fmac_f32_e32 v29, v116, v28
	v_fmac_f32_e32 v45, v118, v44
	v_fmac_f32_dpp v29, v28, v122 quad_perm:[1,0,3,2] row_mask:0xf bank_mask:0xf
	v_fmac_f32_dpp v45, v44, v123 quad_perm:[1,0,3,2] row_mask:0xf bank_mask:0xf
	v_cvt_pk_bf16_f32 v149, v29, v45
	ds_write_b32 v151, v149 offset:6800
	v_fmac_f32_e32 v30, v116, v29
	v_fmac_f32_e32 v46, v118, v45
	v_fmac_f32_dpp v30, v29, v122 quad_perm:[1,0,3,2] row_mask:0xf bank_mask:0xf
	v_fmac_f32_dpp v46, v45, v123 quad_perm:[1,0,3,2] row_mask:0xf bank_mask:0xf
	v_cvt_pk_bf16_f32 v148, v30, v46
	ds_write_b32 v151, v148 offset:7072
	v_fmac_f32_e32 v31, v116, v30
	v_fmac_f32_e32 v47, v118, v46
	v_fmac_f32_dpp v31, v30, v122 quad_perm:[1,0,3,2] row_mask:0xf bank_mask:0xf
	v_fmac_f32_dpp v47, v46, v123 quad_perm:[1,0,3,2] row_mask:0xf bank_mask:0xf
	v_cvt_pk_bf16_f32 v149, v31, v47
	ds_write_b32 v151, v149 offset:7344
	v_fmac_f32_e32 v60, v116, v31
	v_fmac_f32_e32 v76, v118, v47
	v_fmac_f32_dpp v60, v31, v122 quad_perm:[1,0,3,2] row_mask:0xf bank_mask:0xf
	v_fmac_f32_dpp v76, v47, v123 quad_perm:[1,0,3,2] row_mask:0xf bank_mask:0xf
	v_cvt_pk_bf16_f32 v148, v60, v76
	ds_write_b32 v151, v148 offset:7616
	v_fmac_f32_e32 v61, v116, v60
	v_fmac_f32_e32 v77, v118, v76
	v_fmac_f32_dpp v61, v60, v122 quad_perm:[1,0,3,2] row_mask:0xf bank_mask:0xf
	v_fmac_f32_dpp v77, v76, v123 quad_perm:[1,0,3,2] row_mask:0xf bank_mask:0xf
	v_cvt_pk_bf16_f32 v149, v61, v77
	ds_write_b32 v151, v149 offset:7888
	v_fmac_f32_e32 v62, v116, v61
	v_fmac_f32_e32 v78, v118, v77
	v_fmac_f32_dpp v62, v61, v122 quad_perm:[1,0,3,2] row_mask:0xf bank_mask:0xf
	v_fmac_f32_dpp v78, v77, v123 quad_perm:[1,0,3,2] row_mask:0xf bank_mask:0xf
	v_cvt_pk_bf16_f32 v148, v62, v78
	ds_write_b32 v151, v148 offset:8160
	v_fmac_f32_e32 v63, v116, v62
	v_fmac_f32_e32 v79, v118, v78
	v_fmac_f32_dpp v63, v62, v122 quad_perm:[1,0,3,2] row_mask:0xf bank_mask:0xf
	v_fmac_f32_dpp v79, v78, v123 quad_perm:[1,0,3,2] row_mask:0xf bank_mask:0xf
	v_cvt_pk_bf16_f32 v149, v63, v79
	ds_write_b32 v151, v149 offset:8432
	v_mov_b32_e32 v120, v63
	v_mov_b32_e32 v121, v79
	ds_read_b128 v[124:127], v152
	ds_read_b128 v[128:131], v152 offset:64
	ds_read_b128 v[132:135], v152 offset:128
	ds_read_b128 v[136:139], v152 offset:192
	s_waitcnt lgkmcnt(3)
	v_mfma_f32_16x16x32_bf16 v[140:143], v[100:103], v[124:127], 0
	s_waitcnt lgkmcnt(2)
	v_mfma_f32_16x16x32_bf16 v[140:143], v[104:107], v[128:131], v[140:143]
	s_waitcnt lgkmcnt(1)
	v_mfma_f32_16x16x32_bf16 v[140:143], v[108:111], v[132:135], v[140:143]
	s_waitcnt lgkmcnt(0)
	v_mfma_f32_16x16x32_bf16 v[140:143], v[112:115], v[136:139], v[140:143]
	s_nop 9
	s_waitcnt vmcnt(9)
	v_add_f32_e32 v182, v6, v140
	v_add_f32_e32 v183, v7, v141
	v_add_f32_e32 v184, v8, v142
	v_add_f32_e32 v185, v9, v143
	v_lshlrev_b32_e32 v186, 16, v160
	v_and_b32_e32 v187, 0xffff0000, v160
	v_lshlrev_b32_e32 v188, 16, v161
	v_and_b32_e32 v189, 0xffff0000, v161
	v_fmac_f32_e32 v182, v164, v186
	v_fmac_f32_e32 v183, v165, v187
	v_fmac_f32_e32 v184, v166, v188
	v_fmac_f32_e32 v185, v167, v189
	v_mul_f32_e32 v186, 0x3d372713, v182
	v_mul_f32_e32 v187, 0x3d372713, v183
	v_mul_f32_e32 v188, 0x3d372713, v184
	v_mul_f32_e32 v189, 0x3d372713, v185
	v_mul_f32_e32 v186, v182, v186
	v_mul_f32_e32 v187, v183, v187
	v_mul_f32_e32 v188, v184, v188
	v_mul_f32_e32 v189, v185, v189
	v_fma_f32 v186, v182, v186, v182
	v_fma_f32 v187, v183, v187, v183
	v_fma_f32 v188, v184, v188, v184
	v_fma_f32 v189, v185, v189, v185
	v_mul_f32_e32 v186, 0xbfcc422a, v186
	v_mul_f32_e32 v187, 0xbfcc422a, v187
	v_mul_f32_e32 v188, 0xbfcc422a, v188
	v_mul_f32_e32 v189, 0xbfcc422a, v189
	v_mul_f32_e32 v186, 0x3fb8aa3b, v186
	v_mul_f32_e32 v187, 0x3fb8aa3b, v187
	v_mul_f32_e32 v188, 0x3fb8aa3b, v188
	v_mul_f32_e32 v189, 0x3fb8aa3b, v189
	v_exp_f32_e32 v186, v186
	v_exp_f32_e32 v187, v187
	v_exp_f32_e32 v188, v188
	v_exp_f32_e32 v189, v189
	v_add_f32_e32 v186, 1.0, v186
	v_add_f32_e32 v187, 1.0, v187
	v_add_f32_e32 v188, 1.0, v188
	v_add_f32_e32 v189, 1.0, v189
	v_rcp_f32_e32 v186, v186
	v_rcp_f32_e32 v187, v187
	v_rcp_f32_e32 v188, v188
	v_rcp_f32_e32 v189, v189
	v_mul_f32_e32 v182, v182, v186
	v_mul_f32_e32 v183, v183, v187
	v_mul_f32_e32 v184, v184, v188
	v_mul_f32_e32 v185, v185, v189
	v_cvt_pk_bf16_f32 v148, v182, v183
	v_cvt_pk_bf16_f32 v149, v184, v185
	global_store_dwordx2 v156, v[148:149], s[12:13]
	ds_read_b128 v[124:127], v152 offset:4352
	ds_read_b128 v[128:131], v152 offset:4416
	ds_read_b128 v[132:135], v152 offset:4480
	ds_read_b128 v[136:139], v152 offset:4544
	s_waitcnt lgkmcnt(3)
	v_mfma_f32_16x16x32_bf16 v[140:143], v[100:103], v[124:127], 0
	s_waitcnt lgkmcnt(2)
	v_mfma_f32_16x16x32_bf16 v[140:143], v[104:107], v[128:131], v[140:143]
	s_waitcnt lgkmcnt(1)
	v_mfma_f32_16x16x32_bf16 v[140:143], v[108:111], v[132:135], v[140:143]
	s_waitcnt lgkmcnt(0)
	v_mfma_f32_16x16x32_bf16 v[140:143], v[112:115], v[136:139], v[140:143]
	s_nop 9
	s_waitcnt vmcnt(9)
	v_add_f32_e32 v182, v10, v140
	v_add_f32_e32 v183, v11, v141
	v_add_f32_e32 v184, v12, v142
	v_add_f32_e32 v185, v13, v143
	v_lshlrev_b32_e32 v186, 16, v162
	v_and_b32_e32 v187, 0xffff0000, v162
	v_lshlrev_b32_e32 v188, 16, v163
	v_and_b32_e32 v189, 0xffff0000, v163
	v_fmac_f32_e32 v182, v164, v186
	v_fmac_f32_e32 v183, v165, v187
	v_fmac_f32_e32 v184, v166, v188
	v_fmac_f32_e32 v185, v167, v189
	v_mul_f32_e32 v186, 0x3d372713, v182
	v_mul_f32_e32 v187, 0x3d372713, v183
	v_mul_f32_e32 v188, 0x3d372713, v184
	v_mul_f32_e32 v189, 0x3d372713, v185
	v_mul_f32_e32 v186, v182, v186
	v_mul_f32_e32 v187, v183, v187
	v_mul_f32_e32 v188, v184, v188
	v_mul_f32_e32 v189, v185, v189
	v_fma_f32 v186, v182, v186, v182
	v_fma_f32 v187, v183, v187, v183
	v_fma_f32 v188, v184, v188, v184
	v_fma_f32 v189, v185, v189, v185
	v_mul_f32_e32 v186, 0xbfcc422a, v186
	v_mul_f32_e32 v187, 0xbfcc422a, v187
	v_mul_f32_e32 v188, 0xbfcc422a, v188
	v_mul_f32_e32 v189, 0xbfcc422a, v189
	v_mul_f32_e32 v186, 0x3fb8aa3b, v186
	v_mul_f32_e32 v187, 0x3fb8aa3b, v187
	v_mul_f32_e32 v188, 0x3fb8aa3b, v188
	v_mul_f32_e32 v189, 0x3fb8aa3b, v189
	v_exp_f32_e32 v186, v186
	v_exp_f32_e32 v187, v187
	v_exp_f32_e32 v188, v188
	v_exp_f32_e32 v189, v189
	v_add_f32_e32 v186, 1.0, v186
	v_add_f32_e32 v187, 1.0, v187
	v_add_f32_e32 v188, 1.0, v188
	v_add_f32_e32 v189, 1.0, v189
	v_rcp_f32_e32 v186, v186
	v_rcp_f32_e32 v187, v187
	v_rcp_f32_e32 v188, v188
	v_rcp_f32_e32 v189, v189
	v_mul_f32_e32 v182, v182, v186
	v_mul_f32_e32 v183, v183, v187
	v_mul_f32_e32 v184, v184, v188
	v_mul_f32_e32 v185, v185, v189
	v_cvt_pk_bf16_f32 v148, v182, v183
	v_cvt_pk_bf16_f32 v149, v184, v185
	global_store_dwordx2 v159, v[148:149], s[12:13]
	s_add_u32 s12, s12, 65536
	s_addc_u32 s13, s13, 0
	s_waitcnt vmcnt(9)
	v_mfma_f32_32x32x16_bf16 v[16:31], v[144:147], v[84:87], 0
	v_mfma_f32_32x32x16_bf16 v[32:47], v[144:147], v[88:91], 0
	v_mfma_f32_32x32x16_bf16 v[48:63], v[144:147], v[92:95], 0
	v_mfma_f32_32x32x16_bf16 v[64:79], v[144:147], v[96:99], 0
	global_load_dwordx2 v[160:161], v154, s[34:35]
	global_load_dwordx2 v[162:163], v158, s[34:35]
	global_load_dwordx4 v[6:9], v153, s[42:43]
	global_load_dwordx4 v[10:13], v157, s[42:43]
	s_add_u32 s42, s42, 131072
	s_addc_u32 s43, s43, 0
	s_nop 11
	global_load_dwordx4 v[144:147], v150, s[10:11]
	s_add_u32 s34, s34, 196608
	s_addc_u32 s35, s35, 0
	s_add_u32 s10, s10, 196608
	s_addc_u32 s11, s11, 0
	v_permlane32_swap_b32_e32 v16, v48
	v_permlane32_swap_b32_e32 v17, v49
	v_permlane32_swap_b32_e32 v18, v50
	v_permlane32_swap_b32_e32 v19, v51
	v_permlane32_swap_b32_e32 v20, v52
	v_permlane32_swap_b32_e32 v21, v53
	v_permlane32_swap_b32_e32 v22, v54
	v_permlane32_swap_b32_e32 v23, v55
	v_permlane32_swap_b32_e32 v24, v56
	v_permlane32_swap_b32_e32 v25, v57
	v_permlane32_swap_b32_e32 v26, v58
	v_permlane32_swap_b32_e32 v27, v59
	v_permlane32_swap_b32_e32 v28, v60
	v_permlane32_swap_b32_e32 v29, v61
	v_permlane32_swap_b32_e32 v30, v62
	v_permlane32_swap_b32_e32 v31, v63
	v_permlane32_swap_b32_e32 v32, v64
	v_permlane32_swap_b32_e32 v33, v65
	v_permlane32_swap_b32_e32 v34, v66
	v_permlane32_swap_b32_e32 v35, v67
	v_permlane32_swap_b32_e32 v36, v68
	v_permlane32_swap_b32_e32 v37, v69
	v_permlane32_swap_b32_e32 v38, v70
	v_permlane32_swap_b32_e32 v39, v71
	v_permlane32_swap_b32_e32 v40, v72
	v_permlane32_swap_b32_e32 v41, v73
	v_permlane32_swap_b32_e32 v42, v74
	v_permlane32_swap_b32_e32 v43, v75
	v_permlane32_swap_b32_e32 v44, v76
	v_permlane32_swap_b32_e32 v45, v77
	v_permlane32_swap_b32_e32 v46, v78
	v_permlane32_swap_b32_e32 v47, v79
	v_fmac_f32_e32 v16, v116, v120
	v_fmac_f32_e32 v32, v118, v121
	v_fmac_f32_dpp v16, v120, v122 quad_perm:[1,0,3,2] row_mask:0xf bank_mask:0xf
	v_fmac_f32_dpp v32, v121, v123 quad_perm:[1,0,3,2] row_mask:0xf bank_mask:0xf
	v_cvt_pk_bf16_f32 v148, v16, v32
	ds_write_b32 v151, v148
	v_fmac_f32_e32 v17, v116, v16
	v_fmac_f32_e32 v33, v118, v32
	v_fmac_f32_dpp v17, v16, v122 quad_perm:[1,0,3,2] row_mask:0xf bank_mask:0xf
	v_fmac_f32_dpp v33, v32, v123 quad_perm:[1,0,3,2] row_mask:0xf bank_mask:0xf
	v_cvt_pk_bf16_f32 v149, v17, v33
	ds_write_b32 v151, v149 offset:272
	v_fmac_f32_e32 v18, v116, v17
	v_fmac_f32_e32 v34, v118, v33
	v_fmac_f32_dpp v18, v17, v122 quad_perm:[1,0,3,2] row_mask:0xf bank_mask:0xf
	v_fmac_f32_dpp v34, v33, v123 quad_perm:[1,0,3,2] row_mask:0xf bank_mask:0xf
	v_cvt_pk_bf16_f32 v148, v18, v34
	ds_write_b32 v151, v148 offset:544
	v_fmac_f32_e32 v19, v116, v18
	v_fmac_f32_e32 v35, v118, v34
	v_fmac_f32_dpp v19, v18, v122 quad_perm:[1,0,3,2] row_mask:0xf bank_mask:0xf
	v_fmac_f32_dpp v35, v34, v123 quad_perm:[1,0,3,2] row_mask:0xf bank_mask:0xf
	v_cvt_pk_bf16_f32 v149, v19, v35
	ds_write_b32 v151, v149 offset:816
	v_fmac_f32_e32 v48, v116, v19
	v_fmac_f32_e32 v64, v118, v35
	v_fmac_f32_dpp v48, v19, v122 quad_perm:[1,0,3,2] row_mask:0xf bank_mask:0xf
	v_fmac_f32_dpp v64, v35, v123 quad_perm:[1,0,3,2] row_mask:0xf bank_mask:0xf
	v_cvt_pk_bf16_f32 v148, v48, v64
	ds_write_b32 v151, v148 offset:1088
	v_fmac_f32_e32 v49, v116, v48
	v_fmac_f32_e32 v65, v118, v64
	v_fmac_f32_dpp v49, v48, v122 quad_perm:[1,0,3,2] row_mask:0xf bank_mask:0xf
	v_fmac_f32_dpp v65, v64, v123 quad_perm:[1,0,3,2] row_mask:0xf bank_mask:0xf
	v_cvt_pk_bf16_f32 v149, v49, v65
	ds_write_b32 v151, v149 offset:1360
	v_fmac_f32_e32 v50, v116, v49
	v_fmac_f32_e32 v66, v118, v65
	v_fmac_f32_dpp v50, v49, v122 quad_perm:[1,0,3,2] row_mask:0xf bank_mask:0xf
	v_fmac_f32_dpp v66, v65, v123 quad_perm:[1,0,3,2] row_mask:0xf bank_mask:0xf
	v_cvt_pk_bf16_f32 v148, v50, v66
	ds_write_b32 v151, v148 offset:1632
	v_fmac_f32_e32 v51, v116, v50
	v_fmac_f32_e32 v67, v118, v66
	v_fmac_f32_dpp v51, v50, v122 quad_perm:[1,0,3,2] row_mask:0xf bank_mask:0xf
	v_fmac_f32_dpp v67, v66, v123 quad_perm:[1,0,3,2] row_mask:0xf bank_mask:0xf
	v_cvt_pk_bf16_f32 v149, v51, v67
	ds_write_b32 v151, v149 offset:1904
	v_fmac_f32_e32 v20, v116, v51
	v_fmac_f32_e32 v36, v118, v67
	v_fmac_f32_dpp v20, v51, v122 quad_perm:[1,0,3,2] row_mask:0xf bank_mask:0xf
	v_fmac_f32_dpp v36, v67, v123 quad_perm:[1,0,3,2] row_mask:0xf bank_mask:0xf
	v_cvt_pk_bf16_f32 v148, v20, v36
	ds_write_b32 v151, v148 offset:2176
	v_fmac_f32_e32 v21, v116, v20
	v_fmac_f32_e32 v37, v118, v36
	v_fmac_f32_dpp v21, v20, v122 quad_perm:[1,0,3,2] row_mask:0xf bank_mask:0xf
	v_fmac_f32_dpp v37, v36, v123 quad_perm:[1,0,3,2] row_mask:0xf bank_mask:0xf
	v_cvt_pk_bf16_f32 v149, v21, v37
	ds_write_b32 v151, v149 offset:2448
	v_fmac_f32_e32 v22, v116, v21
	v_fmac_f32_e32 v38, v118, v37
	v_fmac_f32_dpp v22, v21, v122 quad_perm:[1,0,3,2] row_mask:0xf bank_mask:0xf
	v_fmac_f32_dpp v38, v37, v123 quad_perm:[1,0,3,2] row_mask:0xf bank_mask:0xf
	v_cvt_pk_bf16_f32 v148, v22, v38
	ds_write_b32 v151, v148 offset:2720
	v_fmac_f32_e32 v23, v116, v22
	v_fmac_f32_e32 v39, v118, v38
	v_fmac_f32_dpp v23, v22, v122 quad_perm:[1,0,3,2] row_mask:0xf bank_mask:0xf
	v_fmac_f32_dpp v39, v38, v123 quad_perm:[1,0,3,2] row_mask:0xf bank_mask:0xf
	v_cvt_pk_bf16_f32 v149, v23, v39
	ds_write_b32 v151, v149 offset:2992
	v_fmac_f32_e32 v52, v116, v23
	v_fmac_f32_e32 v68, v118, v39
	v_fmac_f32_dpp v52, v23, v122 quad_perm:[1,0,3,2] row_mask:0xf bank_mask:0xf
	v_fmac_f32_dpp v68, v39, v123 quad_perm:[1,0,3,2] row_mask:0xf bank_mask:0xf
	v_cvt_pk_bf16_f32 v148, v52, v68
	ds_write_b32 v151, v148 offset:3264
	v_fmac_f32_e32 v53, v116, v52
	v_fmac_f32_e32 v69, v118, v68
	v_fmac_f32_dpp v53, v52, v122 quad_perm:[1,0,3,2] row_mask:0xf bank_mask:0xf
	v_fmac_f32_dpp v69, v68, v123 quad_perm:[1,0,3,2] row_mask:0xf bank_mask:0xf
	v_cvt_pk_bf16_f32 v149, v53, v69
	ds_write_b32 v151, v149 offset:3536
	v_fmac_f32_e32 v54, v116, v53
	v_fmac_f32_e32 v70, v118, v69
	v_fmac_f32_dpp v54, v53, v122 quad_perm:[1,0,3,2] row_mask:0xf bank_mask:0xf
	v_fmac_f32_dpp v70, v69, v123 quad_perm:[1,0,3,2] row_mask:0xf bank_mask:0xf
	v_cvt_pk_bf16_f32 v148, v54, v70
	ds_write_b32 v151, v148 offset:3808
	v_fmac_f32_e32 v55, v116, v54
	v_fmac_f32_e32 v71, v118, v70
	v_fmac_f32_dpp v55, v54, v122 quad_perm:[1,0,3,2] row_mask:0xf bank_mask:0xf
	v_fmac_f32_dpp v71, v70, v123 quad_perm:[1,0,3,2] row_mask:0xf bank_mask:0xf
	v_cvt_pk_bf16_f32 v149, v55, v71
	ds_write_b32 v151, v149 offset:4080
	v_fmac_f32_e32 v24, v116, v55
	v_fmac_f32_e32 v40, v118, v71
	v_fmac_f32_dpp v24, v55, v122 quad_perm:[1,0,3,2] row_mask:0xf bank_mask:0xf
	v_fmac_f32_dpp v40, v71, v123 quad_perm:[1,0,3,2] row_mask:0xf bank_mask:0xf
	v_cvt_pk_bf16_f32 v148, v24, v40
	ds_write_b32 v151, v148 offset:4352
	v_fmac_f32_e32 v25, v116, v24
	v_fmac_f32_e32 v41, v118, v40
	v_fmac_f32_dpp v25, v24, v122 quad_perm:[1,0,3,2] row_mask:0xf bank_mask:0xf
	v_fmac_f32_dpp v41, v40, v123 quad_perm:[1,0,3,2] row_mask:0xf bank_mask:0xf
	v_cvt_pk_bf16_f32 v149, v25, v41
	ds_write_b32 v151, v149 offset:4624
	v_fmac_f32_e32 v26, v116, v25
	v_fmac_f32_e32 v42, v118, v41
	v_fmac_f32_dpp v26, v25, v122 quad_perm:[1,0,3,2] row_mask:0xf bank_mask:0xf
	v_fmac_f32_dpp v42, v41, v123 quad_perm:[1,0,3,2] row_mask:0xf bank_mask:0xf
	v_cvt_pk_bf16_f32 v148, v26, v42
	ds_write_b32 v151, v148 offset:4896
	v_fmac_f32_e32 v27, v116, v26
	v_fmac_f32_e32 v43, v118, v42
	v_fmac_f32_dpp v27, v26, v122 quad_perm:[1,0,3,2] row_mask:0xf bank_mask:0xf
	v_fmac_f32_dpp v43, v42, v123 quad_perm:[1,0,3,2] row_mask:0xf bank_mask:0xf
	v_cvt_pk_bf16_f32 v149, v27, v43
	ds_write_b32 v151, v149 offset:5168
	v_fmac_f32_e32 v56, v116, v27
	v_fmac_f32_e32 v72, v118, v43
	v_fmac_f32_dpp v56, v27, v122 quad_perm:[1,0,3,2] row_mask:0xf bank_mask:0xf
	v_fmac_f32_dpp v72, v43, v123 quad_perm:[1,0,3,2] row_mask:0xf bank_mask:0xf
	v_cvt_pk_bf16_f32 v148, v56, v72
	ds_write_b32 v151, v148 offset:5440
	v_fmac_f32_e32 v57, v116, v56
	v_fmac_f32_e32 v73, v118, v72
	v_fmac_f32_dpp v57, v56, v122 quad_perm:[1,0,3,2] row_mask:0xf bank_mask:0xf
	v_fmac_f32_dpp v73, v72, v123 quad_perm:[1,0,3,2] row_mask:0xf bank_mask:0xf
	v_cvt_pk_bf16_f32 v149, v57, v73
	ds_write_b32 v151, v149 offset:5712
	v_fmac_f32_e32 v58, v116, v57
	v_fmac_f32_e32 v74, v118, v73
	v_fmac_f32_dpp v58, v57, v122 quad_perm:[1,0,3,2] row_mask:0xf bank_mask:0xf
	v_fmac_f32_dpp v74, v73, v123 quad_perm:[1,0,3,2] row_mask:0xf bank_mask:0xf
	v_cvt_pk_bf16_f32 v148, v58, v74
	ds_write_b32 v151, v148 offset:5984
	v_fmac_f32_e32 v59, v116, v58
	v_fmac_f32_e32 v75, v118, v74
	v_fmac_f32_dpp v59, v58, v122 quad_perm:[1,0,3,2] row_mask:0xf bank_mask:0xf
	v_fmac_f32_dpp v75, v74, v123 quad_perm:[1,0,3,2] row_mask:0xf bank_mask:0xf
	v_cvt_pk_bf16_f32 v149, v59, v75
	ds_write_b32 v151, v149 offset:6256
	v_fmac_f32_e32 v28, v116, v59
	v_fmac_f32_e32 v44, v118, v75
	v_fmac_f32_dpp v28, v59, v122 quad_perm:[1,0,3,2] row_mask:0xf bank_mask:0xf
	v_fmac_f32_dpp v44, v75, v123 quad_perm:[1,0,3,2] row_mask:0xf bank_mask:0xf
	v_cvt_pk_bf16_f32 v148, v28, v44
	ds_write_b32 v151, v148 offset:6528
	v_fmac_f32_e32 v29, v116, v28
	v_fmac_f32_e32 v45, v118, v44
	v_fmac_f32_dpp v29, v28, v122 quad_perm:[1,0,3,2] row_mask:0xf bank_mask:0xf
	v_fmac_f32_dpp v45, v44, v123 quad_perm:[1,0,3,2] row_mask:0xf bank_mask:0xf
	v_cvt_pk_bf16_f32 v149, v29, v45
	ds_write_b32 v151, v149 offset:6800
	v_fmac_f32_e32 v30, v116, v29
	v_fmac_f32_e32 v46, v118, v45
	v_fmac_f32_dpp v30, v29, v122 quad_perm:[1,0,3,2] row_mask:0xf bank_mask:0xf
	v_fmac_f32_dpp v46, v45, v123 quad_perm:[1,0,3,2] row_mask:0xf bank_mask:0xf
	v_cvt_pk_bf16_f32 v148, v30, v46
	ds_write_b32 v151, v148 offset:7072
	v_fmac_f32_e32 v31, v116, v30
	v_fmac_f32_e32 v47, v118, v46
	v_fmac_f32_dpp v31, v30, v122 quad_perm:[1,0,3,2] row_mask:0xf bank_mask:0xf
	v_fmac_f32_dpp v47, v46, v123 quad_perm:[1,0,3,2] row_mask:0xf bank_mask:0xf
	v_cvt_pk_bf16_f32 v149, v31, v47
	ds_write_b32 v151, v149 offset:7344
	v_fmac_f32_e32 v60, v116, v31
	v_fmac_f32_e32 v76, v118, v47
	v_fmac_f32_dpp v60, v31, v122 quad_perm:[1,0,3,2] row_mask:0xf bank_mask:0xf
	v_fmac_f32_dpp v76, v47, v123 quad_perm:[1,0,3,2] row_mask:0xf bank_mask:0xf
	v_cvt_pk_bf16_f32 v148, v60, v76
	ds_write_b32 v151, v148 offset:7616
	v_fmac_f32_e32 v61, v116, v60
	v_fmac_f32_e32 v77, v118, v76
	v_fmac_f32_dpp v61, v60, v122 quad_perm:[1,0,3,2] row_mask:0xf bank_mask:0xf
	v_fmac_f32_dpp v77, v76, v123 quad_perm:[1,0,3,2] row_mask:0xf bank_mask:0xf
	v_cvt_pk_bf16_f32 v149, v61, v77
	ds_write_b32 v151, v149 offset:7888
	v_fmac_f32_e32 v62, v116, v61
	v_fmac_f32_e32 v78, v118, v77
	v_fmac_f32_dpp v62, v61, v122 quad_perm:[1,0,3,2] row_mask:0xf bank_mask:0xf
	v_fmac_f32_dpp v78, v77, v123 quad_perm:[1,0,3,2] row_mask:0xf bank_mask:0xf
	v_cvt_pk_bf16_f32 v148, v62, v78
	ds_write_b32 v151, v148 offset:8160
	v_fmac_f32_e32 v63, v116, v62
	v_fmac_f32_e32 v79, v118, v78
	v_fmac_f32_dpp v63, v62, v122 quad_perm:[1,0,3,2] row_mask:0xf bank_mask:0xf
	v_fmac_f32_dpp v79, v78, v123 quad_perm:[1,0,3,2] row_mask:0xf bank_mask:0xf
	v_cvt_pk_bf16_f32 v149, v63, v79
	ds_write_b32 v151, v149 offset:8432
	v_mov_b32_e32 v120, v63
	v_mov_b32_e32 v121, v79
	ds_read_b128 v[124:127], v152
	ds_read_b128 v[128:131], v152 offset:64
	ds_read_b128 v[132:135], v152 offset:128
	ds_read_b128 v[136:139], v152 offset:192
	s_waitcnt lgkmcnt(3)
	v_mfma_f32_16x16x32_bf16 v[140:143], v[100:103], v[124:127], 0
	s_waitcnt lgkmcnt(2)
	v_mfma_f32_16x16x32_bf16 v[140:143], v[104:107], v[128:131], v[140:143]
	s_waitcnt lgkmcnt(1)
	v_mfma_f32_16x16x32_bf16 v[140:143], v[108:111], v[132:135], v[140:143]
	s_waitcnt lgkmcnt(0)
	v_mfma_f32_16x16x32_bf16 v[140:143], v[112:115], v[136:139], v[140:143]
	s_nop 9
	s_waitcnt vmcnt(9)
	v_add_f32_e32 v182, v172, v140
	v_add_f32_e32 v183, v173, v141
	v_add_f32_e32 v184, v174, v142
	v_add_f32_e32 v185, v175, v143
	v_lshlrev_b32_e32 v186, 16, v2
	v_and_b32_e32 v187, 0xffff0000, v2
	v_lshlrev_b32_e32 v188, 16, v3
	v_and_b32_e32 v189, 0xffff0000, v3
	v_fmac_f32_e32 v182, v164, v186
	v_fmac_f32_e32 v183, v165, v187
	v_fmac_f32_e32 v184, v166, v188
	v_fmac_f32_e32 v185, v167, v189
	v_mul_f32_e32 v186, 0x3d372713, v182
	v_mul_f32_e32 v187, 0x3d372713, v183
	v_mul_f32_e32 v188, 0x3d372713, v184
	v_mul_f32_e32 v189, 0x3d372713, v185
	v_mul_f32_e32 v186, v182, v186
	v_mul_f32_e32 v187, v183, v187
	v_mul_f32_e32 v188, v184, v188
	v_mul_f32_e32 v189, v185, v189
	v_fma_f32 v186, v182, v186, v182
	v_fma_f32 v187, v183, v187, v183
	v_fma_f32 v188, v184, v188, v184
	v_fma_f32 v189, v185, v189, v185
	v_mul_f32_e32 v186, 0xbfcc422a, v186
	v_mul_f32_e32 v187, 0xbfcc422a, v187
	v_mul_f32_e32 v188, 0xbfcc422a, v188
	v_mul_f32_e32 v189, 0xbfcc422a, v189
	v_mul_f32_e32 v186, 0x3fb8aa3b, v186
	v_mul_f32_e32 v187, 0x3fb8aa3b, v187
	v_mul_f32_e32 v188, 0x3fb8aa3b, v188
	v_mul_f32_e32 v189, 0x3fb8aa3b, v189
	v_exp_f32_e32 v186, v186
	v_exp_f32_e32 v187, v187
	v_exp_f32_e32 v188, v188
	v_exp_f32_e32 v189, v189
	v_add_f32_e32 v186, 1.0, v186
	v_add_f32_e32 v187, 1.0, v187
	v_add_f32_e32 v188, 1.0, v188
	v_add_f32_e32 v189, 1.0, v189
	v_rcp_f32_e32 v186, v186
	v_rcp_f32_e32 v187, v187
	v_rcp_f32_e32 v188, v188
	v_rcp_f32_e32 v189, v189
	v_mul_f32_e32 v182, v182, v186
	v_mul_f32_e32 v183, v183, v187
	v_mul_f32_e32 v184, v184, v188
	v_mul_f32_e32 v185, v185, v189
	v_cvt_pk_bf16_f32 v148, v182, v183
	v_cvt_pk_bf16_f32 v149, v184, v185
	global_store_dwordx2 v156, v[148:149], s[12:13]
	ds_read_b128 v[124:127], v152 offset:4352
	ds_read_b128 v[128:131], v152 offset:4416
	ds_read_b128 v[132:135], v152 offset:4480
	ds_read_b128 v[136:139], v152 offset:4544
	s_waitcnt lgkmcnt(3)
	v_mfma_f32_16x16x32_bf16 v[140:143], v[100:103], v[124:127], 0
	s_waitcnt lgkmcnt(2)
	v_mfma_f32_16x16x32_bf16 v[140:143], v[104:107], v[128:131], v[140:143]
	s_waitcnt lgkmcnt(1)
	v_mfma_f32_16x16x32_bf16 v[140:143], v[108:111], v[132:135], v[140:143]
	s_waitcnt lgkmcnt(0)
	v_mfma_f32_16x16x32_bf16 v[140:143], v[112:115], v[136:139], v[140:143]
	s_nop 9
	s_waitcnt vmcnt(9)
	v_add_f32_e32 v182, v176, v140
	v_add_f32_e32 v183, v177, v141
	v_add_f32_e32 v184, v178, v142
	v_add_f32_e32 v185, v179, v143
	v_lshlrev_b32_e32 v186, 16, v4
	v_and_b32_e32 v187, 0xffff0000, v4
	v_lshlrev_b32_e32 v188, 16, v5
	v_and_b32_e32 v189, 0xffff0000, v5
	v_fmac_f32_e32 v182, v164, v186
	v_fmac_f32_e32 v183, v165, v187
	v_fmac_f32_e32 v184, v166, v188
	v_fmac_f32_e32 v185, v167, v189
	v_mul_f32_e32 v186, 0x3d372713, v182
	v_mul_f32_e32 v187, 0x3d372713, v183
	v_mul_f32_e32 v188, 0x3d372713, v184
	v_mul_f32_e32 v189, 0x3d372713, v185
	v_mul_f32_e32 v186, v182, v186
	v_mul_f32_e32 v187, v183, v187
	v_mul_f32_e32 v188, v184, v188
	v_mul_f32_e32 v189, v185, v189
	v_fma_f32 v186, v182, v186, v182
	v_fma_f32 v187, v183, v187, v183
	v_fma_f32 v188, v184, v188, v184
	v_fma_f32 v189, v185, v189, v185
	v_mul_f32_e32 v186, 0xbfcc422a, v186
	v_mul_f32_e32 v187, 0xbfcc422a, v187
	v_mul_f32_e32 v188, 0xbfcc422a, v188
	v_mul_f32_e32 v189, 0xbfcc422a, v189
	v_mul_f32_e32 v186, 0x3fb8aa3b, v186
	v_mul_f32_e32 v187, 0x3fb8aa3b, v187
	v_mul_f32_e32 v188, 0x3fb8aa3b, v188
	v_mul_f32_e32 v189, 0x3fb8aa3b, v189
	v_exp_f32_e32 v186, v186
	v_exp_f32_e32 v187, v187
	v_exp_f32_e32 v188, v188
	v_exp_f32_e32 v189, v189
	v_add_f32_e32 v186, 1.0, v186
	v_add_f32_e32 v187, 1.0, v187
	v_add_f32_e32 v188, 1.0, v188
	v_add_f32_e32 v189, 1.0, v189
	v_rcp_f32_e32 v186, v186
	v_rcp_f32_e32 v187, v187
	v_rcp_f32_e32 v188, v188
	v_rcp_f32_e32 v189, v189
	v_mul_f32_e32 v182, v182, v186
	v_mul_f32_e32 v183, v183, v187
	v_mul_f32_e32 v184, v184, v188
	v_mul_f32_e32 v185, v185, v189
	v_cvt_pk_bf16_f32 v148, v182, v183
	v_cvt_pk_bf16_f32 v149, v184, v185
	global_store_dwordx2 v159, v[148:149], s[12:13]
	s_add_u32 s12, s12, 65536
	s_addc_u32 s13, s13, 0
	s_add_u32 s14, s14, 2
	s_cmp_lt_u32 s14, 32
	s_cbranch_scc1 .Lssm_tileB_d0m0
	s_waitcnt vmcnt(0) lgkmcnt(0)
	s_branch .Lssm_lat_join
.Lssm_lat_bwd:
	s_add_u32 s28, s24, 64
	s_lshl_b32 s29, s28, 13
	s_add_u32 s29, s29, 0x200000
	s_add_u32 s10, s62, s29
	s_addc_u32 s11, s63, 0
	global_load_dwordx4 v[84:87], v177, s[10:11]
	global_load_dwordx4 v[88:91], v177, s[10:11] offset:2048
	s_add_u32 s12, s10, 0x1000
	s_addc_u32 s13, s11, 0
	global_load_dwordx4 v[92:95], v177, s[12:13]
	global_load_dwordx4 v[96:99], v177, s[12:13] offset:2048
	s_lshl_b32 s29, s28, 12
	s_add_u32 s29, s29, 0x300000
	s_add_u32 s16, s62, s29
	s_addc_u32 s17, s63, 0
	global_load_dwordx2 v[2:3], v178, s[16:17]
	global_load_dwordx2 v[4:5], v178, s[16:17] offset:1024
	global_load_dwordx2 v[6:7], v178, s[16:17] offset:512
	global_load_dwordx2 v[8:9], v178, s[16:17] offset:1536
	global_load_dwordx2 v[10:11], v178, s[16:17] offset:2048
	global_load_dwordx2 v[12:13], v178, s[16:17] offset:3072
	global_load_dwordx2 v[14:15], v178, s[16:17] offset:2560
	global_load_dwordx2 v[16:17], v178, s[16:17] offset:3584
	s_lshl_b32 s29, s28, 9
	s_add_u32 s29, s29, 0x100000
	s_add_u32 s18, s62, s29
	s_addc_u32 s19, s63, 0
	global_load_dwordx2 v[116:117], v179, s[18:19]
	global_load_dwordx2 v[118:119], v179, s[18:19] offset:128
	s_lshl_b32 s30, s23, 1
	s_add_u32 s30, s30, 1
	s_lshl_b32 s30, s30, 15
	s_lshl_b32 s31, s24, 8
	s_add_u32 s30, s30, s31
	v_readlane_b32 s34, v254, 10
	v_readlane_b32 s35, v254, 11
	s_nop 3
	s_add_u32 s34, s34, s30
	s_addc_u32 s35, s35, 0
	global_load_dword v120, v180, s[34:35]
	global_load_dword v121, v180, s[34:35] offset:64
	v_readlane_b32 s34, v254, 28
	v_readlane_b32 s35, v254, 29
	s_nop 3
	s_lshl_b32 s31, s24, 6
	s_add_u32 s34, s34, s31
	s_addc_u32 s35, s35, 0
	global_load_dwordx4 v[164:167], v181, s[34:35]
	s_mul_i32 s31, s25, 0x1800
	s_lshl_b32 s29, s24, 5
	s_add_u32 s31, s31, s29
	s_add_u32 s31, s31, 0x8801000
	s_add_u32 s4, s62, s31
	s_addc_u32 s5, s63, 0
	s_lshl_b32 s31, s25, 12
	s_lshl_b32 s29, s24, 6
	s_add_u32 s31, s31, s29
	s_add_u32 s31, s31, 0x4000000
	s_add_u32 s6, s60, s31
	s_addc_u32 s7, s61, 0
	s_add_u32 s34, s4, 6094848
	s_addc_u32 s35, s5, 0
	global_load_dwordx4 v[80:83], v150, s[34:35]
	s_mov_b64 s[10:11], s[34:35]
	s_sub_u32 s10, s10, 196608
	s_subb_u32 s11, s11, 0
	global_load_dwordx4 v[144:147], v150, s[10:11]
	s_mov_b64 s[34:35], s[10:11]
	s_sub_u32 s10, s10, 196608
	s_subb_u32 s11, s11, 0
	s_add_u32 s12, s6, 4063232
	s_addc_u32 s13, s7, 0
	s_mov_b32 s14, 0
	s_mov_b32 s40, 0xffff0000
	s_waitcnt vmcnt(0)
	v_and_b32_e32 v182, 0xffff, v2
	v_lshrrev_b32_e32 v183, 16, v2
	v_and_b32_e32 v184, 0xffff, v3
	v_lshrrev_b32_e32 v185, 16, v3
	v_lshl_or_b32 v100, v4, 16, v182
	v_and_or_b32 v101, v4, s40, v183
	v_lshl_or_b32 v102, v5, 16, v184
	v_and_or_b32 v103, v5, s40, v185
	v_and_b32_e32 v182, 0xffff, v6
	v_lshrrev_b32_e32 v183, 16, v6
	v_and_b32_e32 v184, 0xffff, v7
	v_lshrrev_b32_e32 v185, 16, v7
	v_lshl_or_b32 v104, v8, 16, v182
	v_and_or_b32 v105, v8, s40, v183
	v_lshl_or_b32 v106, v9, 16, v184
	v_and_or_b32 v107, v9, s40, v185
	v_and_b32_e32 v182, 0xffff, v10
	v_lshrrev_b32_e32 v183, 16, v10
	v_and_b32_e32 v184, 0xffff, v11
	v_lshrrev_b32_e32 v185, 16, v11
	v_lshl_or_b32 v108, v12, 16, v182
	v_and_or_b32 v109, v12, s40, v183
	v_lshl_or_b32 v110, v13, 16, v184
	v_and_or_b32 v111, v13, s40, v185
	v_and_b32_e32 v182, 0xffff, v14
	v_lshrrev_b32_e32 v183, 16, v14
	v_and_b32_e32 v184, 0xffff, v15
	v_lshrrev_b32_e32 v185, 16, v15
	v_lshl_or_b32 v112, v16, 16, v182
	v_and_or_b32 v113, v16, s40, v183
	v_lshl_or_b32 v114, v17, 16, v184
	v_and_or_b32 v115, v17, s40, v185
	v_cmp_eq_u32_e32 vcc, 1, v174
	v_xor_b32_e32 v182, 0x80000000, v117
	v_xor_b32_e32 v183, 0x80000000, v119
	s_nop 1
	v_cndmask_b32_e32 v122, v182, v117, vcc
	v_cndmask_b32_e32 v123, v183, v119, vcc
.Lssm_tileA_d1m0:
	s_waitcnt vmcnt(5)
	v_mfma_f32_32x32x16_bf16 v[16:31], v[80:83], v[84:87], 0
	v_mfma_f32_32x32x16_bf16 v[32:47], v[80:83], v[88:91], 0
	v_mfma_f32_32x32x16_bf16 v[48:63], v[80:83], v[92:95], 0
	v_mfma_f32_32x32x16_bf16 v[64:79], v[80:83], v[96:99], 0
	s_nop 11
	global_load_dwordx4 v[80:83], v150, s[10:11]
	s_sub_u32 s34, s34, 196608
	s_subb_u32 s35, s35, 0
	s_sub_u32 s10, s10, 196608
	s_subb_u32 s11, s11, 0
	v_permlane32_swap_b32_e32 v16, v48
	v_permlane32_swap_b32_e32 v17, v49
	v_permlane32_swap_b32_e32 v18, v50
	v_permlane32_swap_b32_e32 v19, v51
	v_permlane32_swap_b32_e32 v20, v52
	v_permlane32_swap_b32_e32 v21, v53
	v_permlane32_swap_b32_e32 v22, v54
	v_permlane32_swap_b32_e32 v23, v55
	v_permlane32_swap_b32_e32 v24, v56
	v_permlane32_swap_b32_e32 v25, v57
	v_permlane32_swap_b32_e32 v26, v58
	v_permlane32_swap_b32_e32 v27, v59
	v_permlane32_swap_b32_e32 v28, v60
	v_permlane32_swap_b32_e32 v29, v61
	v_permlane32_swap_b32_e32 v30, v62
	v_permlane32_swap_b32_e32 v31, v63
	v_permlane32_swap_b32_e32 v32, v64
	v_permlane32_swap_b32_e32 v33, v65
	v_permlane32_swap_b32_e32 v34, v66
	v_permlane32_swap_b32_e32 v35, v67
	v_permlane32_swap_b32_e32 v36, v68
	v_permlane32_swap_b32_e32 v37, v69
	v_permlane32_swap_b32_e32 v38, v70
	v_permlane32_swap_b32_e32 v39, v71
	v_permlane32_swap_b32_e32 v40, v72
	v_permlane32_swap_b32_e32 v41, v73
	v_permlane32_swap_b32_e32 v42, v74
	v_permlane32_swap_b32_e32 v43, v75
	v_permlane32_swap_b32_e32 v44, v76
	v_permlane32_swap_b32_e32 v45, v77
	v_permlane32_swap_b32_e32 v46, v78
	v_permlane32_swap_b32_e32 v47, v79
	v_fmac_f32_e32 v63, v116, v120
	v_fmac_f32_e32 v79, v118, v121
	v_fmac_f32_dpp v63, v120, v122 quad_perm:[1,0,3,2] row_mask:0xf bank_mask:0xf
	v_fmac_f32_dpp v79, v121, v123 quad_perm:[1,0,3,2] row_mask:0xf bank_mask:0xf
	v_cvt_pk_bf16_f32 v148, v63, v79
	ds_write_b32 v151, v148 offset:8432
	v_fmac_f32_e32 v62, v116, v63
	v_fmac_f32_e32 v78, v118, v79
	v_fmac_f32_dpp v62, v63, v122 quad_perm:[1,0,3,2] row_mask:0xf bank_mask:0xf
	v_fmac_f32_dpp v78, v79, v123 quad_perm:[1,0,3,2] row_mask:0xf bank_mask:0xf
	v_cvt_pk_bf16_f32 v149, v62, v78
	ds_write_b32 v151, v149 offset:8160
	v_fmac_f32_e32 v61, v116, v62
	v_fmac_f32_e32 v77, v118, v78
	v_fmac_f32_dpp v61, v62, v122 quad_perm:[1,0,3,2] row_mask:0xf bank_mask:0xf
	v_fmac_f32_dpp v77, v78, v123 quad_perm:[1,0,3,2] row_mask:0xf bank_mask:0xf
	v_cvt_pk_bf16_f32 v148, v61, v77
	ds_write_b32 v151, v148 offset:7888
	v_fmac_f32_e32 v60, v116, v61
	v_fmac_f32_e32 v76, v118, v77
	v_fmac_f32_dpp v60, v61, v122 quad_perm:[1,0,3,2] row_mask:0xf bank_mask:0xf
	v_fmac_f32_dpp v76, v77, v123 quad_perm:[1,0,3,2] row_mask:0xf bank_mask:0xf
	v_cvt_pk_bf16_f32 v149, v60, v76
	ds_write_b32 v151, v149 offset:7616
	v_fmac_f32_e32 v31, v116, v60
	v_fmac_f32_e32 v47, v118, v76
	v_fmac_f32_dpp v31, v60, v122 quad_perm:[1,0,3,2] row_mask:0xf bank_mask:0xf
	v_fmac_f32_dpp v47, v76, v123 quad_perm:[1,0,3,2] row_mask:0xf bank_mask:0xf
	v_cvt_pk_bf16_f32 v148, v31, v47
	ds_write_b32 v151, v148 offset:7344
	v_fmac_f32_e32 v30, v116, v31
	v_fmac_f32_e32 v46, v118, v47
	v_fmac_f32_dpp v30, v31, v122 quad_perm:[1,0,3,2] row_mask:0xf bank_mask:0xf
	v_fmac_f32_dpp v46, v47, v123 quad_perm:[1,0,3,2] row_mask:0xf bank_mask:0xf
	v_cvt_pk_bf16_f32 v149, v30, v46
	ds_write_b32 v151, v149 offset:7072
	v_fmac_f32_e32 v29, v116, v30
	v_fmac_f32_e32 v45, v118, v46
	v_fmac_f32_dpp v29, v30, v122 quad_perm:[1,0,3,2] row_mask:0xf bank_mask:0xf
	v_fmac_f32_dpp v45, v46, v123 quad_perm:[1,0,3,2] row_mask:0xf bank_mask:0xf
	v_cvt_pk_bf16_f32 v148, v29, v45
	ds_write_b32 v151, v148 offset:6800
	v_fmac_f32_e32 v28, v116, v29
	v_fmac_f32_e32 v44, v118, v45
	v_fmac_f32_dpp v28, v29, v122 quad_perm:[1,0,3,2] row_mask:0xf bank_mask:0xf
	v_fmac_f32_dpp v44, v45, v123 quad_perm:[1,0,3,2] row_mask:0xf bank_mask:0xf
	v_cvt_pk_bf16_f32 v149, v28, v44
	ds_write_b32 v151, v149 offset:6528
	v_fmac_f32_e32 v59, v116, v28
	v_fmac_f32_e32 v75, v118, v44
	v_fmac_f32_dpp v59, v28, v122 quad_perm:[1,0,3,2] row_mask:0xf bank_mask:0xf
	v_fmac_f32_dpp v75, v44, v123 quad_perm:[1,0,3,2] row_mask:0xf bank_mask:0xf
	v_cvt_pk_bf16_f32 v148, v59, v75
	ds_write_b32 v151, v148 offset:6256
	v_fmac_f32_e32 v58, v116, v59
	v_fmac_f32_e32 v74, v118, v75
	v_fmac_f32_dpp v58, v59, v122 quad_perm:[1,0,3,2] row_mask:0xf bank_mask:0xf
	v_fmac_f32_dpp v74, v75, v123 quad_perm:[1,0,3,2] row_mask:0xf bank_mask:0xf
	v_cvt_pk_bf16_f32 v149, v58, v74
	ds_write_b32 v151, v149 offset:5984
	v_fmac_f32_e32 v57, v116, v58
	v_fmac_f32_e32 v73, v118, v74
	v_fmac_f32_dpp v57, v58, v122 quad_perm:[1,0,3,2] row_mask:0xf bank_mask:0xf
	v_fmac_f32_dpp v73, v74, v123 quad_perm:[1,0,3,2] row_mask:0xf bank_mask:0xf
	v_cvt_pk_bf16_f32 v148, v57, v73
	ds_write_b32 v151, v148 offset:5712
	v_fmac_f32_e32 v56, v116, v57
	v_fmac_f32_e32 v72, v118, v73
	v_fmac_f32_dpp v56, v57, v122 quad_perm:[1,0,3,2] row_mask:0xf bank_mask:0xf
	v_fmac_f32_dpp v72, v73, v123 quad_perm:[1,0,3,2] row_mask:0xf bank_mask:0xf
	v_cvt_pk_bf16_f32 v149, v56, v72
	ds_write_b32 v151, v149 offset:5440
	v_fmac_f32_e32 v27, v116, v56
	v_fmac_f32_e32 v43, v118, v72
	v_fmac_f32_dpp v27, v56, v122 quad_perm:[1,0,3,2] row_mask:0xf bank_mask:0xf
	v_fmac_f32_dpp v43, v72, v123 quad_perm:[1,0,3,2] row_mask:0xf bank_mask:0xf
	v_cvt_pk_bf16_f32 v148, v27, v43
	ds_write_b32 v151, v148 offset:5168
	v_fmac_f32_e32 v26, v116, v27
	v_fmac_f32_e32 v42, v118, v43
	v_fmac_f32_dpp v26, v27, v122 quad_perm:[1,0,3,2] row_mask:0xf bank_mask:0xf
	v_fmac_f32_dpp v42, v43, v123 quad_perm:[1,0,3,2] row_mask:0xf bank_mask:0xf
	v_cvt_pk_bf16_f32 v149, v26, v42
	ds_write_b32 v151, v149 offset:4896
	v_fmac_f32_e32 v25, v116, v26
	v_fmac_f32_e32 v41, v118, v42
	v_fmac_f32_dpp v25, v26, v122 quad_perm:[1,0,3,2] row_mask:0xf bank_mask:0xf
	v_fmac_f32_dpp v41, v42, v123 quad_perm:[1,0,3,2] row_mask:0xf bank_mask:0xf
	v_cvt_pk_bf16_f32 v148, v25, v41
	ds_write_b32 v151, v148 offset:4624
	v_fmac_f32_e32 v24, v116, v25
	v_fmac_f32_e32 v40, v118, v41
	v_fmac_f32_dpp v24, v25, v122 quad_perm:[1,0,3,2] row_mask:0xf bank_mask:0xf
	v_fmac_f32_dpp v40, v41, v123 quad_perm:[1,0,3,2] row_mask:0xf bank_mask:0xf
	v_cvt_pk_bf16_f32 v149, v24, v40
	ds_write_b32 v151, v149 offset:4352
	v_fmac_f32_e32 v55, v116, v24
	v_fmac_f32_e32 v71, v118, v40
	v_fmac_f32_dpp v55, v24, v122 quad_perm:[1,0,3,2] row_mask:0xf bank_mask:0xf
	v_fmac_f32_dpp v71, v40, v123 quad_perm:[1,0,3,2] row_mask:0xf bank_mask:0xf
	v_cvt_pk_bf16_f32 v148, v55, v71
	ds_write_b32 v151, v148 offset:4080
	v_fmac_f32_e32 v54, v116, v55
	v_fmac_f32_e32 v70, v118, v71
	v_fmac_f32_dpp v54, v55, v122 quad_perm:[1,0,3,2] row_mask:0xf bank_mask:0xf
	v_fmac_f32_dpp v70, v71, v123 quad_perm:[1,0,3,2] row_mask:0xf bank_mask:0xf
	v_cvt_pk_bf16_f32 v149, v54, v70
	ds_write_b32 v151, v149 offset:3808
	v_fmac_f32_e32 v53, v116, v54
	v_fmac_f32_e32 v69, v118, v70
	v_fmac_f32_dpp v53, v54, v122 quad_perm:[1,0,3,2] row_mask:0xf bank_mask:0xf
	v_fmac_f32_dpp v69, v70, v123 quad_perm:[1,0,3,2] row_mask:0xf bank_mask:0xf
	v_cvt_pk_bf16_f32 v148, v53, v69
	ds_write_b32 v151, v148 offset:3536
	v_fmac_f32_e32 v52, v116, v53
	v_fmac_f32_e32 v68, v118, v69
	v_fmac_f32_dpp v52, v53, v122 quad_perm:[1,0,3,2] row_mask:0xf bank_mask:0xf
	v_fmac_f32_dpp v68, v69, v123 quad_perm:[1,0,3,2] row_mask:0xf bank_mask:0xf
	v_cvt_pk_bf16_f32 v149, v52, v68
	ds_write_b32 v151, v149 offset:3264
	v_fmac_f32_e32 v23, v116, v52
	v_fmac_f32_e32 v39, v118, v68
	v_fmac_f32_dpp v23, v52, v122 quad_perm:[1,0,3,2] row_mask:0xf bank_mask:0xf
	v_fmac_f32_dpp v39, v68, v123 quad_perm:[1,0,3,2] row_mask:0xf bank_mask:0xf
	v_cvt_pk_bf16_f32 v148, v23, v39
	ds_write_b32 v151, v148 offset:2992
	v_fmac_f32_e32 v22, v116, v23
	v_fmac_f32_e32 v38, v118, v39
	v_fmac_f32_dpp v22, v23, v122 quad_perm:[1,0,3,2] row_mask:0xf bank_mask:0xf
	v_fmac_f32_dpp v38, v39, v123 quad_perm:[1,0,3,2] row_mask:0xf bank_mask:0xf
	v_cvt_pk_bf16_f32 v149, v22, v38
	ds_write_b32 v151, v149 offset:2720
	v_fmac_f32_e32 v21, v116, v22
	v_fmac_f32_e32 v37, v118, v38
	v_fmac_f32_dpp v21, v22, v122 quad_perm:[1,0,3,2] row_mask:0xf bank_mask:0xf
	v_fmac_f32_dpp v37, v38, v123 quad_perm:[1,0,3,2] row_mask:0xf bank_mask:0xf
	v_cvt_pk_bf16_f32 v148, v21, v37
	ds_write_b32 v151, v148 offset:2448
	v_fmac_f32_e32 v20, v116, v21
	v_fmac_f32_e32 v36, v118, v37
	v_fmac_f32_dpp v20, v21, v122 quad_perm:[1,0,3,2] row_mask:0xf bank_mask:0xf
	v_fmac_f32_dpp v36, v37, v123 quad_perm:[1,0,3,2] row_mask:0xf bank_mask:0xf
	v_cvt_pk_bf16_f32 v149, v20, v36
	ds_write_b32 v151, v149 offset:2176
	v_fmac_f32_e32 v51, v116, v20
	v_fmac_f32_e32 v67, v118, v36
	v_fmac_f32_dpp v51, v20, v122 quad_perm:[1,0,3,2] row_mask:0xf bank_mask:0xf
	v_fmac_f32_dpp v67, v36, v123 quad_perm:[1,0,3,2] row_mask:0xf bank_mask:0xf
	v_cvt_pk_bf16_f32 v148, v51, v67
	ds_write_b32 v151, v148 offset:1904
	v_fmac_f32_e32 v50, v116, v51
	v_fmac_f32_e32 v66, v118, v67
	v_fmac_f32_dpp v50, v51, v122 quad_perm:[1,0,3,2] row_mask:0xf bank_mask:0xf
	v_fmac_f32_dpp v66, v67, v123 quad_perm:[1,0,3,2] row_mask:0xf bank_mask:0xf
	v_cvt_pk_bf16_f32 v149, v50, v66
	ds_write_b32 v151, v149 offset:1632
	v_fmac_f32_e32 v49, v116, v50
	v_fmac_f32_e32 v65, v118, v66
	v_fmac_f32_dpp v49, v50, v122 quad_perm:[1,0,3,2] row_mask:0xf bank_mask:0xf
	v_fmac_f32_dpp v65, v66, v123 quad_perm:[1,0,3,2] row_mask:0xf bank_mask:0xf
	v_cvt_pk_bf16_f32 v148, v49, v65
	ds_write_b32 v151, v148 offset:1360
	v_fmac_f32_e32 v48, v116, v49
	v_fmac_f32_e32 v64, v118, v65
	v_fmac_f32_dpp v48, v49, v122 quad_perm:[1,0,3,2] row_mask:0xf bank_mask:0xf
	v_fmac_f32_dpp v64, v65, v123 quad_perm:[1,0,3,2] row_mask:0xf bank_mask:0xf
	v_cvt_pk_bf16_f32 v149, v48, v64
	ds_write_b32 v151, v149 offset:1088
	v_fmac_f32_e32 v19, v116, v48
	v_fmac_f32_e32 v35, v118, v64
	v_fmac_f32_dpp v19, v48, v122 quad_perm:[1,0,3,2] row_mask:0xf bank_mask:0xf
	v_fmac_f32_dpp v35, v64, v123 quad_perm:[1,0,3,2] row_mask:0xf bank_mask:0xf
	v_cvt_pk_bf16_f32 v148, v19, v35
	ds_write_b32 v151, v148 offset:816
	v_fmac_f32_e32 v18, v116, v19
	v_fmac_f32_e32 v34, v118, v35
	v_fmac_f32_dpp v18, v19, v122 quad_perm:[1,0,3,2] row_mask:0xf bank_mask:0xf
	v_fmac_f32_dpp v34, v35, v123 quad_perm:[1,0,3,2] row_mask:0xf bank_mask:0xf
	v_cvt_pk_bf16_f32 v149, v18, v34
	ds_write_b32 v151, v149 offset:544
	v_fmac_f32_e32 v17, v116, v18
	v_fmac_f32_e32 v33, v118, v34
	v_fmac_f32_dpp v17, v18, v122 quad_perm:[1,0,3,2] row_mask:0xf bank_mask:0xf
	v_fmac_f32_dpp v33, v34, v123 quad_perm:[1,0,3,2] row_mask:0xf bank_mask:0xf
	v_cvt_pk_bf16_f32 v148, v17, v33
	ds_write_b32 v151, v148 offset:272
	v_fmac_f32_e32 v16, v116, v17
	v_fmac_f32_e32 v32, v118, v33
	v_fmac_f32_dpp v16, v17, v122 quad_perm:[1,0,3,2] row_mask:0xf bank_mask:0xf
	v_fmac_f32_dpp v32, v33, v123 quad_perm:[1,0,3,2] row_mask:0xf bank_mask:0xf
	v_cvt_pk_bf16_f32 v149, v16, v32
	ds_write_b32 v151, v149
	v_mov_b32_e32 v120, v16
	v_mov_b32_e32 v121, v32
	ds_read_b128 v[124:127], v152
	ds_read_b128 v[128:131], v152 offset:64
	ds_read_b128 v[132:135], v152 offset:128
	ds_read_b128 v[136:139], v152 offset:192
	s_waitcnt lgkmcnt(3)
	v_mfma_f32_16x16x32_bf16 v[140:143], v[100:103], v[124:127], 0
	s_waitcnt lgkmcnt(2)
	v_mfma_f32_16x16x32_bf16 v[140:143], v[104:107], v[128:131], v[140:143]
	s_waitcnt lgkmcnt(1)
	v_mfma_f32_16x16x32_bf16 v[140:143], v[108:111], v[132:135], v[140:143]
	s_waitcnt lgkmcnt(0)
	v_mfma_f32_16x16x32_bf16 v[140:143], v[112:115], v[136:139], v[140:143]
	s_nop 9
	global_store_dwordx4 v153, v[140:143], s[12:13]
	s_nop 1
	ds_read_b128 v[124:127], v152 offset:4352
	ds_read_b128 v[128:131], v152 offset:4416
	ds_read_b128 v[132:135], v152 offset:4480
	ds_read_b128 v[136:139], v152 offset:4544
	s_waitcnt lgkmcnt(3)
	v_mfma_f32_16x16x32_bf16 v[140:143], v[100:103], v[124:127], 0
	s_waitcnt lgkmcnt(2)
	v_mfma_f32_16x16x32_bf16 v[140:143], v[104:107], v[128:131], v[140:143]
	s_waitcnt lgkmcnt(1)
	v_mfma_f32_16x16x32_bf16 v[140:143], v[108:111], v[132:135], v[140:143]
	s_waitcnt lgkmcnt(0)
	v_mfma_f32_16x16x32_bf16 v[140:143], v[112:115], v[136:139], v[140:143]
	s_nop 9
	global_store_dwordx4 v157, v[140:143], s[12:13]
	s_nop 1
	s_sub_u32 s12, s12, 131072
	s_subb_u32 s13, s13, 0
	s_waitcnt vmcnt(5)
	v_mfma_f32_32x32x16_bf16 v[16:31], v[144:147], v[84:87], 0
	v_mfma_f32_32x32x16_bf16 v[32:47], v[144:147], v[88:91], 0
	v_mfma_f32_32x32x16_bf16 v[48:63], v[144:147], v[92:95], 0
	v_mfma_f32_32x32x16_bf16 v[64:79], v[144:147], v[96:99], 0
	s_nop 11
	global_load_dwordx4 v[144:147], v150, s[10:11]
	s_sub_u32 s34, s34, 196608
	s_subb_u32 s35, s35, 0
	s_sub_u32 s10, s10, 196608
	s_subb_u32 s11, s11, 0
	v_permlane32_swap_b32_e32 v16, v48
	v_permlane32_swap_b32_e32 v17, v49
	v_permlane32_swap_b32_e32 v18, v50
	v_permlane32_swap_b32_e32 v19, v51
	v_permlane32_swap_b32_e32 v20, v52
	v_permlane32_swap_b32_e32 v21, v53
	v_permlane32_swap_b32_e32 v22, v54
	v_permlane32_swap_b32_e32 v23, v55
	v_permlane32_swap_b32_e32 v24, v56
	v_permlane32_swap_b32_e32 v25, v57
	v_permlane32_swap_b32_e32 v26, v58
	v_permlane32_swap_b32_e32 v27, v59
	v_permlane32_swap_b32_e32 v28, v60
	v_permlane32_swap_b32_e32 v29, v61
	v_permlane32_swap_b32_e32 v30, v62
	v_permlane32_swap_b32_e32 v31, v63
	v_permlane32_swap_b32_e32 v32, v64
	v_permlane32_swap_b32_e32 v33, v65
	v_permlane32_swap_b32_e32 v34, v66
	v_permlane32_swap_b32_e32 v35, v67
	v_permlane32_swap_b32_e32 v36, v68
	v_permlane32_swap_b32_e32 v37, v69
	v_permlane32_swap_b32_e32 v38, v70
	v_permlane32_swap_b32_e32 v39, v71
	v_permlane32_swap_b32_e32 v40, v72
	v_permlane32_swap_b32_e32 v41, v73
	v_permlane32_swap_b32_e32 v42, v74
	v_permlane32_swap_b32_e32 v43, v75
	v_permlane32_swap_b32_e32 v44, v76
	v_permlane32_swap_b32_e32 v45, v77
	v_permlane32_swap_b32_e32 v46, v78
	v_permlane32_swap_b32_e32 v47, v79
	v_fmac_f32_e32 v63, v116, v120
	v_fmac_f32_e32 v79, v118, v121
	v_fmac_f32_dpp v63, v120, v122 quad_perm:[1,0,3,2] row_mask:0xf bank_mask:0xf
	v_fmac_f32_dpp v79, v121, v123 quad_perm:[1,0,3,2] row_mask:0xf bank_mask:0xf
	v_cvt_pk_bf16_f32 v148, v63, v79
	ds_write_b32 v151, v148 offset:8432
	v_fmac_f32_e32 v62, v116, v63
	v_fmac_f32_e32 v78, v118, v79
	v_fmac_f32_dpp v62, v63, v122 quad_perm:[1,0,3,2] row_mask:0xf bank_mask:0xf
	v_fmac_f32_dpp v78, v79, v123 quad_perm:[1,0,3,2] row_mask:0xf bank_mask:0xf
	v_cvt_pk_bf16_f32 v149, v62, v78
	ds_write_b32 v151, v149 offset:8160
	v_fmac_f32_e32 v61, v116, v62
	v_fmac_f32_e32 v77, v118, v78
	v_fmac_f32_dpp v61, v62, v122 quad_perm:[1,0,3,2] row_mask:0xf bank_mask:0xf
	v_fmac_f32_dpp v77, v78, v123 quad_perm:[1,0,3,2] row_mask:0xf bank_mask:0xf
	v_cvt_pk_bf16_f32 v148, v61, v77
	ds_write_b32 v151, v148 offset:7888
	v_fmac_f32_e32 v60, v116, v61
	v_fmac_f32_e32 v76, v118, v77
	v_fmac_f32_dpp v60, v61, v122 quad_perm:[1,0,3,2] row_mask:0xf bank_mask:0xf
	v_fmac_f32_dpp v76, v77, v123 quad_perm:[1,0,3,2] row_mask:0xf bank_mask:0xf
	v_cvt_pk_bf16_f32 v149, v60, v76
	ds_write_b32 v151, v149 offset:7616
	v_fmac_f32_e32 v31, v116, v60
	v_fmac_f32_e32 v47, v118, v76
	v_fmac_f32_dpp v31, v60, v122 quad_perm:[1,0,3,2] row_mask:0xf bank_mask:0xf
	v_fmac_f32_dpp v47, v76, v123 quad_perm:[1,0,3,2] row_mask:0xf bank_mask:0xf
	v_cvt_pk_bf16_f32 v148, v31, v47
	ds_write_b32 v151, v148 offset:7344
	v_fmac_f32_e32 v30, v116, v31
	v_fmac_f32_e32 v46, v118, v47
	v_fmac_f32_dpp v30, v31, v122 quad_perm:[1,0,3,2] row_mask:0xf bank_mask:0xf
	v_fmac_f32_dpp v46, v47, v123 quad_perm:[1,0,3,2] row_mask:0xf bank_mask:0xf
	v_cvt_pk_bf16_f32 v149, v30, v46
	ds_write_b32 v151, v149 offset:7072
	v_fmac_f32_e32 v29, v116, v30
	v_fmac_f32_e32 v45, v118, v46
	v_fmac_f32_dpp v29, v30, v122 quad_perm:[1,0,3,2] row_mask:0xf bank_mask:0xf
	v_fmac_f32_dpp v45, v46, v123 quad_perm:[1,0,3,2] row_mask:0xf bank_mask:0xf
	v_cvt_pk_bf16_f32 v148, v29, v45
	ds_write_b32 v151, v148 offset:6800
	v_fmac_f32_e32 v28, v116, v29
	v_fmac_f32_e32 v44, v118, v45
	v_fmac_f32_dpp v28, v29, v122 quad_perm:[1,0,3,2] row_mask:0xf bank_mask:0xf
	v_fmac_f32_dpp v44, v45, v123 quad_perm:[1,0,3,2] row_mask:0xf bank_mask:0xf
	v_cvt_pk_bf16_f32 v149, v28, v44
	ds_write_b32 v151, v149 offset:6528
	v_fmac_f32_e32 v59, v116, v28
	v_fmac_f32_e32 v75, v118, v44
	v_fmac_f32_dpp v59, v28, v122 quad_perm:[1,0,3,2] row_mask:0xf bank_mask:0xf
	v_fmac_f32_dpp v75, v44, v123 quad_perm:[1,0,3,2] row_mask:0xf bank_mask:0xf
	v_cvt_pk_bf16_f32 v148, v59, v75
	ds_write_b32 v151, v148 offset:6256
	v_fmac_f32_e32 v58, v116, v59
	v_fmac_f32_e32 v74, v118, v75
	v_fmac_f32_dpp v58, v59, v122 quad_perm:[1,0,3,2] row_mask:0xf bank_mask:0xf
	v_fmac_f32_dpp v74, v75, v123 quad_perm:[1,0,3,2] row_mask:0xf bank_mask:0xf
	v_cvt_pk_bf16_f32 v149, v58, v74
	ds_write_b32 v151, v149 offset:5984
	v_fmac_f32_e32 v57, v116, v58
	v_fmac_f32_e32 v73, v118, v74
	v_fmac_f32_dpp v57, v58, v122 quad_perm:[1,0,3,2] row_mask:0xf bank_mask:0xf
	v_fmac_f32_dpp v73, v74, v123 quad_perm:[1,0,3,2] row_mask:0xf bank_mask:0xf
	v_cvt_pk_bf16_f32 v148, v57, v73
	ds_write_b32 v151, v148 offset:5712
	v_fmac_f32_e32 v56, v116, v57
	v_fmac_f32_e32 v72, v118, v73
	v_fmac_f32_dpp v56, v57, v122 quad_perm:[1,0,3,2] row_mask:0xf bank_mask:0xf
	v_fmac_f32_dpp v72, v73, v123 quad_perm:[1,0,3,2] row_mask:0xf bank_mask:0xf
	v_cvt_pk_bf16_f32 v149, v56, v72
	ds_write_b32 v151, v149 offset:5440
	v_fmac_f32_e32 v27, v116, v56
	v_fmac_f32_e32 v43, v118, v72
	v_fmac_f32_dpp v27, v56, v122 quad_perm:[1,0,3,2] row_mask:0xf bank_mask:0xf
	v_fmac_f32_dpp v43, v72, v123 quad_perm:[1,0,3,2] row_mask:0xf bank_mask:0xf
	v_cvt_pk_bf16_f32 v148, v27, v43
	ds_write_b32 v151, v148 offset:5168
	v_fmac_f32_e32 v26, v116, v27
	v_fmac_f32_e32 v42, v118, v43
	v_fmac_f32_dpp v26, v27, v122 quad_perm:[1,0,3,2] row_mask:0xf bank_mask:0xf
	v_fmac_f32_dpp v42, v43, v123 quad_perm:[1,0,3,2] row_mask:0xf bank_mask:0xf
	v_cvt_pk_bf16_f32 v149, v26, v42
	ds_write_b32 v151, v149 offset:4896
	v_fmac_f32_e32 v25, v116, v26
	v_fmac_f32_e32 v41, v118, v42
	v_fmac_f32_dpp v25, v26, v122 quad_perm:[1,0,3,2] row_mask:0xf bank_mask:0xf
	v_fmac_f32_dpp v41, v42, v123 quad_perm:[1,0,3,2] row_mask:0xf bank_mask:0xf
	v_cvt_pk_bf16_f32 v148, v25, v41
	ds_write_b32 v151, v148 offset:4624
	v_fmac_f32_e32 v24, v116, v25
	v_fmac_f32_e32 v40, v118, v41
	v_fmac_f32_dpp v24, v25, v122 quad_perm:[1,0,3,2] row_mask:0xf bank_mask:0xf
	v_fmac_f32_dpp v40, v41, v123 quad_perm:[1,0,3,2] row_mask:0xf bank_mask:0xf
	v_cvt_pk_bf16_f32 v149, v24, v40
	ds_write_b32 v151, v149 offset:4352
	v_fmac_f32_e32 v55, v116, v24
	v_fmac_f32_e32 v71, v118, v40
	v_fmac_f32_dpp v55, v24, v122 quad_perm:[1,0,3,2] row_mask:0xf bank_mask:0xf
	v_fmac_f32_dpp v71, v40, v123 quad_perm:[1,0,3,2] row_mask:0xf bank_mask:0xf
	v_cvt_pk_bf16_f32 v148, v55, v71
	ds_write_b32 v151, v148 offset:4080
	v_fmac_f32_e32 v54, v116, v55
	v_fmac_f32_e32 v70, v118, v71
	v_fmac_f32_dpp v54, v55, v122 quad_perm:[1,0,3,2] row_mask:0xf bank_mask:0xf
	v_fmac_f32_dpp v70, v71, v123 quad_perm:[1,0,3,2] row_mask:0xf bank_mask:0xf
	v_cvt_pk_bf16_f32 v149, v54, v70
	ds_write_b32 v151, v149 offset:3808
	v_fmac_f32_e32 v53, v116, v54
	v_fmac_f32_e32 v69, v118, v70
	v_fmac_f32_dpp v53, v54, v122 quad_perm:[1,0,3,2] row_mask:0xf bank_mask:0xf
	v_fmac_f32_dpp v69, v70, v123 quad_perm:[1,0,3,2] row_mask:0xf bank_mask:0xf
	v_cvt_pk_bf16_f32 v148, v53, v69
	ds_write_b32 v151, v148 offset:3536
	v_fmac_f32_e32 v52, v116, v53
	v_fmac_f32_e32 v68, v118, v69
	v_fmac_f32_dpp v52, v53, v122 quad_perm:[1,0,3,2] row_mask:0xf bank_mask:0xf
	v_fmac_f32_dpp v68, v69, v123 quad_perm:[1,0,3,2] row_mask:0xf bank_mask:0xf
	v_cvt_pk_bf16_f32 v149, v52, v68
	ds_write_b32 v151, v149 offset:3264
	v_fmac_f32_e32 v23, v116, v52
	v_fmac_f32_e32 v39, v118, v68
	v_fmac_f32_dpp v23, v52, v122 quad_perm:[1,0,3,2] row_mask:0xf bank_mask:0xf
	v_fmac_f32_dpp v39, v68, v123 quad_perm:[1,0,3,2] row_mask:0xf bank_mask:0xf
	v_cvt_pk_bf16_f32 v148, v23, v39
	ds_write_b32 v151, v148 offset:2992
	v_fmac_f32_e32 v22, v116, v23
	v_fmac_f32_e32 v38, v118, v39
	v_fmac_f32_dpp v22, v23, v122 quad_perm:[1,0,3,2] row_mask:0xf bank_mask:0xf
	v_fmac_f32_dpp v38, v39, v123 quad_perm:[1,0,3,2] row_mask:0xf bank_mask:0xf
	v_cvt_pk_bf16_f32 v149, v22, v38
	ds_write_b32 v151, v149 offset:2720
	v_fmac_f32_e32 v21, v116, v22
	v_fmac_f32_e32 v37, v118, v38
	v_fmac_f32_dpp v21, v22, v122 quad_perm:[1,0,3,2] row_mask:0xf bank_mask:0xf
	v_fmac_f32_dpp v37, v38, v123 quad_perm:[1,0,3,2] row_mask:0xf bank_mask:0xf
	v_cvt_pk_bf16_f32 v148, v21, v37
	ds_write_b32 v151, v148 offset:2448
	v_fmac_f32_e32 v20, v116, v21
	v_fmac_f32_e32 v36, v118, v37
	v_fmac_f32_dpp v20, v21, v122 quad_perm:[1,0,3,2] row_mask:0xf bank_mask:0xf
	v_fmac_f32_dpp v36, v37, v123 quad_perm:[1,0,3,2] row_mask:0xf bank_mask:0xf
	v_cvt_pk_bf16_f32 v149, v20, v36
	ds_write_b32 v151, v149 offset:2176
	v_fmac_f32_e32 v51, v116, v20
	v_fmac_f32_e32 v67, v118, v36
	v_fmac_f32_dpp v51, v20, v122 quad_perm:[1,0,3,2] row_mask:0xf bank_mask:0xf
	v_fmac_f32_dpp v67, v36, v123 quad_perm:[1,0,3,2] row_mask:0xf bank_mask:0xf
	v_cvt_pk_bf16_f32 v148, v51, v67
	ds_write_b32 v151, v148 offset:1904
	v_fmac_f32_e32 v50, v116, v51
	v_fmac_f32_e32 v66, v118, v67
	v_fmac_f32_dpp v50, v51, v122 quad_perm:[1,0,3,2] row_mask:0xf bank_mask:0xf
	v_fmac_f32_dpp v66, v67, v123 quad_perm:[1,0,3,2] row_mask:0xf bank_mask:0xf
	v_cvt_pk_bf16_f32 v149, v50, v66
	ds_write_b32 v151, v149 offset:1632
	v_fmac_f32_e32 v49, v116, v50
	v_fmac_f32_e32 v65, v118, v66
	v_fmac_f32_dpp v49, v50, v122 quad_perm:[1,0,3,2] row_mask:0xf bank_mask:0xf
	v_fmac_f32_dpp v65, v66, v123 quad_perm:[1,0,3,2] row_mask:0xf bank_mask:0xf
	v_cvt_pk_bf16_f32 v148, v49, v65
	ds_write_b32 v151, v148 offset:1360
	v_fmac_f32_e32 v48, v116, v49
	v_fmac_f32_e32 v64, v118, v65
	v_fmac_f32_dpp v48, v49, v122 quad_perm:[1,0,3,2] row_mask:0xf bank_mask:0xf
	v_fmac_f32_dpp v64, v65, v123 quad_perm:[1,0,3,2] row_mask:0xf bank_mask:0xf
	v_cvt_pk_bf16_f32 v149, v48, v64
	ds_write_b32 v151, v149 offset:1088
	v_fmac_f32_e32 v19, v116, v48
	v_fmac_f32_e32 v35, v118, v64
	v_fmac_f32_dpp v19, v48, v122 quad_perm:[1,0,3,2] row_mask:0xf bank_mask:0xf
	v_fmac_f32_dpp v35, v64, v123 quad_perm:[1,0,3,2] row_mask:0xf bank_mask:0xf
	v_cvt_pk_bf16_f32 v148, v19, v35
	ds_write_b32 v151, v148 offset:816
	v_fmac_f32_e32 v18, v116, v19
	v_fmac_f32_e32 v34, v118, v35
	v_fmac_f32_dpp v18, v19, v122 quad_perm:[1,0,3,2] row_mask:0xf bank_mask:0xf
	v_fmac_f32_dpp v34, v35, v123 quad_perm:[1,0,3,2] row_mask:0xf bank_mask:0xf
	v_cvt_pk_bf16_f32 v149, v18, v34
	ds_write_b32 v151, v149 offset:544
	v_fmac_f32_e32 v17, v116, v18
	v_fmac_f32_e32 v33, v118, v34
	v_fmac_f32_dpp v17, v18, v122 quad_perm:[1,0,3,2] row_mask:0xf bank_mask:0xf
	v_fmac_f32_dpp v33, v34, v123 quad_perm:[1,0,3,2] row_mask:0xf bank_mask:0xf
	v_cvt_pk_bf16_f32 v148, v17, v33
	ds_write_b32 v151, v148 offset:272
	v_fmac_f32_e32 v16, v116, v17
	v_fmac_f32_e32 v32, v118, v33
	v_fmac_f32_dpp v16, v17, v122 quad_perm:[1,0,3,2] row_mask:0xf bank_mask:0xf
	v_fmac_f32_dpp v32, v33, v123 quad_perm:[1,0,3,2] row_mask:0xf bank_mask:0xf
	v_cvt_pk_bf16_f32 v149, v16, v32
	ds_write_b32 v151, v149
	v_mov_b32_e32 v120, v16
	v_mov_b32_e32 v121, v32
	ds_read_b128 v[124:127], v152
	ds_read_b128 v[128:131], v152 offset:64
	ds_read_b128 v[132:135], v152 offset:128
	ds_read_b128 v[136:139], v152 offset:192
	s_waitcnt lgkmcnt(3)
	v_mfma_f32_16x16x32_bf16 v[140:143], v[100:103], v[124:127], 0
	s_waitcnt lgkmcnt(2)
	v_mfma_f32_16x16x32_bf16 v[140:143], v[104:107], v[128:131], v[140:143]
	s_waitcnt lgkmcnt(1)
	v_mfma_f32_16x16x32_bf16 v[140:143], v[108:111], v[132:135], v[140:143]
	s_waitcnt lgkmcnt(0)
	v_mfma_f32_16x16x32_bf16 v[140:143], v[112:115], v[136:139], v[140:143]
	s_nop 9
	global_store_dwordx4 v153, v[140:143], s[12:13]
	s_nop 1
	ds_read_b128 v[124:127], v152 offset:4352
	ds_read_b128 v[128:131], v152 offset:4416
	ds_read_b128 v[132:135], v152 offset:4480
	ds_read_b128 v[136:139], v152 offset:4544
	s_waitcnt lgkmcnt(3)
	v_mfma_f32_16x16x32_bf16 v[140:143], v[100:103], v[124:127], 0
	s_waitcnt lgkmcnt(2)
	v_mfma_f32_16x16x32_bf16 v[140:143], v[104:107], v[128:131], v[140:143]
	s_waitcnt lgkmcnt(1)
	v_mfma_f32_16x16x32_bf16 v[140:143], v[108:111], v[132:135], v[140:143]
	s_waitcnt lgkmcnt(0)
	v_mfma_f32_16x16x32_bf16 v[140:143], v[112:115], v[136:139], v[140:143]
	s_nop 9
	global_store_dwordx4 v157, v[140:143], s[12:13]
	s_nop 1
	s_sub_u32 s12, s12, 131072
	s_subb_u32 s13, s13, 0
	s_add_u32 s14, s14, 2
	s_cmp_lt_u32 s14, 16
	s_cbranch_scc1 .Lssm_tileA_d1m0
	s_waitcnt vmcnt(0) lgkmcnt(0)
	s_lshr_b32 s21, s89, 1
	s_lshl_b32 s21, s21, 2
	s_add_u32 s37, s21, 0x21000
	v_mov_b32_e32 v182, s37
	v_mov_b32_e32 v183, 1
	v_cmp_eq_u32_e32 vcc, 0, v191
	s_and_saveexec_b64 s[0:1], vcc
	ds_add_u32 v182, v183
	s_mov_b64 exec, s[0:1]
	s_waitcnt lgkmcnt(0)
	s_mov_b32 s38, 0

.Lssm_spin_done_d1m0:
	s_mov_b64 s[42:43], s[12:13]
	s_sub_u32 s42, s42, 67108864
	s_subb_u32 s43, s43, 0
	s_lshl_b32 s31, s25, 11
	s_lshl_b32 s29, s24, 5
	s_add_u32 s31, s31, s29
	s_add_u32 s31, s31, 344915968
	s_add_u32 s12, s62, s31
	s_addc_u32 s13, s63, 0
	s_mov_b64 s[64:65], s[34:35]
	s_add_u32 s64, s64, 196608
	s_addc_u32 s65, s65, 0
	global_load_dwordx2 v[160:161], v154, s[64:65]
	global_load_dwordx2 v[162:163], v158, s[64:65]
	global_load_dwordx4 v[6:9], v153, s[42:43]
	global_load_dwordx4 v[10:13], v157, s[42:43]
	s_sub_u32 s42, s42, 131072
	s_subb_u32 s43, s43, 0
	s_waitcnt vmcnt(0)
.Lssm_tileB_d1m0:
	s_waitcnt vmcnt(9)
	v_mfma_f32_32x32x16_bf16 v[16:31], v[80:83], v[84:87], 0
	v_mfma_f32_32x32x16_bf16 v[32:47], v[80:83], v[88:91], 0
	v_mfma_f32_32x32x16_bf16 v[48:63], v[80:83], v[92:95], 0
	v_mfma_f32_32x32x16_bf16 v[64:79], v[80:83], v[96:99], 0
	global_load_dwordx2 v[2:3], v154, s[34:35]
	global_load_dwordx2 v[4:5], v158, s[34:35]
	global_load_dwordx4 v[172:175], v153, s[42:43]
	global_load_dwordx4 v[176:179], v157, s[42:43]
	s_sub_u32 s42, s42, 131072
	s_subb_u32 s43, s43, 0
	s_nop 11
	global_load_dwordx4 v[80:83], v150, s[10:11]
	s_sub_u32 s34, s34, 196608
	s_subb_u32 s35, s35, 0
	s_sub_u32 s10, s10, 196608
	s_subb_u32 s11, s11, 0
	v_permlane32_swap_b32_e32 v16, v48
	v_permlane32_swap_b32_e32 v17, v49
	v_permlane32_swap_b32_e32 v18, v50
	v_permlane32_swap_b32_e32 v19, v51
	v_permlane32_swap_b32_e32 v20, v52
	v_permlane32_swap_b32_e32 v21, v53
	v_permlane32_swap_b32_e32 v22, v54
	v_permlane32_swap_b32_e32 v23, v55
	v_permlane32_swap_b32_e32 v24, v56
	v_permlane32_swap_b32_e32 v25, v57
	v_permlane32_swap_b32_e32 v26, v58
	v_permlane32_swap_b32_e32 v27, v59
	v_permlane32_swap_b32_e32 v28, v60
	v_permlane32_swap_b32_e32 v29, v61
	v_permlane32_swap_b32_e32 v30, v62
	v_permlane32_swap_b32_e32 v31, v63
	v_permlane32_swap_b32_e32 v32, v64
	v_permlane32_swap_b32_e32 v33, v65
	v_permlane32_swap_b32_e32 v34, v66
	v_permlane32_swap_b32_e32 v35, v67
	v_permlane32_swap_b32_e32 v36, v68
	v_permlane32_swap_b32_e32 v37, v69
	v_permlane32_swap_b32_e32 v38, v70
	v_permlane32_swap_b32_e32 v39, v71
	v_permlane32_swap_b32_e32 v40, v72
	v_permlane32_swap_b32_e32 v41, v73
	v_permlane32_swap_b32_e32 v42, v74
	v_permlane32_swap_b32_e32 v43, v75
	v_permlane32_swap_b32_e32 v44, v76
	v_permlane32_swap_b32_e32 v45, v77
	v_permlane32_swap_b32_e32 v46, v78
	v_permlane32_swap_b32_e32 v47, v79
	v_fmac_f32_e32 v63, v116, v120
	v_fmac_f32_e32 v79, v118, v121
	v_fmac_f32_dpp v63, v120, v122 quad_perm:[1,0,3,2] row_mask:0xf bank_mask:0xf
	v_fmac_f32_dpp v79, v121, v123 quad_perm:[1,0,3,2] row_mask:0xf bank_mask:0xf
	v_cvt_pk_bf16_f32 v148, v63, v79
	ds_write_b32 v151, v148 offset:8432
	v_fmac_f32_e32 v62, v116, v63
	v_fmac_f32_e32 v78, v118, v79
	v_fmac_f32_dpp v62, v63, v122 quad_perm:[1,0,3,2] row_mask:0xf bank_mask:0xf
	v_fmac_f32_dpp v78, v79, v123 quad_perm:[1,0,3,2] row_mask:0xf bank_mask:0xf
	v_cvt_pk_bf16_f32 v149, v62, v78
	ds_write_b32 v151, v149 offset:8160
	v_fmac_f32_e32 v61, v116, v62
	v_fmac_f32_e32 v77, v118, v78
	v_fmac_f32_dpp v61, v62, v122 quad_perm:[1,0,3,2] row_mask:0xf bank_mask:0xf
	v_fmac_f32_dpp v77, v78, v123 quad_perm:[1,0,3,2] row_mask:0xf bank_mask:0xf
	v_cvt_pk_bf16_f32 v148, v61, v77
	ds_write_b32 v151, v148 offset:7888
	v_fmac_f32_e32 v60, v116, v61
	v_fmac_f32_e32 v76, v118, v77
	v_fmac_f32_dpp v60, v61, v122 quad_perm:[1,0,3,2] row_mask:0xf bank_mask:0xf
	v_fmac_f32_dpp v76, v77, v123 quad_perm:[1,0,3,2] row_mask:0xf bank_mask:0xf
	v_cvt_pk_bf16_f32 v149, v60, v76
	ds_write_b32 v151, v149 offset:7616
	v_fmac_f32_e32 v31, v116, v60
	v_fmac_f32_e32 v47, v118, v76
	v_fmac_f32_dpp v31, v60, v122 quad_perm:[1,0,3,2] row_mask:0xf bank_mask:0xf
	v_fmac_f32_dpp v47, v76, v123 quad_perm:[1,0,3,2] row_mask:0xf bank_mask:0xf
	v_cvt_pk_bf16_f32 v148, v31, v47
	ds_write_b32 v151, v148 offset:7344
	v_fmac_f32_e32 v30, v116, v31
	v_fmac_f32_e32 v46, v118, v47
	v_fmac_f32_dpp v30, v31, v122 quad_perm:[1,0,3,2] row_mask:0xf bank_mask:0xf
	v_fmac_f32_dpp v46, v47, v123 quad_perm:[1,0,3,2] row_mask:0xf bank_mask:0xf
	v_cvt_pk_bf16_f32 v149, v30, v46
	ds_write_b32 v151, v149 offset:7072
	v_fmac_f32_e32 v29, v116, v30
	v_fmac_f32_e32 v45, v118, v46
	v_fmac_f32_dpp v29, v30, v122 quad_perm:[1,0,3,2] row_mask:0xf bank_mask:0xf
	v_fmac_f32_dpp v45, v46, v123 quad_perm:[1,0,3,2] row_mask:0xf bank_mask:0xf
	v_cvt_pk_bf16_f32 v148, v29, v45
	ds_write_b32 v151, v148 offset:6800
	v_fmac_f32_e32 v28, v116, v29
	v_fmac_f32_e32 v44, v118, v45
	v_fmac_f32_dpp v28, v29, v122 quad_perm:[1,0,3,2] row_mask:0xf bank_mask:0xf
	v_fmac_f32_dpp v44, v45, v123 quad_perm:[1,0,3,2] row_mask:0xf bank_mask:0xf
	v_cvt_pk_bf16_f32 v149, v28, v44
	ds_write_b32 v151, v149 offset:6528
	v_fmac_f32_e32 v59, v116, v28
	v_fmac_f32_e32 v75, v118, v44
	v_fmac_f32_dpp v59, v28, v122 quad_perm:[1,0,3,2] row_mask:0xf bank_mask:0xf
	v_fmac_f32_dpp v75, v44, v123 quad_perm:[1,0,3,2] row_mask:0xf bank_mask:0xf
	v_cvt_pk_bf16_f32 v148, v59, v75
	ds_write_b32 v151, v148 offset:6256
	v_fmac_f32_e32 v58, v116, v59
	v_fmac_f32_e32 v74, v118, v75
	v_fmac_f32_dpp v58, v59, v122 quad_perm:[1,0,3,2] row_mask:0xf bank_mask:0xf
	v_fmac_f32_dpp v74, v75, v123 quad_perm:[1,0,3,2] row_mask:0xf bank_mask:0xf
	v_cvt_pk_bf16_f32 v149, v58, v74
	ds_write_b32 v151, v149 offset:5984
	v_fmac_f32_e32 v57, v116, v58
	v_fmac_f32_e32 v73, v118, v74
	v_fmac_f32_dpp v57, v58, v122 quad_perm:[1,0,3,2] row_mask:0xf bank_mask:0xf
	v_fmac_f32_dpp v73, v74, v123 quad_perm:[1,0,3,2] row_mask:0xf bank_mask:0xf
	v_cvt_pk_bf16_f32 v148, v57, v73
	ds_write_b32 v151, v148 offset:5712
	v_fmac_f32_e32 v56, v116, v57
	v_fmac_f32_e32 v72, v118, v73
	v_fmac_f32_dpp v56, v57, v122 quad_perm:[1,0,3,2] row_mask:0xf bank_mask:0xf
	v_fmac_f32_dpp v72, v73, v123 quad_perm:[1,0,3,2] row_mask:0xf bank_mask:0xf
	v_cvt_pk_bf16_f32 v149, v56, v72
	ds_write_b32 v151, v149 offset:5440
	v_fmac_f32_e32 v27, v116, v56
	v_fmac_f32_e32 v43, v118, v72
	v_fmac_f32_dpp v27, v56, v122 quad_perm:[1,0,3,2] row_mask:0xf bank_mask:0xf
	v_fmac_f32_dpp v43, v72, v123 quad_perm:[1,0,3,2] row_mask:0xf bank_mask:0xf
	v_cvt_pk_bf16_f32 v148, v27, v43
	ds_write_b32 v151, v148 offset:5168
	v_fmac_f32_e32 v26, v116, v27
	v_fmac_f32_e32 v42, v118, v43
	v_fmac_f32_dpp v26, v27, v122 quad_perm:[1,0,3,2] row_mask:0xf bank_mask:0xf
	v_fmac_f32_dpp v42, v43, v123 quad_perm:[1,0,3,2] row_mask:0xf bank_mask:0xf
	v_cvt_pk_bf16_f32 v149, v26, v42
	ds_write_b32 v151, v149 offset:4896
	v_fmac_f32_e32 v25, v116, v26
	v_fmac_f32_e32 v41, v118, v42
	v_fmac_f32_dpp v25, v26, v122 quad_perm:[1,0,3,2] row_mask:0xf bank_mask:0xf
	v_fmac_f32_dpp v41, v42, v123 quad_perm:[1,0,3,2] row_mask:0xf bank_mask:0xf
	v_cvt_pk_bf16_f32 v148, v25, v41
	ds_write_b32 v151, v148 offset:4624
	v_fmac_f32_e32 v24, v116, v25
	v_fmac_f32_e32 v40, v118, v41
	v_fmac_f32_dpp v24, v25, v122 quad_perm:[1,0,3,2] row_mask:0xf bank_mask:0xf
	v_fmac_f32_dpp v40, v41, v123 quad_perm:[1,0,3,2] row_mask:0xf bank_mask:0xf
	v_cvt_pk_bf16_f32 v149, v24, v40
	ds_write_b32 v151, v149 offset:4352
	v_fmac_f32_e32 v55, v116, v24
	v_fmac_f32_e32 v71, v118, v40
	v_fmac_f32_dpp v55, v24, v122 quad_perm:[1,0,3,2] row_mask:0xf bank_mask:0xf
	v_fmac_f32_dpp v71, v40, v123 quad_perm:[1,0,3,2] row_mask:0xf bank_mask:0xf
	v_cvt_pk_bf16_f32 v148, v55, v71
	ds_write_b32 v151, v148 offset:4080
	v_fmac_f32_e32 v54, v116, v55
	v_fmac_f32_e32 v70, v118, v71
	v_fmac_f32_dpp v54, v55, v122 quad_perm:[1,0,3,2] row_mask:0xf bank_mask:0xf
	v_fmac_f32_dpp v70, v71, v123 quad_perm:[1,0,3,2] row_mask:0xf bank_mask:0xf
	v_cvt_pk_bf16_f32 v149, v54, v70
	ds_write_b32 v151, v149 offset:3808
	v_fmac_f32_e32 v53, v116, v54
	v_fmac_f32_e32 v69, v118, v70
	v_fmac_f32_dpp v53, v54, v122 quad_perm:[1,0,3,2] row_mask:0xf bank_mask:0xf
	v_fmac_f32_dpp v69, v70, v123 quad_perm:[1,0,3,2] row_mask:0xf bank_mask:0xf
	v_cvt_pk_bf16_f32 v148, v53, v69
	ds_write_b32 v151, v148 offset:3536
	v_fmac_f32_e32 v52, v116, v53
	v_fmac_f32_e32 v68, v118, v69
	v_fmac_f32_dpp v52, v53, v122 quad_perm:[1,0,3,2] row_mask:0xf bank_mask:0xf
	v_fmac_f32_dpp v68, v69, v123 quad_perm:[1,0,3,2] row_mask:0xf bank_mask:0xf
	v_cvt_pk_bf16_f32 v149, v52, v68
	ds_write_b32 v151, v149 offset:3264
	v_fmac_f32_e32 v23, v116, v52
	v_fmac_f32_e32 v39, v118, v68
	v_fmac_f32_dpp v23, v52, v122 quad_perm:[1,0,3,2] row_mask:0xf bank_mask:0xf
	v_fmac_f32_dpp v39, v68, v123 quad_perm:[1,0,3,2] row_mask:0xf bank_mask:0xf
	v_cvt_pk_bf16_f32 v148, v23, v39
	ds_write_b32 v151, v148 offset:2992
	v_fmac_f32_e32 v22, v116, v23
	v_fmac_f32_e32 v38, v118, v39
	v_fmac_f32_dpp v22, v23, v122 quad_perm:[1,0,3,2] row_mask:0xf bank_mask:0xf
	v_fmac_f32_dpp v38, v39, v123 quad_perm:[1,0,3,2] row_mask:0xf bank_mask:0xf
	v_cvt_pk_bf16_f32 v149, v22, v38
	ds_write_b32 v151, v149 offset:2720
	v_fmac_f32_e32 v21, v116, v22
	v_fmac_f32_e32 v37, v118, v38
	v_fmac_f32_dpp v21, v22, v122 quad_perm:[1,0,3,2] row_mask:0xf bank_mask:0xf
	v_fmac_f32_dpp v37, v38, v123 quad_perm:[1,0,3,2] row_mask:0xf bank_mask:0xf
	v_cvt_pk_bf16_f32 v148, v21, v37
	ds_write_b32 v151, v148 offset:2448
	v_fmac_f32_e32 v20, v116, v21
	v_fmac_f32_e32 v36, v118, v37
	v_fmac_f32_dpp v20, v21, v122 quad_perm:[1,0,3,2] row_mask:0xf bank_mask:0xf
	v_fmac_f32_dpp v36, v37, v123 quad_perm:[1,0,3,2] row_mask:0xf bank_mask:0xf
	v_cvt_pk_bf16_f32 v149, v20, v36
	ds_write_b32 v151, v149 offset:2176
	v_fmac_f32_e32 v51, v116, v20
	v_fmac_f32_e32 v67, v118, v36
	v_fmac_f32_dpp v51, v20, v122 quad_perm:[1,0,3,2] row_mask:0xf bank_mask:0xf
	v_fmac_f32_dpp v67, v36, v123 quad_perm:[1,0,3,2] row_mask:0xf bank_mask:0xf
	v_cvt_pk_bf16_f32 v148, v51, v67
	ds_write_b32 v151, v148 offset:1904
	v_fmac_f32_e32 v50, v116, v51
	v_fmac_f32_e32 v66, v118, v67
	v_fmac_f32_dpp v50, v51, v122 quad_perm:[1,0,3,2] row_mask:0xf bank_mask:0xf
	v_fmac_f32_dpp v66, v67, v123 quad_perm:[1,0,3,2] row_mask:0xf bank_mask:0xf
	v_cvt_pk_bf16_f32 v149, v50, v66
	ds_write_b32 v151, v149 offset:1632
	v_fmac_f32_e32 v49, v116, v50
	v_fmac_f32_e32 v65, v118, v66
	v_fmac_f32_dpp v49, v50, v122 quad_perm:[1,0,3,2] row_mask:0xf bank_mask:0xf
	v_fmac_f32_dpp v65, v66, v123 quad_perm:[1,0,3,2] row_mask:0xf bank_mask:0xf
	v_cvt_pk_bf16_f32 v148, v49, v65
	ds_write_b32 v151, v148 offset:1360
	v_fmac_f32_e32 v48, v116, v49
	v_fmac_f32_e32 v64, v118, v65
	v_fmac_f32_dpp v48, v49, v122 quad_perm:[1,0,3,2] row_mask:0xf bank_mask:0xf
	v_fmac_f32_dpp v64, v65, v123 quad_perm:[1,0,3,2] row_mask:0xf bank_mask:0xf
	v_cvt_pk_bf16_f32 v149, v48, v64
	ds_write_b32 v151, v149 offset:1088
	v_fmac_f32_e32 v19, v116, v48
	v_fmac_f32_e32 v35, v118, v64
	v_fmac_f32_dpp v19, v48, v122 quad_perm:[1,0,3,2] row_mask:0xf bank_mask:0xf
	v_fmac_f32_dpp v35, v64, v123 quad_perm:[1,0,3,2] row_mask:0xf bank_mask:0xf
	v_cvt_pk_bf16_f32 v148, v19, v35
	ds_write_b32 v151, v148 offset:816
	v_fmac_f32_e32 v18, v116, v19
	v_fmac_f32_e32 v34, v118, v35
	v_fmac_f32_dpp v18, v19, v122 quad_perm:[1,0,3,2] row_mask:0xf bank_mask:0xf
	v_fmac_f32_dpp v34, v35, v123 quad_perm:[1,0,3,2] row_mask:0xf bank_mask:0xf
	v_cvt_pk_bf16_f32 v149, v18, v34
	ds_write_b32 v151, v149 offset:544
	v_fmac_f32_e32 v17, v116, v18
	v_fmac_f32_e32 v33, v118, v34
	v_fmac_f32_dpp v17, v18, v122 quad_perm:[1,0,3,2] row_mask:0xf bank_mask:0xf
	v_fmac_f32_dpp v33, v34, v123 quad_perm:[1,0,3,2] row_mask:0xf bank_mask:0xf
	v_cvt_pk_bf16_f32 v148, v17, v33
	ds_write_b32 v151, v148 offset:272
	v_fmac_f32_e32 v16, v116, v17
	v_fmac_f32_e32 v32, v118, v33
	v_fmac_f32_dpp v16, v17, v122 quad_perm:[1,0,3,2] row_mask:0xf bank_mask:0xf
	v_fmac_f32_dpp v32, v33, v123 quad_perm:[1,0,3,2] row_mask:0xf bank_mask:0xf
	v_cvt_pk_bf16_f32 v149, v16, v32
	ds_write_b32 v151, v149
	v_mov_b32_e32 v120, v16
	v_mov_b32_e32 v121, v32
	ds_read_b128 v[124:127], v152
	ds_read_b128 v[128:131], v152 offset:64
	ds_read_b128 v[132:135], v152 offset:128
	ds_read_b128 v[136:139], v152 offset:192
	s_waitcnt lgkmcnt(3)
	v_mfma_f32_16x16x32_bf16 v[140:143], v[100:103], v[124:127], 0
	s_waitcnt lgkmcnt(2)
	v_mfma_f32_16x16x32_bf16 v[140:143], v[104:107], v[128:131], v[140:143]
	s_waitcnt lgkmcnt(1)
	v_mfma_f32_16x16x32_bf16 v[140:143], v[108:111], v[132:135], v[140:143]
	s_waitcnt lgkmcnt(0)
	v_mfma_f32_16x16x32_bf16 v[140:143], v[112:115], v[136:139], v[140:143]
	s_nop 9
	s_waitcnt vmcnt(9)
	v_add_f32_e32 v182, v6, v140
	v_add_f32_e32 v183, v7, v141
	v_add_f32_e32 v184, v8, v142
	v_add_f32_e32 v185, v9, v143
	v_lshlrev_b32_e32 v186, 16, v160
	v_and_b32_e32 v187, 0xffff0000, v160
	v_lshlrev_b32_e32 v188, 16, v161
	v_and_b32_e32 v189, 0xffff0000, v161
	v_fmac_f32_e32 v182, v164, v186
	v_fmac_f32_e32 v183, v165, v187
	v_fmac_f32_e32 v184, v166, v188
	v_fmac_f32_e32 v185, v167, v189
	v_mul_f32_e32 v186, 0x3d372713, v182
	v_mul_f32_e32 v187, 0x3d372713, v183
	v_mul_f32_e32 v188, 0x3d372713, v184
	v_mul_f32_e32 v189, 0x3d372713, v185
	v_mul_f32_e32 v186, v182, v186
	v_mul_f32_e32 v187, v183, v187
	v_mul_f32_e32 v188, v184, v188
	v_mul_f32_e32 v189, v185, v189
	v_fma_f32 v186, v182, v186, v182
	v_fma_f32 v187, v183, v187, v183
	v_fma_f32 v188, v184, v188, v184
	v_fma_f32 v189, v185, v189, v185
	v_mul_f32_e32 v186, 0xbfcc422a, v186
	v_mul_f32_e32 v187, 0xbfcc422a, v187
	v_mul_f32_e32 v188, 0xbfcc422a, v188
	v_mul_f32_e32 v189, 0xbfcc422a, v189
	v_mul_f32_e32 v186, 0x3fb8aa3b, v186
	v_mul_f32_e32 v187, 0x3fb8aa3b, v187
	v_mul_f32_e32 v188, 0x3fb8aa3b, v188
	v_mul_f32_e32 v189, 0x3fb8aa3b, v189
	v_exp_f32_e32 v186, v186
	v_exp_f32_e32 v187, v187
	v_exp_f32_e32 v188, v188
	v_exp_f32_e32 v189, v189
	v_add_f32_e32 v186, 1.0, v186
	v_add_f32_e32 v187, 1.0, v187
	v_add_f32_e32 v188, 1.0, v188
	v_add_f32_e32 v189, 1.0, v189
	v_rcp_f32_e32 v186, v186
	v_rcp_f32_e32 v187, v187
	v_rcp_f32_e32 v188, v188
	v_rcp_f32_e32 v189, v189
	v_mul_f32_e32 v182, v182, v186
	v_mul_f32_e32 v183, v183, v187
	v_mul_f32_e32 v184, v184, v188
	v_mul_f32_e32 v185, v185, v189
	v_cvt_pk_bf16_f32 v148, v182, v183
	v_cvt_pk_bf16_f32 v149, v184, v185
	global_store_dwordx2 v156, v[148:149], s[12:13]
	ds_read_b128 v[124:127], v152 offset:4352
	ds_read_b128 v[128:131], v152 offset:4416
	ds_read_b128 v[132:135], v152 offset:4480
	ds_read_b128 v[136:139], v152 offset:4544
	s_waitcnt lgkmcnt(3)
	v_mfma_f32_16x16x32_bf16 v[140:143], v[100:103], v[124:127], 0
	s_waitcnt lgkmcnt(2)
	v_mfma_f32_16x16x32_bf16 v[140:143], v[104:107], v[128:131], v[140:143]
	s_waitcnt lgkmcnt(1)
	v_mfma_f32_16x16x32_bf16 v[140:143], v[108:111], v[132:135], v[140:143]
	s_waitcnt lgkmcnt(0)
	v_mfma_f32_16x16x32_bf16 v[140:143], v[112:115], v[136:139], v[140:143]
	s_nop 9
	s_waitcnt vmcnt(9)
	v_add_f32_e32 v182, v10, v140
	v_add_f32_e32 v183, v11, v141
	v_add_f32_e32 v184, v12, v142
	v_add_f32_e32 v185, v13, v143
	v_lshlrev_b32_e32 v186, 16, v162
	v_and_b32_e32 v187, 0xffff0000, v162
	v_lshlrev_b32_e32 v188, 16, v163
	v_and_b32_e32 v189, 0xffff0000, v163
	v_fmac_f32_e32 v182, v164, v186
	v_fmac_f32_e32 v183, v165, v187
	v_fmac_f32_e32 v184, v166, v188
	v_fmac_f32_e32 v185, v167, v189
	v_mul_f32_e32 v186, 0x3d372713, v182
	v_mul_f32_e32 v187, 0x3d372713, v183
	v_mul_f32_e32 v188, 0x3d372713, v184
	v_mul_f32_e32 v189, 0x3d372713, v185
	v_mul_f32_e32 v186, v182, v186
	v_mul_f32_e32 v187, v183, v187
	v_mul_f32_e32 v188, v184, v188
	v_mul_f32_e32 v189, v185, v189
	v_fma_f32 v186, v182, v186, v182
	v_fma_f32 v187, v183, v187, v183
	v_fma_f32 v188, v184, v188, v184
	v_fma_f32 v189, v185, v189, v185
	v_mul_f32_e32 v186, 0xbfcc422a, v186
	v_mul_f32_e32 v187, 0xbfcc422a, v187
	v_mul_f32_e32 v188, 0xbfcc422a, v188
	v_mul_f32_e32 v189, 0xbfcc422a, v189
	v_mul_f32_e32 v186, 0x3fb8aa3b, v186
	v_mul_f32_e32 v187, 0x3fb8aa3b, v187
	v_mul_f32_e32 v188, 0x3fb8aa3b, v188
	v_mul_f32_e32 v189, 0x3fb8aa3b, v189
	v_exp_f32_e32 v186, v186
	v_exp_f32_e32 v187, v187
	v_exp_f32_e32 v188, v188
	v_exp_f32_e32 v189, v189
	v_add_f32_e32 v186, 1.0, v186
	v_add_f32_e32 v187, 1.0, v187
	v_add_f32_e32 v188, 1.0, v188
	v_add_f32_e32 v189, 1.0, v189
	v_rcp_f32_e32 v186, v186
	v_rcp_f32_e32 v187, v187
	v_rcp_f32_e32 v188, v188
	v_rcp_f32_e32 v189, v189
	v_mul_f32_e32 v182, v182, v186
	v_mul_f32_e32 v183, v183, v187
	v_mul_f32_e32 v184, v184, v188
	v_mul_f32_e32 v185, v185, v189
	v_cvt_pk_bf16_f32 v148, v182, v183
	v_cvt_pk_bf16_f32 v149, v184, v185
	global_store_dwordx2 v159, v[148:149], s[12:13]
	s_sub_u32 s12, s12, 65536
	s_subb_u32 s13, s13, 0
	s_waitcnt vmcnt(9)
	v_mfma_f32_32x32x16_bf16 v[16:31], v[144:147], v[84:87], 0
	v_mfma_f32_32x32x16_bf16 v[32:47], v[144:147], v[88:91], 0
	v_mfma_f32_32x32x16_bf16 v[48:63], v[144:147], v[92:95], 0
	v_mfma_f32_32x32x16_bf16 v[64:79], v[144:147], v[96:99], 0
	global_load_dwordx2 v[160:161], v154, s[34:35]
	global_load_dwordx2 v[162:163], v158, s[34:35]
	global_load_dwordx4 v[6:9], v153, s[42:43]
	global_load_dwordx4 v[10:13], v157, s[42:43]
	s_sub_u32 s42, s42, 131072
	s_subb_u32 s43, s43, 0
	s_nop 11
	global_load_dwordx4 v[144:147], v150, s[10:11]
	s_sub_u32 s34, s34, 196608
	s_subb_u32 s35, s35, 0
	s_sub_u32 s10, s10, 196608
	s_subb_u32 s11, s11, 0
	v_permlane32_swap_b32_e32 v16, v48
	v_permlane32_swap_b32_e32 v17, v49
	v_permlane32_swap_b32_e32 v18, v50
	v_permlane32_swap_b32_e32 v19, v51
	v_permlane32_swap_b32_e32 v20, v52
	v_permlane32_swap_b32_e32 v21, v53
	v_permlane32_swap_b32_e32 v22, v54
	v_permlane32_swap_b32_e32 v23, v55
	v_permlane32_swap_b32_e32 v24, v56
	v_permlane32_swap_b32_e32 v25, v57
	v_permlane32_swap_b32_e32 v26, v58
	v_permlane32_swap_b32_e32 v27, v59
	v_permlane32_swap_b32_e32 v28, v60
	v_permlane32_swap_b32_e32 v29, v61
	v_permlane32_swap_b32_e32 v30, v62
	v_permlane32_swap_b32_e32 v31, v63
	v_permlane32_swap_b32_e32 v32, v64
	v_permlane32_swap_b32_e32 v33, v65
	v_permlane32_swap_b32_e32 v34, v66
	v_permlane32_swap_b32_e32 v35, v67
	v_permlane32_swap_b32_e32 v36, v68
	v_permlane32_swap_b32_e32 v37, v69
	v_permlane32_swap_b32_e32 v38, v70
	v_permlane32_swap_b32_e32 v39, v71
	v_permlane32_swap_b32_e32 v40, v72
	v_permlane32_swap_b32_e32 v41, v73
	v_permlane32_swap_b32_e32 v42, v74
	v_permlane32_swap_b32_e32 v43, v75
	v_permlane32_swap_b32_e32 v44, v76
	v_permlane32_swap_b32_e32 v45, v77
	v_permlane32_swap_b32_e32 v46, v78
	v_permlane32_swap_b32_e32 v47, v79
	v_fmac_f32_e32 v63, v116, v120
	v_fmac_f32_e32 v79, v118, v121
	v_fmac_f32_dpp v63, v120, v122 quad_perm:[1,0,3,2] row_mask:0xf bank_mask:0xf
	v_fmac_f32_dpp v79, v121, v123 quad_perm:[1,0,3,2] row_mask:0xf bank_mask:0xf
	v_cvt_pk_bf16_f32 v148, v63, v79
	ds_write_b32 v151, v148 offset:8432
	v_fmac_f32_e32 v62, v116, v63
	v_fmac_f32_e32 v78, v118, v79
	v_fmac_f32_dpp v62, v63, v122 quad_perm:[1,0,3,2] row_mask:0xf bank_mask:0xf
	v_fmac_f32_dpp v78, v79, v123 quad_perm:[1,0,3,2] row_mask:0xf bank_mask:0xf
	v_cvt_pk_bf16_f32 v149, v62, v78
	ds_write_b32 v151, v149 offset:8160
	v_fmac_f32_e32 v61, v116, v62
	v_fmac_f32_e32 v77, v118, v78
	v_fmac_f32_dpp v61, v62, v122 quad_perm:[1,0,3,2] row_mask:0xf bank_mask:0xf
	v_fmac_f32_dpp v77, v78, v123 quad_perm:[1,0,3,2] row_mask:0xf bank_mask:0xf
	v_cvt_pk_bf16_f32 v148, v61, v77
	ds_write_b32 v151, v148 offset:7888
	v_fmac_f32_e32 v60, v116, v61
	v_fmac_f32_e32 v76, v118, v77
	v_fmac_f32_dpp v60, v61, v122 quad_perm:[1,0,3,2] row_mask:0xf bank_mask:0xf
	v_fmac_f32_dpp v76, v77, v123 quad_perm:[1,0,3,2] row_mask:0xf bank_mask:0xf
	v_cvt_pk_bf16_f32 v149, v60, v76
	ds_write_b32 v151, v149 offset:7616
	v_fmac_f32_e32 v31, v116, v60
	v_fmac_f32_e32 v47, v118, v76
	v_fmac_f32_dpp v31, v60, v122 quad_perm:[1,0,3,2] row_mask:0xf bank_mask:0xf
	v_fmac_f32_dpp v47, v76, v123 quad_perm:[1,0,3,2] row_mask:0xf bank_mask:0xf
	v_cvt_pk_bf16_f32 v148, v31, v47
	ds_write_b32 v151, v148 offset:7344
	v_fmac_f32_e32 v30, v116, v31
	v_fmac_f32_e32 v46, v118, v47
	v_fmac_f32_dpp v30, v31, v122 quad_perm:[1,0,3,2] row_mask:0xf bank_mask:0xf
	v_fmac_f32_dpp v46, v47, v123 quad_perm:[1,0,3,2] row_mask:0xf bank_mask:0xf
	v_cvt_pk_bf16_f32 v149, v30, v46
	ds_write_b32 v151, v149 offset:7072
	v_fmac_f32_e32 v29, v116, v30
	v_fmac_f32_e32 v45, v118, v46
	v_fmac_f32_dpp v29, v30, v122 quad_perm:[1,0,3,2] row_mask:0xf bank_mask:0xf
	v_fmac_f32_dpp v45, v46, v123 quad_perm:[1,0,3,2] row_mask:0xf bank_mask:0xf
	v_cvt_pk_bf16_f32 v148, v29, v45
	ds_write_b32 v151, v148 offset:6800
	v_fmac_f32_e32 v28, v116, v29
	v_fmac_f32_e32 v44, v118, v45
	v_fmac_f32_dpp v28, v29, v122 quad_perm:[1,0,3,2] row_mask:0xf bank_mask:0xf
	v_fmac_f32_dpp v44, v45, v123 quad_perm:[1,0,3,2] row_mask:0xf bank_mask:0xf
	v_cvt_pk_bf16_f32 v149, v28, v44
	ds_write_b32 v151, v149 offset:6528
	v_fmac_f32_e32 v59, v116, v28
	v_fmac_f32_e32 v75, v118, v44
	v_fmac_f32_dpp v59, v28, v122 quad_perm:[1,0,3,2] row_mask:0xf bank_mask:0xf
	v_fmac_f32_dpp v75, v44, v123 quad_perm:[1,0,3,2] row_mask:0xf bank_mask:0xf
	v_cvt_pk_bf16_f32 v148, v59, v75
	ds_write_b32 v151, v148 offset:6256
	v_fmac_f32_e32 v58, v116, v59
	v_fmac_f32_e32 v74, v118, v75
	v_fmac_f32_dpp v58, v59, v122 quad_perm:[1,0,3,2] row_mask:0xf bank_mask:0xf
	v_fmac_f32_dpp v74, v75, v123 quad_perm:[1,0,3,2] row_mask:0xf bank_mask:0xf
	v_cvt_pk_bf16_f32 v149, v58, v74
	ds_write_b32 v151, v149 offset:5984
	v_fmac_f32_e32 v57, v116, v58
	v_fmac_f32_e32 v73, v118, v74
	v_fmac_f32_dpp v57, v58, v122 quad_perm:[1,0,3,2] row_mask:0xf bank_mask:0xf
	v_fmac_f32_dpp v73, v74, v123 quad_perm:[1,0,3,2] row_mask:0xf bank_mask:0xf
	v_cvt_pk_bf16_f32 v148, v57, v73
	ds_write_b32 v151, v148 offset:5712
	v_fmac_f32_e32 v56, v116, v57
	v_fmac_f32_e32 v72, v118, v73
	v_fmac_f32_dpp v56, v57, v122 quad_perm:[1,0,3,2] row_mask:0xf bank_mask:0xf
	v_fmac_f32_dpp v72, v73, v123 quad_perm:[1,0,3,2] row_mask:0xf bank_mask:0xf
	v_cvt_pk_bf16_f32 v149, v56, v72
	ds_write_b32 v151, v149 offset:5440
	v_fmac_f32_e32 v27, v116, v56
	v_fmac_f32_e32 v43, v118, v72
	v_fmac_f32_dpp v27, v56, v122 quad_perm:[1,0,3,2] row_mask:0xf bank_mask:0xf
	v_fmac_f32_dpp v43, v72, v123 quad_perm:[1,0,3,2] row_mask:0xf bank_mask:0xf
	v_cvt_pk_bf16_f32 v148, v27, v43
	ds_write_b32 v151, v148 offset:5168
	v_fmac_f32_e32 v26, v116, v27
	v_fmac_f32_e32 v42, v118, v43
	v_fmac_f32_dpp v26, v27, v122 quad_perm:[1,0,3,2] row_mask:0xf bank_mask:0xf
	v_fmac_f32_dpp v42, v43, v123 quad_perm:[1,0,3,2] row_mask:0xf bank_mask:0xf
	v_cvt_pk_bf16_f32 v149, v26, v42
	ds_write_b32 v151, v149 offset:4896
	v_fmac_f32_e32 v25, v116, v26
	v_fmac_f32_e32 v41, v118, v42
	v_fmac_f32_dpp v25, v26, v122 quad_perm:[1,0,3,2] row_mask:0xf bank_mask:0xf
	v_fmac_f32_dpp v41, v42, v123 quad_perm:[1,0,3,2] row_mask:0xf bank_mask:0xf
	v_cvt_pk_bf16_f32 v148, v25, v41
	ds_write_b32 v151, v148 offset:4624
	v_fmac_f32_e32 v24, v116, v25
	v_fmac_f32_e32 v40, v118, v41
	v_fmac_f32_dpp v24, v25, v122 quad_perm:[1,0,3,2] row_mask:0xf bank_mask:0xf
	v_fmac_f32_dpp v40, v41, v123 quad_perm:[1,0,3,2] row_mask:0xf bank_mask:0xf
	v_cvt_pk_bf16_f32 v149, v24, v40
	ds_write_b32 v151, v149 offset:4352
	v_fmac_f32_e32 v55, v116, v24
	v_fmac_f32_e32 v71, v118, v40
	v_fmac_f32_dpp v55, v24, v122 quad_perm:[1,0,3,2] row_mask:0xf bank_mask:0xf
	v_fmac_f32_dpp v71, v40, v123 quad_perm:[1,0,3,2] row_mask:0xf bank_mask:0xf
	v_cvt_pk_bf16_f32 v148, v55, v71
	ds_write_b32 v151, v148 offset:4080
	v_fmac_f32_e32 v54, v116, v55
	v_fmac_f32_e32 v70, v118, v71
	v_fmac_f32_dpp v54, v55, v122 quad_perm:[1,0,3,2] row_mask:0xf bank_mask:0xf
	v_fmac_f32_dpp v70, v71, v123 quad_perm:[1,0,3,2] row_mask:0xf bank_mask:0xf
	v_cvt_pk_bf16_f32 v149, v54, v70
	ds_write_b32 v151, v149 offset:3808
	v_fmac_f32_e32 v53, v116, v54
	v_fmac_f32_e32 v69, v118, v70
	v_fmac_f32_dpp v53, v54, v122 quad_perm:[1,0,3,2] row_mask:0xf bank_mask:0xf
	v_fmac_f32_dpp v69, v70, v123 quad_perm:[1,0,3,2] row_mask:0xf bank_mask:0xf
	v_cvt_pk_bf16_f32 v148, v53, v69
	ds_write_b32 v151, v148 offset:3536
	v_fmac_f32_e32 v52, v116, v53
	v_fmac_f32_e32 v68, v118, v69
	v_fmac_f32_dpp v52, v53, v122 quad_perm:[1,0,3,2] row_mask:0xf bank_mask:0xf
	v_fmac_f32_dpp v68, v69, v123 quad_perm:[1,0,3,2] row_mask:0xf bank_mask:0xf
	v_cvt_pk_bf16_f32 v149, v52, v68
	ds_write_b32 v151, v149 offset:3264
	v_fmac_f32_e32 v23, v116, v52
	v_fmac_f32_e32 v39, v118, v68
	v_fmac_f32_dpp v23, v52, v122 quad_perm:[1,0,3,2] row_mask:0xf bank_mask:0xf
	v_fmac_f32_dpp v39, v68, v123 quad_perm:[1,0,3,2] row_mask:0xf bank_mask:0xf
	v_cvt_pk_bf16_f32 v148, v23, v39
	ds_write_b32 v151, v148 offset:2992
	v_fmac_f32_e32 v22, v116, v23
	v_fmac_f32_e32 v38, v118, v39
	v_fmac_f32_dpp v22, v23, v122 quad_perm:[1,0,3,2] row_mask:0xf bank_mask:0xf
	v_fmac_f32_dpp v38, v39, v123 quad_perm:[1,0,3,2] row_mask:0xf bank_mask:0xf
	v_cvt_pk_bf16_f32 v149, v22, v38
	ds_write_b32 v151, v149 offset:2720
	v_fmac_f32_e32 v21, v116, v22
	v_fmac_f32_e32 v37, v118, v38
	v_fmac_f32_dpp v21, v22, v122 quad_perm:[1,0,3,2] row_mask:0xf bank_mask:0xf
	v_fmac_f32_dpp v37, v38, v123 quad_perm:[1,0,3,2] row_mask:0xf bank_mask:0xf
	v_cvt_pk_bf16_f32 v148, v21, v37
	ds_write_b32 v151, v148 offset:2448
	v_fmac_f32_e32 v20, v116, v21
	v_fmac_f32_e32 v36, v118, v37
	v_fmac_f32_dpp v20, v21, v122 quad_perm:[1,0,3,2] row_mask:0xf bank_mask:0xf
	v_fmac_f32_dpp v36, v37, v123 quad_perm:[1,0,3,2] row_mask:0xf bank_mask:0xf
	v_cvt_pk_bf16_f32 v149, v20, v36
	ds_write_b32 v151, v149 offset:2176
	v_fmac_f32_e32 v51, v116, v20
	v_fmac_f32_e32 v67, v118, v36
	v_fmac_f32_dpp v51, v20, v122 quad_perm:[1,0,3,2] row_mask:0xf bank_mask:0xf
	v_fmac_f32_dpp v67, v36, v123 quad_perm:[1,0,3,2] row_mask:0xf bank_mask:0xf
	v_cvt_pk_bf16_f32 v148, v51, v67
	ds_write_b32 v151, v148 offset:1904
	v_fmac_f32_e32 v50, v116, v51
	v_fmac_f32_e32 v66, v118, v67
	v_fmac_f32_dpp v50, v51, v122 quad_perm:[1,0,3,2] row_mask:0xf bank_mask:0xf
	v_fmac_f32_dpp v66, v67, v123 quad_perm:[1,0,3,2] row_mask:0xf bank_mask:0xf
	v_cvt_pk_bf16_f32 v149, v50, v66
	ds_write_b32 v151, v149 offset:1632
	v_fmac_f32_e32 v49, v116, v50
	v_fmac_f32_e32 v65, v118, v66
	v_fmac_f32_dpp v49, v50, v122 quad_perm:[1,0,3,2] row_mask:0xf bank_mask:0xf
	v_fmac_f32_dpp v65, v66, v123 quad_perm:[1,0,3,2] row_mask:0xf bank_mask:0xf
	v_cvt_pk_bf16_f32 v148, v49, v65
	ds_write_b32 v151, v148 offset:1360
	v_fmac_f32_e32 v48, v116, v49
	v_fmac_f32_e32 v64, v118, v65
	v_fmac_f32_dpp v48, v49, v122 quad_perm:[1,0,3,2] row_mask:0xf bank_mask:0xf
	v_fmac_f32_dpp v64, v65, v123 quad_perm:[1,0,3,2] row_mask:0xf bank_mask:0xf
	v_cvt_pk_bf16_f32 v149, v48, v64
	ds_write_b32 v151, v149 offset:1088
	v_fmac_f32_e32 v19, v116, v48
	v_fmac_f32_e32 v35, v118, v64
	v_fmac_f32_dpp v19, v48, v122 quad_perm:[1,0,3,2] row_mask:0xf bank_mask:0xf
	v_fmac_f32_dpp v35, v64, v123 quad_perm:[1,0,3,2] row_mask:0xf bank_mask:0xf
	v_cvt_pk_bf16_f32 v148, v19, v35
	ds_write_b32 v151, v148 offset:816
	v_fmac_f32_e32 v18, v116, v19
	v_fmac_f32_e32 v34, v118, v35
	v_fmac_f32_dpp v18, v19, v122 quad_perm:[1,0,3,2] row_mask:0xf bank_mask:0xf
	v_fmac_f32_dpp v34, v35, v123 quad_perm:[1,0,3,2] row_mask:0xf bank_mask:0xf
	v_cvt_pk_bf16_f32 v149, v18, v34
	ds_write_b32 v151, v149 offset:544
	v_fmac_f32_e32 v17, v116, v18
	v_fmac_f32_e32 v33, v118, v34
	v_fmac_f32_dpp v17, v18, v122 quad_perm:[1,0,3,2] row_mask:0xf bank_mask:0xf
	v_fmac_f32_dpp v33, v34, v123 quad_perm:[1,0,3,2] row_mask:0xf bank_mask:0xf
	v_cvt_pk_bf16_f32 v148, v17, v33
	ds_write_b32 v151, v148 offset:272
	v_fmac_f32_e32 v16, v116, v17
	v_fmac_f32_e32 v32, v118, v33
	v_fmac_f32_dpp v16, v17, v122 quad_perm:[1,0,3,2] row_mask:0xf bank_mask:0xf
	v_fmac_f32_dpp v32, v33, v123 quad_perm:[1,0,3,2] row_mask:0xf bank_mask:0xf
	v_cvt_pk_bf16_f32 v149, v16, v32
	ds_write_b32 v151, v149
	v_mov_b32_e32 v120, v16
	v_mov_b32_e32 v121, v32
	ds_read_b128 v[124:127], v152
	ds_read_b128 v[128:131], v152 offset:64
	ds_read_b128 v[132:135], v152 offset:128
	ds_read_b128 v[136:139], v152 offset:192
	s_waitcnt lgkmcnt(3)
	v_mfma_f32_16x16x32_bf16 v[140:143], v[100:103], v[124:127], 0
	s_waitcnt lgkmcnt(2)
	v_mfma_f32_16x16x32_bf16 v[140:143], v[104:107], v[128:131], v[140:143]
	s_waitcnt lgkmcnt(1)
	v_mfma_f32_16x16x32_bf16 v[140:143], v[108:111], v[132:135], v[140:143]
	s_waitcnt lgkmcnt(0)
	v_mfma_f32_16x16x32_bf16 v[140:143], v[112:115], v[136:139], v[140:143]
	s_nop 9
	s_waitcnt vmcnt(9)
	v_add_f32_e32 v182, v172, v140
	v_add_f32_e32 v183, v173, v141
	v_add_f32_e32 v184, v174, v142
	v_add_f32_e32 v185, v175, v143
	v_lshlrev_b32_e32 v186, 16, v2
	v_and_b32_e32 v187, 0xffff0000, v2
	v_lshlrev_b32_e32 v188, 16, v3
	v_and_b32_e32 v189, 0xffff0000, v3
	v_fmac_f32_e32 v182, v164, v186
	v_fmac_f32_e32 v183, v165, v187
	v_fmac_f32_e32 v184, v166, v188
	v_fmac_f32_e32 v185, v167, v189
	v_mul_f32_e32 v186, 0x3d372713, v182
	v_mul_f32_e32 v187, 0x3d372713, v183
	v_mul_f32_e32 v188, 0x3d372713, v184
	v_mul_f32_e32 v189, 0x3d372713, v185
	v_mul_f32_e32 v186, v182, v186
	v_mul_f32_e32 v187, v183, v187
	v_mul_f32_e32 v188, v184, v188
	v_mul_f32_e32 v189, v185, v189
	v_fma_f32 v186, v182, v186, v182
	v_fma_f32 v187, v183, v187, v183
	v_fma_f32 v188, v184, v188, v184
	v_fma_f32 v189, v185, v189, v185
	v_mul_f32_e32 v186, 0xbfcc422a, v186
	v_mul_f32_e32 v187, 0xbfcc422a, v187
	v_mul_f32_e32 v188, 0xbfcc422a, v188
	v_mul_f32_e32 v189, 0xbfcc422a, v189
	v_mul_f32_e32 v186, 0x3fb8aa3b, v186
	v_mul_f32_e32 v187, 0x3fb8aa3b, v187
	v_mul_f32_e32 v188, 0x3fb8aa3b, v188
	v_mul_f32_e32 v189, 0x3fb8aa3b, v189
	v_exp_f32_e32 v186, v186
	v_exp_f32_e32 v187, v187
	v_exp_f32_e32 v188, v188
	v_exp_f32_e32 v189, v189
	v_add_f32_e32 v186, 1.0, v186
	v_add_f32_e32 v187, 1.0, v187
	v_add_f32_e32 v188, 1.0, v188
	v_add_f32_e32 v189, 1.0, v189
	v_rcp_f32_e32 v186, v186
	v_rcp_f32_e32 v187, v187
	v_rcp_f32_e32 v188, v188
	v_rcp_f32_e32 v189, v189
	v_mul_f32_e32 v182, v182, v186
	v_mul_f32_e32 v183, v183, v187
	v_mul_f32_e32 v184, v184, v188
	v_mul_f32_e32 v185, v185, v189
	v_cvt_pk_bf16_f32 v148, v182, v183
	v_cvt_pk_bf16_f32 v149, v184, v185
	global_store_dwordx2 v156, v[148:149], s[12:13]
	ds_read_b128 v[124:127], v152 offset:4352
	ds_read_b128 v[128:131], v152 offset:4416
	ds_read_b128 v[132:135], v152 offset:4480
	ds_read_b128 v[136:139], v152 offset:4544
	s_waitcnt lgkmcnt(3)
	v_mfma_f32_16x16x32_bf16 v[140:143], v[100:103], v[124:127], 0
	s_waitcnt lgkmcnt(2)
	v_mfma_f32_16x16x32_bf16 v[140:143], v[104:107], v[128:131], v[140:143]
	s_waitcnt lgkmcnt(1)
	v_mfma_f32_16x16x32_bf16 v[140:143], v[108:111], v[132:135], v[140:143]
	s_waitcnt lgkmcnt(0)
	v_mfma_f32_16x16x32_bf16 v[140:143], v[112:115], v[136:139], v[140:143]
	s_nop 9
	s_waitcnt vmcnt(9)
	v_add_f32_e32 v182, v176, v140
	v_add_f32_e32 v183, v177, v141
	v_add_f32_e32 v184, v178, v142
	v_add_f32_e32 v185, v179, v143
	v_lshlrev_b32_e32 v186, 16, v4
	v_and_b32_e32 v187, 0xffff0000, v4
	v_lshlrev_b32_e32 v188, 16, v5
	v_and_b32_e32 v189, 0xffff0000, v5
	v_fmac_f32_e32 v182, v164, v186
	v_fmac_f32_e32 v183, v165, v187
	v_fmac_f32_e32 v184, v166, v188
	v_fmac_f32_e32 v185, v167, v189
	v_mul_f32_e32 v186, 0x3d372713, v182
	v_mul_f32_e32 v187, 0x3d372713, v183
	v_mul_f32_e32 v188, 0x3d372713, v184
	v_mul_f32_e32 v189, 0x3d372713, v185
	v_mul_f32_e32 v186, v182, v186
	v_mul_f32_e32 v187, v183, v187
	v_mul_f32_e32 v188, v184, v188
	v_mul_f32_e32 v189, v185, v189
	v_fma_f32 v186, v182, v186, v182
	v_fma_f32 v187, v183, v187, v183
	v_fma_f32 v188, v184, v188, v184
	v_fma_f32 v189, v185, v189, v185
	v_mul_f32_e32 v186, 0xbfcc422a, v186
	v_mul_f32_e32 v187, 0xbfcc422a, v187
	v_mul_f32_e32 v188, 0xbfcc422a, v188
	v_mul_f32_e32 v189, 0xbfcc422a, v189
	v_mul_f32_e32 v186, 0x3fb8aa3b, v186
	v_mul_f32_e32 v187, 0x3fb8aa3b, v187
	v_mul_f32_e32 v188, 0x3fb8aa3b, v188
	v_mul_f32_e32 v189, 0x3fb8aa3b, v189
	v_exp_f32_e32 v186, v186
	v_exp_f32_e32 v187, v187
	v_exp_f32_e32 v188, v188
	v_exp_f32_e32 v189, v189
	v_add_f32_e32 v186, 1.0, v186
	v_add_f32_e32 v187, 1.0, v187
	v_add_f32_e32 v188, 1.0, v188
	v_add_f32_e32 v189, 1.0, v189
	v_rcp_f32_e32 v186, v186
	v_rcp_f32_e32 v187, v187
	v_rcp_f32_e32 v188, v188
	v_rcp_f32_e32 v189, v189
	v_mul_f32_e32 v182, v182, v186
	v_mul_f32_e32 v183, v183, v187
	v_mul_f32_e32 v184, v184, v188
	v_mul_f32_e32 v185, v185, v189
	v_cvt_pk_bf16_f32 v148, v182, v183
	v_cvt_pk_bf16_f32 v149, v184, v185
	global_store_dwordx2 v159, v[148:149], s[12:13]
	s_sub_u32 s12, s12, 65536
	s_subb_u32 s13, s13, 0
	s_add_u32 s14, s14, 2
	s_cmp_lt_u32 s14, 32
	s_cbranch_scc1 .Lssm_tileB_d1m0
	s_waitcnt vmcnt(0) lgkmcnt(0)
.Lssm_lat_join:
	s_branch .Lssm_done

.Lssm_tile_d1m2:
	s_waitcnt vmcnt(7)
	v_mfma_f32_32x32x16_bf16 v[16:31], v[80:83], v[84:87], 0
	v_mfma_f32_32x32x16_bf16 v[32:47], v[80:83], v[88:91], 0
	v_mfma_f32_32x32x16_bf16 v[48:63], v[80:83], v[92:95], 0
	v_mfma_f32_32x32x16_bf16 v[64:79], v[80:83], v[96:99], 0
	v_add_u32_e32 v171, s36, v155
	global_load_dwordx2 v[2:3], v154, s[34:35]
	global_load_dwordx2 v[4:5], v158, s[34:35]
	s_nop 11
	global_load_dwordx4 v[80:83], v150, s[10:11]
	s_sub_u32 s34, s34, 196608
	s_subb_u32 s35, s35, 0
	s_sub_u32 s10, s10, 196608
	s_subb_u32 s11, s11, 0
	v_permlane32_swap_b32_e32 v16, v48
	v_permlane32_swap_b32_e32 v17, v49
	v_permlane32_swap_b32_e32 v18, v50
	v_permlane32_swap_b32_e32 v19, v51
	v_permlane32_swap_b32_e32 v20, v52
	v_permlane32_swap_b32_e32 v21, v53
	v_permlane32_swap_b32_e32 v22, v54
	v_permlane32_swap_b32_e32 v23, v55
	v_permlane32_swap_b32_e32 v24, v56
	v_permlane32_swap_b32_e32 v25, v57
	v_permlane32_swap_b32_e32 v26, v58
	v_permlane32_swap_b32_e32 v27, v59
	v_permlane32_swap_b32_e32 v28, v60
	v_permlane32_swap_b32_e32 v29, v61
	v_permlane32_swap_b32_e32 v30, v62
	v_permlane32_swap_b32_e32 v31, v63
	v_permlane32_swap_b32_e32 v32, v64
	v_permlane32_swap_b32_e32 v33, v65
	v_permlane32_swap_b32_e32 v34, v66
	v_permlane32_swap_b32_e32 v35, v67
	v_permlane32_swap_b32_e32 v36, v68
	v_permlane32_swap_b32_e32 v37, v69
	v_permlane32_swap_b32_e32 v38, v70
	v_permlane32_swap_b32_e32 v39, v71
	v_permlane32_swap_b32_e32 v40, v72
	v_permlane32_swap_b32_e32 v41, v73
	v_permlane32_swap_b32_e32 v42, v74
	v_permlane32_swap_b32_e32 v43, v75
	v_permlane32_swap_b32_e32 v44, v76
	v_permlane32_swap_b32_e32 v45, v77
	v_permlane32_swap_b32_e32 v46, v78
	v_permlane32_swap_b32_e32 v47, v79
	v_fmac_f32_e32 v63, v116, v120
	v_fmac_f32_e32 v79, v118, v121
	v_fmac_f32_dpp v63, v120, v122 quad_perm:[1,0,3,2] row_mask:0xf bank_mask:0xf
	v_fmac_f32_dpp v79, v121, v123 quad_perm:[1,0,3,2] row_mask:0xf bank_mask:0xf
	v_cvt_pk_bf16_f32 v148, v63, v79
	ds_write_b32 v151, v148 offset:8432
	v_fmac_f32_e32 v62, v116, v63
	v_fmac_f32_e32 v78, v118, v79
	v_fmac_f32_dpp v62, v63, v122 quad_perm:[1,0,3,2] row_mask:0xf bank_mask:0xf
	v_fmac_f32_dpp v78, v79, v123 quad_perm:[1,0,3,2] row_mask:0xf bank_mask:0xf
	v_cvt_pk_bf16_f32 v149, v62, v78
	ds_write_b32 v151, v149 offset:8160
	v_fmac_f32_e32 v61, v116, v62
	v_fmac_f32_e32 v77, v118, v78
	v_fmac_f32_dpp v61, v62, v122 quad_perm:[1,0,3,2] row_mask:0xf bank_mask:0xf
	v_fmac_f32_dpp v77, v78, v123 quad_perm:[1,0,3,2] row_mask:0xf bank_mask:0xf
	v_cvt_pk_bf16_f32 v148, v61, v77
	ds_write_b32 v151, v148 offset:7888
	v_fmac_f32_e32 v60, v116, v61
	v_fmac_f32_e32 v76, v118, v77
	v_fmac_f32_dpp v60, v61, v122 quad_perm:[1,0,3,2] row_mask:0xf bank_mask:0xf
	v_fmac_f32_dpp v76, v77, v123 quad_perm:[1,0,3,2] row_mask:0xf bank_mask:0xf
	v_cvt_pk_bf16_f32 v149, v60, v76
	ds_write_b32 v151, v149 offset:7616
	v_fmac_f32_e32 v31, v116, v60
	v_fmac_f32_e32 v47, v118, v76
	v_fmac_f32_dpp v31, v60, v122 quad_perm:[1,0,3,2] row_mask:0xf bank_mask:0xf
	v_fmac_f32_dpp v47, v76, v123 quad_perm:[1,0,3,2] row_mask:0xf bank_mask:0xf
	v_cvt_pk_bf16_f32 v148, v31, v47
	ds_write_b32 v151, v148 offset:7344
	v_fmac_f32_e32 v30, v116, v31
	v_fmac_f32_e32 v46, v118, v47
	v_fmac_f32_dpp v30, v31, v122 quad_perm:[1,0,3,2] row_mask:0xf bank_mask:0xf
	v_fmac_f32_dpp v46, v47, v123 quad_perm:[1,0,3,2] row_mask:0xf bank_mask:0xf
	v_cvt_pk_bf16_f32 v149, v30, v46
	ds_write_b32 v151, v149 offset:7072
	v_fmac_f32_e32 v29, v116, v30
	v_fmac_f32_e32 v45, v118, v46
	v_fmac_f32_dpp v29, v30, v122 quad_perm:[1,0,3,2] row_mask:0xf bank_mask:0xf
	v_fmac_f32_dpp v45, v46, v123 quad_perm:[1,0,3,2] row_mask:0xf bank_mask:0xf
	v_cvt_pk_bf16_f32 v148, v29, v45
	ds_write_b32 v151, v148 offset:6800
	v_fmac_f32_e32 v28, v116, v29
	v_fmac_f32_e32 v44, v118, v45
	v_fmac_f32_dpp v28, v29, v122 quad_perm:[1,0,3,2] row_mask:0xf bank_mask:0xf
	v_fmac_f32_dpp v44, v45, v123 quad_perm:[1,0,3,2] row_mask:0xf bank_mask:0xf
	v_cvt_pk_bf16_f32 v149, v28, v44
	ds_write_b32 v151, v149 offset:6528
	v_fmac_f32_e32 v59, v116, v28
	v_fmac_f32_e32 v75, v118, v44
	v_fmac_f32_dpp v59, v28, v122 quad_perm:[1,0,3,2] row_mask:0xf bank_mask:0xf
	v_fmac_f32_dpp v75, v44, v123 quad_perm:[1,0,3,2] row_mask:0xf bank_mask:0xf
	v_cvt_pk_bf16_f32 v148, v59, v75
	ds_write_b32 v151, v148 offset:6256
	v_fmac_f32_e32 v58, v116, v59
	v_fmac_f32_e32 v74, v118, v75
	v_fmac_f32_dpp v58, v59, v122 quad_perm:[1,0,3,2] row_mask:0xf bank_mask:0xf
	v_fmac_f32_dpp v74, v75, v123 quad_perm:[1,0,3,2] row_mask:0xf bank_mask:0xf
	v_cvt_pk_bf16_f32 v149, v58, v74
	ds_write_b32 v151, v149 offset:5984
	v_fmac_f32_e32 v57, v116, v58
	v_fmac_f32_e32 v73, v118, v74
	v_fmac_f32_dpp v57, v58, v122 quad_perm:[1,0,3,2] row_mask:0xf bank_mask:0xf
	v_fmac_f32_dpp v73, v74, v123 quad_perm:[1,0,3,2] row_mask:0xf bank_mask:0xf
	v_cvt_pk_bf16_f32 v148, v57, v73
	ds_write_b32 v151, v148 offset:5712
	v_fmac_f32_e32 v56, v116, v57
	v_fmac_f32_e32 v72, v118, v73
	v_fmac_f32_dpp v56, v57, v122 quad_perm:[1,0,3,2] row_mask:0xf bank_mask:0xf
	v_fmac_f32_dpp v72, v73, v123 quad_perm:[1,0,3,2] row_mask:0xf bank_mask:0xf
	v_cvt_pk_bf16_f32 v149, v56, v72
	ds_write_b32 v151, v149 offset:5440
	v_fmac_f32_e32 v27, v116, v56
	v_fmac_f32_e32 v43, v118, v72
	v_fmac_f32_dpp v27, v56, v122 quad_perm:[1,0,3,2] row_mask:0xf bank_mask:0xf
	v_fmac_f32_dpp v43, v72, v123 quad_perm:[1,0,3,2] row_mask:0xf bank_mask:0xf
	v_cvt_pk_bf16_f32 v148, v27, v43
	ds_write_b32 v151, v148 offset:5168
	v_fmac_f32_e32 v26, v116, v27
	v_fmac_f32_e32 v42, v118, v43
	v_fmac_f32_dpp v26, v27, v122 quad_perm:[1,0,3,2] row_mask:0xf bank_mask:0xf
	v_fmac_f32_dpp v42, v43, v123 quad_perm:[1,0,3,2] row_mask:0xf bank_mask:0xf
	v_cvt_pk_bf16_f32 v149, v26, v42
	ds_write_b32 v151, v149 offset:4896
	v_fmac_f32_e32 v25, v116, v26
	v_fmac_f32_e32 v41, v118, v42
	v_fmac_f32_dpp v25, v26, v122 quad_perm:[1,0,3,2] row_mask:0xf bank_mask:0xf
	v_fmac_f32_dpp v41, v42, v123 quad_perm:[1,0,3,2] row_mask:0xf bank_mask:0xf
	v_cvt_pk_bf16_f32 v148, v25, v41
	ds_write_b32 v151, v148 offset:4624
	v_fmac_f32_e32 v24, v116, v25
	v_fmac_f32_e32 v40, v118, v41
	v_fmac_f32_dpp v24, v25, v122 quad_perm:[1,0,3,2] row_mask:0xf bank_mask:0xf
	v_fmac_f32_dpp v40, v41, v123 quad_perm:[1,0,3,2] row_mask:0xf bank_mask:0xf
	v_cvt_pk_bf16_f32 v149, v24, v40
	ds_write_b32 v151, v149 offset:4352
	v_fmac_f32_e32 v55, v116, v24
	v_fmac_f32_e32 v71, v118, v40
	v_fmac_f32_dpp v55, v24, v122 quad_perm:[1,0,3,2] row_mask:0xf bank_mask:0xf
	v_fmac_f32_dpp v71, v40, v123 quad_perm:[1,0,3,2] row_mask:0xf bank_mask:0xf
	v_cvt_pk_bf16_f32 v148, v55, v71
	ds_write_b32 v151, v148 offset:4080
	v_fmac_f32_e32 v54, v116, v55
	v_fmac_f32_e32 v70, v118, v71
	v_fmac_f32_dpp v54, v55, v122 quad_perm:[1,0,3,2] row_mask:0xf bank_mask:0xf
	v_fmac_f32_dpp v70, v71, v123 quad_perm:[1,0,3,2] row_mask:0xf bank_mask:0xf
	v_cvt_pk_bf16_f32 v149, v54, v70
	ds_write_b32 v151, v149 offset:3808
	v_fmac_f32_e32 v53, v116, v54
	v_fmac_f32_e32 v69, v118, v70
	v_fmac_f32_dpp v53, v54, v122 quad_perm:[1,0,3,2] row_mask:0xf bank_mask:0xf
	v_fmac_f32_dpp v69, v70, v123 quad_perm:[1,0,3,2] row_mask:0xf bank_mask:0xf
	v_cvt_pk_bf16_f32 v148, v53, v69
	ds_write_b32 v151, v148 offset:3536
	v_fmac_f32_e32 v52, v116, v53
	v_fmac_f32_e32 v68, v118, v69
	v_fmac_f32_dpp v52, v53, v122 quad_perm:[1,0,3,2] row_mask:0xf bank_mask:0xf
	v_fmac_f32_dpp v68, v69, v123 quad_perm:[1,0,3,2] row_mask:0xf bank_mask:0xf
	v_cvt_pk_bf16_f32 v149, v52, v68
	ds_write_b32 v151, v149 offset:3264
	v_fmac_f32_e32 v23, v116, v52
	v_fmac_f32_e32 v39, v118, v68
	v_fmac_f32_dpp v23, v52, v122 quad_perm:[1,0,3,2] row_mask:0xf bank_mask:0xf
	v_fmac_f32_dpp v39, v68, v123 quad_perm:[1,0,3,2] row_mask:0xf bank_mask:0xf
	v_cvt_pk_bf16_f32 v148, v23, v39
	ds_write_b32 v151, v148 offset:2992
	v_fmac_f32_e32 v22, v116, v23
	v_fmac_f32_e32 v38, v118, v39
	v_fmac_f32_dpp v22, v23, v122 quad_perm:[1,0,3,2] row_mask:0xf bank_mask:0xf
	v_fmac_f32_dpp v38, v39, v123 quad_perm:[1,0,3,2] row_mask:0xf bank_mask:0xf
	v_cvt_pk_bf16_f32 v149, v22, v38
	ds_write_b32 v151, v149 offset:2720
	v_fmac_f32_e32 v21, v116, v22
	v_fmac_f32_e32 v37, v118, v38
	v_fmac_f32_dpp v21, v22, v122 quad_perm:[1,0,3,2] row_mask:0xf bank_mask:0xf
	v_fmac_f32_dpp v37, v38, v123 quad_perm:[1,0,3,2] row_mask:0xf bank_mask:0xf
	v_cvt_pk_bf16_f32 v148, v21, v37
	ds_write_b32 v151, v148 offset:2448
	v_fmac_f32_e32 v20, v116, v21
	v_fmac_f32_e32 v36, v118, v37
	v_fmac_f32_dpp v20, v21, v122 quad_perm:[1,0,3,2] row_mask:0xf bank_mask:0xf
	v_fmac_f32_dpp v36, v37, v123 quad_perm:[1,0,3,2] row_mask:0xf bank_mask:0xf
	v_cvt_pk_bf16_f32 v149, v20, v36
	ds_write_b32 v151, v149 offset:2176
	v_fmac_f32_e32 v51, v116, v20
	v_fmac_f32_e32 v67, v118, v36
	v_fmac_f32_dpp v51, v20, v122 quad_perm:[1,0,3,2] row_mask:0xf bank_mask:0xf
	v_fmac_f32_dpp v67, v36, v123 quad_perm:[1,0,3,2] row_mask:0xf bank_mask:0xf
	v_cvt_pk_bf16_f32 v148, v51, v67
	ds_write_b32 v151, v148 offset:1904
	v_fmac_f32_e32 v50, v116, v51
	v_fmac_f32_e32 v66, v118, v67
	v_fmac_f32_dpp v50, v51, v122 quad_perm:[1,0,3,2] row_mask:0xf bank_mask:0xf
	v_fmac_f32_dpp v66, v67, v123 quad_perm:[1,0,3,2] row_mask:0xf bank_mask:0xf
	v_cvt_pk_bf16_f32 v149, v50, v66
	ds_write_b32 v151, v149 offset:1632
	v_fmac_f32_e32 v49, v116, v50
	v_fmac_f32_e32 v65, v118, v66
	v_fmac_f32_dpp v49, v50, v122 quad_perm:[1,0,3,2] row_mask:0xf bank_mask:0xf
	v_fmac_f32_dpp v65, v66, v123 quad_perm:[1,0,3,2] row_mask:0xf bank_mask:0xf
	v_cvt_pk_bf16_f32 v148, v49, v65
	ds_write_b32 v151, v148 offset:1360
	v_fmac_f32_e32 v48, v116, v49
	v_fmac_f32_e32 v64, v118, v65
	v_fmac_f32_dpp v48, v49, v122 quad_perm:[1,0,3,2] row_mask:0xf bank_mask:0xf
	v_fmac_f32_dpp v64, v65, v123 quad_perm:[1,0,3,2] row_mask:0xf bank_mask:0xf
	v_cvt_pk_bf16_f32 v149, v48, v64
	ds_write_b32 v151, v149 offset:1088
	v_fmac_f32_e32 v19, v116, v48
	v_fmac_f32_e32 v35, v118, v64
	v_fmac_f32_dpp v19, v48, v122 quad_perm:[1,0,3,2] row_mask:0xf bank_mask:0xf
	v_fmac_f32_dpp v35, v64, v123 quad_perm:[1,0,3,2] row_mask:0xf bank_mask:0xf
	v_cvt_pk_bf16_f32 v148, v19, v35
	ds_write_b32 v151, v148 offset:816
	v_fmac_f32_e32 v18, v116, v19
	v_fmac_f32_e32 v34, v118, v35
	v_fmac_f32_dpp v18, v19, v122 quad_perm:[1,0,3,2] row_mask:0xf bank_mask:0xf
	v_fmac_f32_dpp v34, v35, v123 quad_perm:[1,0,3,2] row_mask:0xf bank_mask:0xf
	v_cvt_pk_bf16_f32 v149, v18, v34
	ds_write_b32 v151, v149 offset:544
	v_fmac_f32_e32 v17, v116, v18
	v_fmac_f32_e32 v33, v118, v34
	v_fmac_f32_dpp v17, v18, v122 quad_perm:[1,0,3,2] row_mask:0xf bank_mask:0xf
	v_fmac_f32_dpp v33, v34, v123 quad_perm:[1,0,3,2] row_mask:0xf bank_mask:0xf
	v_cvt_pk_bf16_f32 v148, v17, v33
	ds_write_b32 v151, v148 offset:272
	v_fmac_f32_e32 v16, v116, v17
	v_fmac_f32_e32 v32, v118, v33
	v_fmac_f32_dpp v16, v17, v122 quad_perm:[1,0,3,2] row_mask:0xf bank_mask:0xf
	v_fmac_f32_dpp v32, v33, v123 quad_perm:[1,0,3,2] row_mask:0xf bank_mask:0xf
	v_cvt_pk_bf16_f32 v149, v16, v32
	ds_write_b32 v151, v149
	v_mov_b32_e32 v120, v16
	v_mov_b32_e32 v121, v32
	ds_read_b128 v[124:127], v152
	ds_read_b128 v[128:131], v152 offset:64
	ds_read_b128 v[132:135], v152 offset:128
	ds_read_b128 v[136:139], v152 offset:192
	ds_read_b64 v[168:169], v171
	s_waitcnt lgkmcnt(4)
	v_mfma_f32_16x16x32_bf16 v[140:143], v[100:103], v[124:127], 0
	s_waitcnt lgkmcnt(3)
	v_mfma_f32_16x16x32_bf16 v[140:143], v[104:107], v[128:131], v[140:143]
	s_waitcnt lgkmcnt(2)
	v_mfma_f32_16x16x32_bf16 v[140:143], v[108:111], v[132:135], v[140:143]
	s_waitcnt lgkmcnt(1)
	v_mfma_f32_16x16x32_bf16 v[140:143], v[112:115], v[136:139], v[140:143]
	s_nop 9
	s_waitcnt vmcnt(6) lgkmcnt(0)
	v_lshlrev_b32_e32 v182, 16, v168
	v_and_b32_e32 v183, 0xffff0000, v168
	v_lshlrev_b32_e32 v184, 16, v169
	v_and_b32_e32 v185, 0xffff0000, v169
	v_add_f32_e32 v182, v182, v140
	v_add_f32_e32 v183, v183, v141
	v_add_f32_e32 v184, v184, v142
	v_add_f32_e32 v185, v185, v143
	v_lshlrev_b32_e32 v186, 16, v160
	v_and_b32_e32 v187, 0xffff0000, v160
	v_lshlrev_b32_e32 v188, 16, v161
	v_and_b32_e32 v189, 0xffff0000, v161
	v_fmac_f32_e32 v182, v164, v186
	v_fmac_f32_e32 v183, v165, v187
	v_fmac_f32_e32 v184, v166, v188
	v_fmac_f32_e32 v185, v167, v189
	v_mul_f32_e32 v186, 0x3d372713, v182
	v_mul_f32_e32 v187, 0x3d372713, v183
	v_mul_f32_e32 v188, 0x3d372713, v184
	v_mul_f32_e32 v189, 0x3d372713, v185
	v_mul_f32_e32 v186, v182, v186
	v_mul_f32_e32 v187, v183, v187
	v_mul_f32_e32 v188, v184, v188
	v_mul_f32_e32 v189, v185, v189
	v_fma_f32 v186, v182, v186, v182
	v_fma_f32 v187, v183, v187, v183
	v_fma_f32 v188, v184, v188, v184
	v_fma_f32 v189, v185, v189, v185
	v_mul_f32_e32 v186, 0xbfcc422a, v186
	v_mul_f32_e32 v187, 0xbfcc422a, v187
	v_mul_f32_e32 v188, 0xbfcc422a, v188
	v_mul_f32_e32 v189, 0xbfcc422a, v189
	v_mul_f32_e32 v186, 0x3fb8aa3b, v186
	v_mul_f32_e32 v187, 0x3fb8aa3b, v187
	v_mul_f32_e32 v188, 0x3fb8aa3b, v188
	v_mul_f32_e32 v189, 0x3fb8aa3b, v189
	v_exp_f32_e32 v186, v186
	v_exp_f32_e32 v187, v187
	v_exp_f32_e32 v188, v188
	v_exp_f32_e32 v189, v189
	v_add_f32_e32 v186, 1.0, v186
	v_add_f32_e32 v187, 1.0, v187
	v_add_f32_e32 v188, 1.0, v188
	v_add_f32_e32 v189, 1.0, v189
	v_rcp_f32_e32 v186, v186
	v_rcp_f32_e32 v187, v187
	v_rcp_f32_e32 v188, v188
	v_rcp_f32_e32 v189, v189
	v_mul_f32_e32 v182, v182, v186
	v_mul_f32_e32 v183, v183, v187
	v_mul_f32_e32 v184, v184, v188
	v_mul_f32_e32 v185, v185, v189
	v_cvt_pk_bf16_f32 v148, v182, v183
	v_cvt_pk_bf16_f32 v149, v184, v185
	global_store_dwordx2 v156, v[148:149], s[12:13]
	ds_read_b128 v[124:127], v152 offset:4352
	ds_read_b128 v[128:131], v152 offset:4416
	ds_read_b128 v[132:135], v152 offset:4480
	ds_read_b128 v[136:139], v152 offset:4544
	ds_read_b64 v[168:169], v171 offset:512
	s_waitcnt lgkmcnt(4)
	v_mfma_f32_16x16x32_bf16 v[140:143], v[100:103], v[124:127], 0
	s_waitcnt lgkmcnt(3)
	v_mfma_f32_16x16x32_bf16 v[140:143], v[104:107], v[128:131], v[140:143]
	s_waitcnt lgkmcnt(2)
	v_mfma_f32_16x16x32_bf16 v[140:143], v[108:111], v[132:135], v[140:143]
	s_waitcnt lgkmcnt(1)
	v_mfma_f32_16x16x32_bf16 v[140:143], v[112:115], v[136:139], v[140:143]
	s_nop 9
	s_waitcnt vmcnt(7) lgkmcnt(0)
	v_lshlrev_b32_e32 v182, 16, v168
	v_and_b32_e32 v183, 0xffff0000, v168
	v_lshlrev_b32_e32 v184, 16, v169
	v_and_b32_e32 v185, 0xffff0000, v169
	v_add_f32_e32 v182, v182, v140
	v_add_f32_e32 v183, v183, v141
	v_add_f32_e32 v184, v184, v142
	v_add_f32_e32 v185, v185, v143
	v_lshlrev_b32_e32 v186, 16, v162
	v_and_b32_e32 v187, 0xffff0000, v162
	v_lshlrev_b32_e32 v188, 16, v163
	v_and_b32_e32 v189, 0xffff0000, v163
	v_fmac_f32_e32 v182, v164, v186
	v_fmac_f32_e32 v183, v165, v187
	v_fmac_f32_e32 v184, v166, v188
	v_fmac_f32_e32 v185, v167, v189
	v_mul_f32_e32 v186, 0x3d372713, v182
	v_mul_f32_e32 v187, 0x3d372713, v183
	v_mul_f32_e32 v188, 0x3d372713, v184
	v_mul_f32_e32 v189, 0x3d372713, v185
	v_mul_f32_e32 v186, v182, v186
	v_mul_f32_e32 v187, v183, v187
	v_mul_f32_e32 v188, v184, v188
	v_mul_f32_e32 v189, v185, v189
	v_fma_f32 v186, v182, v186, v182
	v_fma_f32 v187, v183, v187, v183
	v_fma_f32 v188, v184, v188, v184
	v_fma_f32 v189, v185, v189, v185
	v_mul_f32_e32 v186, 0xbfcc422a, v186
	v_mul_f32_e32 v187, 0xbfcc422a, v187
	v_mul_f32_e32 v188, 0xbfcc422a, v188
	v_mul_f32_e32 v189, 0xbfcc422a, v189
	v_mul_f32_e32 v186, 0x3fb8aa3b, v186
	v_mul_f32_e32 v187, 0x3fb8aa3b, v187
	v_mul_f32_e32 v188, 0x3fb8aa3b, v188
	v_mul_f32_e32 v189, 0x3fb8aa3b, v189
	v_exp_f32_e32 v186, v186
	v_exp_f32_e32 v187, v187
	v_exp_f32_e32 v188, v188
	v_exp_f32_e32 v189, v189
	v_add_f32_e32 v186, 1.0, v186
	v_add_f32_e32 v187, 1.0, v187
	v_add_f32_e32 v188, 1.0, v188
	v_add_f32_e32 v189, 1.0, v189
	v_rcp_f32_e32 v186, v186
	v_rcp_f32_e32 v187, v187
	v_rcp_f32_e32 v188, v188
	v_rcp_f32_e32 v189, v189
	v_mul_f32_e32 v182, v182, v186
	v_mul_f32_e32 v183, v183, v187
	v_mul_f32_e32 v184, v184, v188
	v_mul_f32_e32 v185, v185, v189
	v_cvt_pk_bf16_f32 v148, v182, v183
	v_cvt_pk_bf16_f32 v149, v184, v185
	global_store_dwordx2 v159, v[148:149], s[12:13]
	s_sub_u32 s12, s12, 65536
	s_subb_u32 s13, s13, 0
	s_sub_u32 s36, s36, 1024
	s_waitcnt vmcnt(7)
	v_mfma_f32_32x32x16_bf16 v[16:31], v[144:147], v[84:87], 0
	v_mfma_f32_32x32x16_bf16 v[32:47], v[144:147], v[88:91], 0
	v_mfma_f32_32x32x16_bf16 v[48:63], v[144:147], v[92:95], 0
	v_mfma_f32_32x32x16_bf16 v[64:79], v[144:147], v[96:99], 0
	v_add_u32_e32 v171, s36, v155
	global_load_dwordx2 v[160:161], v154, s[34:35]
	global_load_dwordx2 v[162:163], v158, s[34:35]
	s_nop 11
	global_load_dwordx4 v[144:147], v150, s[10:11]
	s_sub_u32 s34, s34, 196608
	s_subb_u32 s35, s35, 0
	s_sub_u32 s10, s10, 196608
	s_subb_u32 s11, s11, 0
	v_permlane32_swap_b32_e32 v16, v48
	v_permlane32_swap_b32_e32 v17, v49
	v_permlane32_swap_b32_e32 v18, v50
	v_permlane32_swap_b32_e32 v19, v51
	v_permlane32_swap_b32_e32 v20, v52
	v_permlane32_swap_b32_e32 v21, v53
	v_permlane32_swap_b32_e32 v22, v54
	v_permlane32_swap_b32_e32 v23, v55
	v_permlane32_swap_b32_e32 v24, v56
	v_permlane32_swap_b32_e32 v25, v57
	v_permlane32_swap_b32_e32 v26, v58
	v_permlane32_swap_b32_e32 v27, v59
	v_permlane32_swap_b32_e32 v28, v60
	v_permlane32_swap_b32_e32 v29, v61
	v_permlane32_swap_b32_e32 v30, v62
	v_permlane32_swap_b32_e32 v31, v63
	v_permlane32_swap_b32_e32 v32, v64
	v_permlane32_swap_b32_e32 v33, v65
	v_permlane32_swap_b32_e32 v34, v66
	v_permlane32_swap_b32_e32 v35, v67
	v_permlane32_swap_b32_e32 v36, v68
	v_permlane32_swap_b32_e32 v37, v69
	v_permlane32_swap_b32_e32 v38, v70
	v_permlane32_swap_b32_e32 v39, v71
	v_permlane32_swap_b32_e32 v40, v72
	v_permlane32_swap_b32_e32 v41, v73
	v_permlane32_swap_b32_e32 v42, v74
	v_permlane32_swap_b32_e32 v43, v75
	v_permlane32_swap_b32_e32 v44, v76
	v_permlane32_swap_b32_e32 v45, v77
	v_permlane32_swap_b32_e32 v46, v78
	v_permlane32_swap_b32_e32 v47, v79
	v_fmac_f32_e32 v63, v116, v120
	v_fmac_f32_e32 v79, v118, v121
	v_fmac_f32_dpp v63, v120, v122 quad_perm:[1,0,3,2] row_mask:0xf bank_mask:0xf
	v_fmac_f32_dpp v79, v121, v123 quad_perm:[1,0,3,2] row_mask:0xf bank_mask:0xf
	v_cvt_pk_bf16_f32 v148, v63, v79
	ds_write_b32 v151, v148 offset:8432
	v_fmac_f32_e32 v62, v116, v63
	v_fmac_f32_e32 v78, v118, v79
	v_fmac_f32_dpp v62, v63, v122 quad_perm:[1,0,3,2] row_mask:0xf bank_mask:0xf
	v_fmac_f32_dpp v78, v79, v123 quad_perm:[1,0,3,2] row_mask:0xf bank_mask:0xf
	v_cvt_pk_bf16_f32 v149, v62, v78
	ds_write_b32 v151, v149 offset:8160
	v_fmac_f32_e32 v61, v116, v62
	v_fmac_f32_e32 v77, v118, v78
	v_fmac_f32_dpp v61, v62, v122 quad_perm:[1,0,3,2] row_mask:0xf bank_mask:0xf
	v_fmac_f32_dpp v77, v78, v123 quad_perm:[1,0,3,2] row_mask:0xf bank_mask:0xf
	v_cvt_pk_bf16_f32 v148, v61, v77
	ds_write_b32 v151, v148 offset:7888
	v_fmac_f32_e32 v60, v116, v61
	v_fmac_f32_e32 v76, v118, v77
	v_fmac_f32_dpp v60, v61, v122 quad_perm:[1,0,3,2] row_mask:0xf bank_mask:0xf
	v_fmac_f32_dpp v76, v77, v123 quad_perm:[1,0,3,2] row_mask:0xf bank_mask:0xf
	v_cvt_pk_bf16_f32 v149, v60, v76
	ds_write_b32 v151, v149 offset:7616
	v_fmac_f32_e32 v31, v116, v60
	v_fmac_f32_e32 v47, v118, v76
	v_fmac_f32_dpp v31, v60, v122 quad_perm:[1,0,3,2] row_mask:0xf bank_mask:0xf
	v_fmac_f32_dpp v47, v76, v123 quad_perm:[1,0,3,2] row_mask:0xf bank_mask:0xf
	v_cvt_pk_bf16_f32 v148, v31, v47
	ds_write_b32 v151, v148 offset:7344
	v_fmac_f32_e32 v30, v116, v31
	v_fmac_f32_e32 v46, v118, v47
	v_fmac_f32_dpp v30, v31, v122 quad_perm:[1,0,3,2] row_mask:0xf bank_mask:0xf
	v_fmac_f32_dpp v46, v47, v123 quad_perm:[1,0,3,2] row_mask:0xf bank_mask:0xf
	v_cvt_pk_bf16_f32 v149, v30, v46
	ds_write_b32 v151, v149 offset:7072
	v_fmac_f32_e32 v29, v116, v30
	v_fmac_f32_e32 v45, v118, v46
	v_fmac_f32_dpp v29, v30, v122 quad_perm:[1,0,3,2] row_mask:0xf bank_mask:0xf
	v_fmac_f32_dpp v45, v46, v123 quad_perm:[1,0,3,2] row_mask:0xf bank_mask:0xf
	v_cvt_pk_bf16_f32 v148, v29, v45
	ds_write_b32 v151, v148 offset:6800
	v_fmac_f32_e32 v28, v116, v29
	v_fmac_f32_e32 v44, v118, v45
	v_fmac_f32_dpp v28, v29, v122 quad_perm:[1,0,3,2] row_mask:0xf bank_mask:0xf
	v_fmac_f32_dpp v44, v45, v123 quad_perm:[1,0,3,2] row_mask:0xf bank_mask:0xf
	v_cvt_pk_bf16_f32 v149, v28, v44
	ds_write_b32 v151, v149 offset:6528
	v_fmac_f32_e32 v59, v116, v28
	v_fmac_f32_e32 v75, v118, v44
	v_fmac_f32_dpp v59, v28, v122 quad_perm:[1,0,3,2] row_mask:0xf bank_mask:0xf
	v_fmac_f32_dpp v75, v44, v123 quad_perm:[1,0,3,2] row_mask:0xf bank_mask:0xf
	v_cvt_pk_bf16_f32 v148, v59, v75
	ds_write_b32 v151, v148 offset:6256
	v_fmac_f32_e32 v58, v116, v59
	v_fmac_f32_e32 v74, v118, v75
	v_fmac_f32_dpp v58, v59, v122 quad_perm:[1,0,3,2] row_mask:0xf bank_mask:0xf
	v_fmac_f32_dpp v74, v75, v123 quad_perm:[1,0,3,2] row_mask:0xf bank_mask:0xf
	v_cvt_pk_bf16_f32 v149, v58, v74
	ds_write_b32 v151, v149 offset:5984
	v_fmac_f32_e32 v57, v116, v58
	v_fmac_f32_e32 v73, v118, v74
	v_fmac_f32_dpp v57, v58, v122 quad_perm:[1,0,3,2] row_mask:0xf bank_mask:0xf
	v_fmac_f32_dpp v73, v74, v123 quad_perm:[1,0,3,2] row_mask:0xf bank_mask:0xf
	v_cvt_pk_bf16_f32 v148, v57, v73
	ds_write_b32 v151, v148 offset:5712
	v_fmac_f32_e32 v56, v116, v57
	v_fmac_f32_e32 v72, v118, v73
	v_fmac_f32_dpp v56, v57, v122 quad_perm:[1,0,3,2] row_mask:0xf bank_mask:0xf
	v_fmac_f32_dpp v72, v73, v123 quad_perm:[1,0,3,2] row_mask:0xf bank_mask:0xf
	v_cvt_pk_bf16_f32 v149, v56, v72
	ds_write_b32 v151, v149 offset:5440
	v_fmac_f32_e32 v27, v116, v56
	v_fmac_f32_e32 v43, v118, v72
	v_fmac_f32_dpp v27, v56, v122 quad_perm:[1,0,3,2] row_mask:0xf bank_mask:0xf
	v_fmac_f32_dpp v43, v72, v123 quad_perm:[1,0,3,2] row_mask:0xf bank_mask:0xf
	v_cvt_pk_bf16_f32 v148, v27, v43
	ds_write_b32 v151, v148 offset:5168
	v_fmac_f32_e32 v26, v116, v27
	v_fmac_f32_e32 v42, v118, v43
	v_fmac_f32_dpp v26, v27, v122 quad_perm:[1,0,3,2] row_mask:0xf bank_mask:0xf
	v_fmac_f32_dpp v42, v43, v123 quad_perm:[1,0,3,2] row_mask:0xf bank_mask:0xf
	v_cvt_pk_bf16_f32 v149, v26, v42
	ds_write_b32 v151, v149 offset:4896
	v_fmac_f32_e32 v25, v116, v26
	v_fmac_f32_e32 v41, v118, v42
	v_fmac_f32_dpp v25, v26, v122 quad_perm:[1,0,3,2] row_mask:0xf bank_mask:0xf
	v_fmac_f32_dpp v41, v42, v123 quad_perm:[1,0,3,2] row_mask:0xf bank_mask:0xf
	v_cvt_pk_bf16_f32 v148, v25, v41
	ds_write_b32 v151, v148 offset:4624
	v_fmac_f32_e32 v24, v116, v25
	v_fmac_f32_e32 v40, v118, v41
	v_fmac_f32_dpp v24, v25, v122 quad_perm:[1,0,3,2] row_mask:0xf bank_mask:0xf
	v_fmac_f32_dpp v40, v41, v123 quad_perm:[1,0,3,2] row_mask:0xf bank_mask:0xf
	v_cvt_pk_bf16_f32 v149, v24, v40
	ds_write_b32 v151, v149 offset:4352
	v_fmac_f32_e32 v55, v116, v24
	v_fmac_f32_e32 v71, v118, v40
	v_fmac_f32_dpp v55, v24, v122 quad_perm:[1,0,3,2] row_mask:0xf bank_mask:0xf
	v_fmac_f32_dpp v71, v40, v123 quad_perm:[1,0,3,2] row_mask:0xf bank_mask:0xf
	v_cvt_pk_bf16_f32 v148, v55, v71
	ds_write_b32 v151, v148 offset:4080
	v_fmac_f32_e32 v54, v116, v55
	v_fmac_f32_e32 v70, v118, v71
	v_fmac_f32_dpp v54, v55, v122 quad_perm:[1,0,3,2] row_mask:0xf bank_mask:0xf
	v_fmac_f32_dpp v70, v71, v123 quad_perm:[1,0,3,2] row_mask:0xf bank_mask:0xf
	v_cvt_pk_bf16_f32 v149, v54, v70
	ds_write_b32 v151, v149 offset:3808
	v_fmac_f32_e32 v53, v116, v54
	v_fmac_f32_e32 v69, v118, v70
	v_fmac_f32_dpp v53, v54, v122 quad_perm:[1,0,3,2] row_mask:0xf bank_mask:0xf
	v_fmac_f32_dpp v69, v70, v123 quad_perm:[1,0,3,2] row_mask:0xf bank_mask:0xf
	v_cvt_pk_bf16_f32 v148, v53, v69
	ds_write_b32 v151, v148 offset:3536
	v_fmac_f32_e32 v52, v116, v53
	v_fmac_f32_e32 v68, v118, v69
	v_fmac_f32_dpp v52, v53, v122 quad_perm:[1,0,3,2] row_mask:0xf bank_mask:0xf
	v_fmac_f32_dpp v68, v69, v123 quad_perm:[1,0,3,2] row_mask:0xf bank_mask:0xf
	v_cvt_pk_bf16_f32 v149, v52, v68
	ds_write_b32 v151, v149 offset:3264
	v_fmac_f32_e32 v23, v116, v52
	v_fmac_f32_e32 v39, v118, v68
	v_fmac_f32_dpp v23, v52, v122 quad_perm:[1,0,3,2] row_mask:0xf bank_mask:0xf
	v_fmac_f32_dpp v39, v68, v123 quad_perm:[1,0,3,2] row_mask:0xf bank_mask:0xf
	v_cvt_pk_bf16_f32 v148, v23, v39
	ds_write_b32 v151, v148 offset:2992
	v_fmac_f32_e32 v22, v116, v23
	v_fmac_f32_e32 v38, v118, v39
	v_fmac_f32_dpp v22, v23, v122 quad_perm:[1,0,3,2] row_mask:0xf bank_mask:0xf
	v_fmac_f32_dpp v38, v39, v123 quad_perm:[1,0,3,2] row_mask:0xf bank_mask:0xf
	v_cvt_pk_bf16_f32 v149, v22, v38
	ds_write_b32 v151, v149 offset:2720
	v_fmac_f32_e32 v21, v116, v22
	v_fmac_f32_e32 v37, v118, v38
	v_fmac_f32_dpp v21, v22, v122 quad_perm:[1,0,3,2] row_mask:0xf bank_mask:0xf
	v_fmac_f32_dpp v37, v38, v123 quad_perm:[1,0,3,2] row_mask:0xf bank_mask:0xf
	v_cvt_pk_bf16_f32 v148, v21, v37
	ds_write_b32 v151, v148 offset:2448
	v_fmac_f32_e32 v20, v116, v21
	v_fmac_f32_e32 v36, v118, v37
	v_fmac_f32_dpp v20, v21, v122 quad_perm:[1,0,3,2] row_mask:0xf bank_mask:0xf
	v_fmac_f32_dpp v36, v37, v123 quad_perm:[1,0,3,2] row_mask:0xf bank_mask:0xf
	v_cvt_pk_bf16_f32 v149, v20, v36
	ds_write_b32 v151, v149 offset:2176
	v_fmac_f32_e32 v51, v116, v20
	v_fmac_f32_e32 v67, v118, v36
	v_fmac_f32_dpp v51, v20, v122 quad_perm:[1,0,3,2] row_mask:0xf bank_mask:0xf
	v_fmac_f32_dpp v67, v36, v123 quad_perm:[1,0,3,2] row_mask:0xf bank_mask:0xf
	v_cvt_pk_bf16_f32 v148, v51, v67
	ds_write_b32 v151, v148 offset:1904
	v_fmac_f32_e32 v50, v116, v51
	v_fmac_f32_e32 v66, v118, v67
	v_fmac_f32_dpp v50, v51, v122 quad_perm:[1,0,3,2] row_mask:0xf bank_mask:0xf
	v_fmac_f32_dpp v66, v67, v123 quad_perm:[1,0,3,2] row_mask:0xf bank_mask:0xf
	v_cvt_pk_bf16_f32 v149, v50, v66
	ds_write_b32 v151, v149 offset:1632
	v_fmac_f32_e32 v49, v116, v50
	v_fmac_f32_e32 v65, v118, v66
	v_fmac_f32_dpp v49, v50, v122 quad_perm:[1,0,3,2] row_mask:0xf bank_mask:0xf
	v_fmac_f32_dpp v65, v66, v123 quad_perm:[1,0,3,2] row_mask:0xf bank_mask:0xf
	v_cvt_pk_bf16_f32 v148, v49, v65
	ds_write_b32 v151, v148 offset:1360
	v_fmac_f32_e32 v48, v116, v49
	v_fmac_f32_e32 v64, v118, v65
	v_fmac_f32_dpp v48, v49, v122 quad_perm:[1,0,3,2] row_mask:0xf bank_mask:0xf
	v_fmac_f32_dpp v64, v65, v123 quad_perm:[1,0,3,2] row_mask:0xf bank_mask:0xf
	v_cvt_pk_bf16_f32 v149, v48, v64
	ds_write_b32 v151, v149 offset:1088
	v_fmac_f32_e32 v19, v116, v48
	v_fmac_f32_e32 v35, v118, v64
	v_fmac_f32_dpp v19, v48, v122 quad_perm:[1,0,3,2] row_mask:0xf bank_mask:0xf
	v_fmac_f32_dpp v35, v64, v123 quad_perm:[1,0,3,2] row_mask:0xf bank_mask:0xf
	v_cvt_pk_bf16_f32 v148, v19, v35
	ds_write_b32 v151, v148 offset:816
	v_fmac_f32_e32 v18, v116, v19
	v_fmac_f32_e32 v34, v118, v35
	v_fmac_f32_dpp v18, v19, v122 quad_perm:[1,0,3,2] row_mask:0xf bank_mask:0xf
	v_fmac_f32_dpp v34, v35, v123 quad_perm:[1,0,3,2] row_mask:0xf bank_mask:0xf
	v_cvt_pk_bf16_f32 v149, v18, v34
	ds_write_b32 v151, v149 offset:544
	v_fmac_f32_e32 v17, v116, v18
	v_fmac_f32_e32 v33, v118, v34
	v_fmac_f32_dpp v17, v18, v122 quad_perm:[1,0,3,2] row_mask:0xf bank_mask:0xf
	v_fmac_f32_dpp v33, v34, v123 quad_perm:[1,0,3,2] row_mask:0xf bank_mask:0xf
	v_cvt_pk_bf16_f32 v148, v17, v33
	ds_write_b32 v151, v148 offset:272
	v_fmac_f32_e32 v16, v116, v17
	v_fmac_f32_e32 v32, v118, v33
	v_fmac_f32_dpp v16, v17, v122 quad_perm:[1,0,3,2] row_mask:0xf bank_mask:0xf
	v_fmac_f32_dpp v32, v33, v123 quad_perm:[1,0,3,2] row_mask:0xf bank_mask:0xf
	v_cvt_pk_bf16_f32 v149, v16, v32
	ds_write_b32 v151, v149
	v_mov_b32_e32 v120, v16
	v_mov_b32_e32 v121, v32
	ds_read_b128 v[124:127], v152
	ds_read_b128 v[128:131], v152 offset:64
	ds_read_b128 v[132:135], v152 offset:128
	ds_read_b128 v[136:139], v152 offset:192
	ds_read_b64 v[168:169], v171
	s_waitcnt lgkmcnt(4)
	v_mfma_f32_16x16x32_bf16 v[140:143], v[100:103], v[124:127], 0
	s_waitcnt lgkmcnt(3)
	v_mfma_f32_16x16x32_bf16 v[140:143], v[104:107], v[128:131], v[140:143]
	s_waitcnt lgkmcnt(2)
	v_mfma_f32_16x16x32_bf16 v[140:143], v[108:111], v[132:135], v[140:143]
	s_waitcnt lgkmcnt(1)
	v_mfma_f32_16x16x32_bf16 v[140:143], v[112:115], v[136:139], v[140:143]
	s_nop 9
	s_waitcnt vmcnt(6) lgkmcnt(0)
	v_lshlrev_b32_e32 v182, 16, v168
	v_and_b32_e32 v183, 0xffff0000, v168
	v_lshlrev_b32_e32 v184, 16, v169
	v_and_b32_e32 v185, 0xffff0000, v169
	v_add_f32_e32 v182, v182, v140
	v_add_f32_e32 v183, v183, v141
	v_add_f32_e32 v184, v184, v142
	v_add_f32_e32 v185, v185, v143
	v_lshlrev_b32_e32 v186, 16, v2
	v_and_b32_e32 v187, 0xffff0000, v2
	v_lshlrev_b32_e32 v188, 16, v3
	v_and_b32_e32 v189, 0xffff0000, v3
	v_fmac_f32_e32 v182, v164, v186
	v_fmac_f32_e32 v183, v165, v187
	v_fmac_f32_e32 v184, v166, v188
	v_fmac_f32_e32 v185, v167, v189
	v_mul_f32_e32 v186, 0x3d372713, v182
	v_mul_f32_e32 v187, 0x3d372713, v183
	v_mul_f32_e32 v188, 0x3d372713, v184
	v_mul_f32_e32 v189, 0x3d372713, v185
	v_mul_f32_e32 v186, v182, v186
	v_mul_f32_e32 v187, v183, v187
	v_mul_f32_e32 v188, v184, v188
	v_mul_f32_e32 v189, v185, v189
	v_fma_f32 v186, v182, v186, v182
	v_fma_f32 v187, v183, v187, v183
	v_fma_f32 v188, v184, v188, v184
	v_fma_f32 v189, v185, v189, v185
	v_mul_f32_e32 v186, 0xbfcc422a, v186
	v_mul_f32_e32 v187, 0xbfcc422a, v187
	v_mul_f32_e32 v188, 0xbfcc422a, v188
	v_mul_f32_e32 v189, 0xbfcc422a, v189
	v_mul_f32_e32 v186, 0x3fb8aa3b, v186
	v_mul_f32_e32 v187, 0x3fb8aa3b, v187
	v_mul_f32_e32 v188, 0x3fb8aa3b, v188
	v_mul_f32_e32 v189, 0x3fb8aa3b, v189
	v_exp_f32_e32 v186, v186
	v_exp_f32_e32 v187, v187
	v_exp_f32_e32 v188, v188
	v_exp_f32_e32 v189, v189
	v_add_f32_e32 v186, 1.0, v186
	v_add_f32_e32 v187, 1.0, v187
	v_add_f32_e32 v188, 1.0, v188
	v_add_f32_e32 v189, 1.0, v189
	v_rcp_f32_e32 v186, v186
	v_rcp_f32_e32 v187, v187
	v_rcp_f32_e32 v188, v188
	v_rcp_f32_e32 v189, v189
	v_mul_f32_e32 v182, v182, v186
	v_mul_f32_e32 v183, v183, v187
	v_mul_f32_e32 v184, v184, v188
	v_mul_f32_e32 v185, v185, v189
	v_cvt_pk_bf16_f32 v148, v182, v183
	v_cvt_pk_bf16_f32 v149, v184, v185
	global_store_dwordx2 v156, v[148:149], s[12:13]
	ds_read_b128 v[124:127], v152 offset:4352
	ds_read_b128 v[128:131], v152 offset:4416
	ds_read_b128 v[132:135], v152 offset:4480
	ds_read_b128 v[136:139], v152 offset:4544
	ds_read_b64 v[168:169], v171 offset:512
	s_waitcnt lgkmcnt(4)
	v_mfma_f32_16x16x32_bf16 v[140:143], v[100:103], v[124:127], 0
	s_waitcnt lgkmcnt(3)
	v_mfma_f32_16x16x32_bf16 v[140:143], v[104:107], v[128:131], v[140:143]
	s_waitcnt lgkmcnt(2)
	v_mfma_f32_16x16x32_bf16 v[140:143], v[108:111], v[132:135], v[140:143]
	s_waitcnt lgkmcnt(1)
	v_mfma_f32_16x16x32_bf16 v[140:143], v[112:115], v[136:139], v[140:143]
	s_nop 9
	s_waitcnt vmcnt(7) lgkmcnt(0)
	v_lshlrev_b32_e32 v182, 16, v168
	v_and_b32_e32 v183, 0xffff0000, v168
	v_lshlrev_b32_e32 v184, 16, v169
	v_and_b32_e32 v185, 0xffff0000, v169
	v_add_f32_e32 v182, v182, v140
	v_add_f32_e32 v183, v183, v141
	v_add_f32_e32 v184, v184, v142
	v_add_f32_e32 v185, v185, v143
	v_lshlrev_b32_e32 v186, 16, v4
	v_and_b32_e32 v187, 0xffff0000, v4
	v_lshlrev_b32_e32 v188, 16, v5
	v_and_b32_e32 v189, 0xffff0000, v5
	v_fmac_f32_e32 v182, v164, v186
	v_fmac_f32_e32 v183, v165, v187
	v_fmac_f32_e32 v184, v166, v188
	v_fmac_f32_e32 v185, v167, v189
	v_mul_f32_e32 v186, 0x3d372713, v182
	v_mul_f32_e32 v187, 0x3d372713, v183
	v_mul_f32_e32 v188, 0x3d372713, v184
	v_mul_f32_e32 v189, 0x3d372713, v185
	v_mul_f32_e32 v186, v182, v186
	v_mul_f32_e32 v187, v183, v187
	v_mul_f32_e32 v188, v184, v188
	v_mul_f32_e32 v189, v185, v189
	v_fma_f32 v186, v182, v186, v182
	v_fma_f32 v187, v183, v187, v183
	v_fma_f32 v188, v184, v188, v184
	v_fma_f32 v189, v185, v189, v185
	v_mul_f32_e32 v186, 0xbfcc422a, v186
	v_mul_f32_e32 v187, 0xbfcc422a, v187
	v_mul_f32_e32 v188, 0xbfcc422a, v188
	v_mul_f32_e32 v189, 0xbfcc422a, v189
	v_mul_f32_e32 v186, 0x3fb8aa3b, v186
	v_mul_f32_e32 v187, 0x3fb8aa3b, v187
	v_mul_f32_e32 v188, 0x3fb8aa3b, v188
	v_mul_f32_e32 v189, 0x3fb8aa3b, v189
	v_exp_f32_e32 v186, v186
	v_exp_f32_e32 v187, v187
	v_exp_f32_e32 v188, v188
	v_exp_f32_e32 v189, v189
	v_add_f32_e32 v186, 1.0, v186
	v_add_f32_e32 v187, 1.0, v187
	v_add_f32_e32 v188, 1.0, v188
	v_add_f32_e32 v189, 1.0, v189
	v_rcp_f32_e32 v186, v186
	v_rcp_f32_e32 v187, v187
	v_rcp_f32_e32 v188, v188
	v_rcp_f32_e32 v189, v189
	v_mul_f32_e32 v182, v182, v186
	v_mul_f32_e32 v183, v183, v187
	v_mul_f32_e32 v184, v184, v188
	v_mul_f32_e32 v185, v185, v189
	v_cvt_pk_bf16_f32 v148, v182, v183
	v_cvt_pk_bf16_f32 v149, v184, v185
	global_store_dwordx2 v159, v[148:149], s[12:13]
	s_sub_u32 s12, s12, 65536
	s_subb_u32 s13, s13, 0
	s_sub_u32 s36, s36, 1024
	s_add_u32 s14, s14, 2
	s_cmp_lt_u32 s14, 8
	s_cbranch_scc1 .Lssm_tile_d1m2
	s_add_u32 s30, s30, 0x8000000
	s_add_u32 s16, s60, s30
	s_addc_u32 s17, s61, 0
	global_store_dword v180, v120, s[16:17]
	global_store_dword v180, v121, s[16:17] offset:64
	s_waitcnt vmcnt(0) lgkmcnt(0)
	s_add_u32 s27, s27, 1
	s_cmp_lt_u32 s27, 2
	s_cbranch_scc1 .Lssm_ctx_loop
